# GEMM k-step: MFMA order walks 2-row bands in a snake (A and B operands alternate being reused)
# speedup vs baseline: 1.0284x; 1.0042x over previous
.Lgy_nn_a:
	s_waitcnt lgkmcnt(0)
	v_add_u32_e32 v240, s61, v238
	v_add_u32_e32 v241, s61, v239
	s_setprio 1
	v_mfma_f32_16x16x32_bf16 v[2:5], v[162:165], v[130:133], 0
	v_mfma_f32_16x16x32_bf16 v[18:21], v[162:165], v[134:137], 0
	v_mfma_f32_16x16x32_bf16 v[22:25], v[166:169], v[134:137], 0
	v_mfma_f32_16x16x32_bf16 v[6:9], v[166:169], v[130:133], 0
	s_waitcnt vmcnt(6)
	s_barrier
	v_mfma_f32_16x16x32_bf16 v[10:13], v[170:173], v[130:133], 0
	s_add_i32 m0, s60, s62
	v_mfma_f32_16x16x32_bf16 v[26:29], v[170:173], v[134:137], 0
	global_load_lds_dwordx4 v226, s[54:55]
	v_mfma_f32_16x16x32_bf16 v[30:33], v[174:177], v[134:137], 0
	v_mfma_f32_16x16x32_bf16 v[14:17], v[174:177], v[130:133], 0
	v_mfma_f32_16x16x32_bf16 v[46:49], v[174:177], v[138:141], 0
	ds_read_b128 v[210:213], v241 offset:0
	v_mfma_f32_16x16x32_bf16 v[62:65], v[174:177], v[142:145], 0
	ds_read_b128 v[214:217], v241 offset:256
	v_mfma_f32_16x16x32_bf16 v[58:61], v[170:173], v[142:145], 0
	ds_read_b128 v[218:221], v241 offset:512
	global_load_lds_dwordx4 v226, s[54:55] offset:1024
	v_mfma_f32_16x16x32_bf16 v[42:45], v[170:173], v[138:141], 0
	ds_read_b128 v[222:225], v241 offset:768
	v_mfma_f32_16x16x32_bf16 v[38:41], v[166:169], v[138:141], 0
	ds_read_b128 v[178:181], v240 offset:0
	v_mfma_f32_16x16x32_bf16 v[54:57], v[166:169], v[142:145], 0
	ds_read_b128 v[182:185], v240 offset:1024
	v_mfma_f32_16x16x32_bf16 v[50:53], v[162:165], v[142:145], 0
	ds_read_b128 v[186:189], v240 offset:2048
	v_mfma_f32_16x16x32_bf16 v[34:37], v[162:165], v[138:141], 0
	ds_read_b128 v[190:193], v240 offset:3072
	global_load_lds_dwordx4 v226, s[54:55] offset:2048
	v_mfma_f32_16x16x32_bf16 v[66:69], v[162:165], v[146:149], 0
	ds_read_b128 v[194:197], v240 offset:4096
	v_mfma_f32_16x16x32_bf16 v[82:85], v[162:165], v[150:153], 0
	ds_read_b128 v[198:201], v240 offset:5120
	v_mfma_f32_16x16x32_bf16 v[86:89], v[166:169], v[150:153], 0
	ds_read_b128 v[202:205], v240 offset:6144
	v_mfma_f32_16x16x32_bf16 v[70:73], v[166:169], v[146:149], 0
	ds_read_b128 v[206:209], v240 offset:7168
	v_mfma_f32_16x16x32_bf16 v[74:77], v[170:173], v[146:149], 0
	global_load_lds_dwordx4 v226, s[54:55] offset:3072
	v_mfma_f32_16x16x32_bf16 v[90:93], v[170:173], v[150:153], 0
	v_mfma_f32_16x16x32_bf16 v[94:97], v[174:177], v[150:153], 0
	v_mfma_f32_16x16x32_bf16 v[78:81], v[174:177], v[146:149], 0
	v_mfma_f32_16x16x32_bf16 v[110:113], v[174:177], v[154:157], 0
	s_add_i32 m0, s60, s63
	v_mfma_f32_16x16x32_bf16 v[126:129], v[174:177], v[158:161], 0
	global_load_lds_dwordx4 v230, s[56:57]
	v_mfma_f32_16x16x32_bf16 v[122:125], v[170:173], v[158:161], 0
	v_mfma_f32_16x16x32_bf16 v[106:109], v[170:173], v[154:157], 0
	v_mfma_f32_16x16x32_bf16 v[102:105], v[166:169], v[154:157], 0
	v_mfma_f32_16x16x32_bf16 v[118:121], v[166:169], v[158:161], 0
	v_mfma_f32_16x16x32_bf16 v[114:117], v[162:165], v[158:161], 0
	global_load_lds_dwordx4 v231, s[56:57] offset:1024
	v_mfma_f32_16x16x32_bf16 v[98:101], v[162:165], v[154:157], 0
	s_setprio 0
	s_add_i32 s60, s60, 0x6000
	s_cmp_eq_u32 s60, 0x12000
	s_cselect_b32 s60, 0, s60
	s_add_u32 s54, s54, s72
	s_addc_u32 s55, s55, 0
	s_add_u32 s56, s56, s73
	s_addc_u32 s57, s57, 0
	s_add_i32 s61, s61, 0x6000
	s_cmp_eq_u32 s61, 0x12000
	s_cselect_b32 s61, 0, s61
	s_waitcnt lgkmcnt(0)
	v_add_u32_e32 v240, s61, v238
	v_add_u32_e32 v241, s61, v239
	s_setprio 1
	v_mfma_f32_16x16x32_bf16 v[2:5], v[210:213], v[178:181], v[2:5]
	v_mfma_f32_16x16x32_bf16 v[18:21], v[210:213], v[182:185], v[18:21]
	v_mfma_f32_16x16x32_bf16 v[22:25], v[214:217], v[182:185], v[22:25]
	v_mfma_f32_16x16x32_bf16 v[6:9], v[214:217], v[178:181], v[6:9]
	s_waitcnt vmcnt(6)
	s_barrier
	v_mfma_f32_16x16x32_bf16 v[10:13], v[218:221], v[178:181], v[10:13]
	s_add_i32 m0, s60, s62
	v_mfma_f32_16x16x32_bf16 v[26:29], v[218:221], v[182:185], v[26:29]
	global_load_lds_dwordx4 v226, s[54:55]
	v_mfma_f32_16x16x32_bf16 v[30:33], v[222:225], v[182:185], v[30:33]
	v_mfma_f32_16x16x32_bf16 v[14:17], v[222:225], v[178:181], v[14:17]
	v_mfma_f32_16x16x32_bf16 v[46:49], v[222:225], v[186:189], v[46:49]
	ds_read_b128 v[162:165], v241 offset:0
	v_mfma_f32_16x16x32_bf16 v[62:65], v[222:225], v[190:193], v[62:65]
	ds_read_b128 v[166:169], v241 offset:256
	v_mfma_f32_16x16x32_bf16 v[58:61], v[218:221], v[190:193], v[58:61]
	ds_read_b128 v[170:173], v241 offset:512
	global_load_lds_dwordx4 v226, s[54:55] offset:1024
	v_mfma_f32_16x16x32_bf16 v[42:45], v[218:221], v[186:189], v[42:45]
	ds_read_b128 v[174:177], v241 offset:768
	v_mfma_f32_16x16x32_bf16 v[38:41], v[214:217], v[186:189], v[38:41]
	ds_read_b128 v[130:133], v240 offset:0
	v_mfma_f32_16x16x32_bf16 v[54:57], v[214:217], v[190:193], v[54:57]
	ds_read_b128 v[134:137], v240 offset:1024
	v_mfma_f32_16x16x32_bf16 v[50:53], v[210:213], v[190:193], v[50:53]
	ds_read_b128 v[138:141], v240 offset:2048
	v_mfma_f32_16x16x32_bf16 v[34:37], v[210:213], v[186:189], v[34:37]
	ds_read_b128 v[142:145], v240 offset:3072
	global_load_lds_dwordx4 v226, s[54:55] offset:2048
	v_mfma_f32_16x16x32_bf16 v[66:69], v[210:213], v[194:197], v[66:69]
	ds_read_b128 v[146:149], v240 offset:4096
	v_mfma_f32_16x16x32_bf16 v[82:85], v[210:213], v[198:201], v[82:85]
	ds_read_b128 v[150:153], v240 offset:5120
	v_mfma_f32_16x16x32_bf16 v[86:89], v[214:217], v[198:201], v[86:89]
	ds_read_b128 v[154:157], v240 offset:6144
	v_mfma_f32_16x16x32_bf16 v[70:73], v[214:217], v[194:197], v[70:73]
	ds_read_b128 v[158:161], v240 offset:7168
	v_mfma_f32_16x16x32_bf16 v[74:77], v[218:221], v[194:197], v[74:77]
	global_load_lds_dwordx4 v226, s[54:55] offset:3072
	v_mfma_f32_16x16x32_bf16 v[90:93], v[218:221], v[198:201], v[90:93]
	v_mfma_f32_16x16x32_bf16 v[94:97], v[222:225], v[198:201], v[94:97]
	v_mfma_f32_16x16x32_bf16 v[78:81], v[222:225], v[194:197], v[78:81]
	v_mfma_f32_16x16x32_bf16 v[110:113], v[222:225], v[202:205], v[110:113]
	s_add_i32 m0, s60, s63
	v_mfma_f32_16x16x32_bf16 v[126:129], v[222:225], v[206:209], v[126:129]
	global_load_lds_dwordx4 v230, s[56:57]
	v_mfma_f32_16x16x32_bf16 v[122:125], v[218:221], v[206:209], v[122:125]
	v_mfma_f32_16x16x32_bf16 v[106:109], v[218:221], v[202:205], v[106:109]
	v_mfma_f32_16x16x32_bf16 v[102:105], v[214:217], v[202:205], v[102:105]
	v_mfma_f32_16x16x32_bf16 v[118:121], v[214:217], v[206:209], v[118:121]
	v_mfma_f32_16x16x32_bf16 v[114:117], v[210:213], v[206:209], v[114:117]
	global_load_lds_dwordx4 v231, s[56:57] offset:1024
	v_mfma_f32_16x16x32_bf16 v[98:101], v[210:213], v[202:205], v[98:101]
	s_setprio 0
	s_add_i32 s60, s60, 0x6000
	s_cmp_eq_u32 s60, 0x12000
	s_cselect_b32 s60, 0, s60
	s_add_u32 s54, s54, s72
	s_addc_u32 s55, s55, 0
	s_add_u32 s56, s56, s73
	s_addc_u32 s57, s57, 0
	s_add_i32 s61, s61, 0x6000
	s_cmp_eq_u32 s61, 0x12000
	s_cselect_b32 s61, 0, s61
	s_branch .Lgy_main

.Lgy_nn_b:
	s_waitcnt lgkmcnt(0)
	v_add_u32_e32 v240, s61, v238
	v_add_u32_e32 v241, s61, v239
	s_setprio 1
	v_mfma_f32_16x16x32_bf16 v[2:5], v[162:165], v[130:133], 0
	v_mfma_f32_16x16x32_bf16 v[18:21], v[162:165], v[134:137], 0
	v_mfma_f32_16x16x32_bf16 v[22:25], v[166:169], v[134:137], 0
	v_mfma_f32_16x16x32_bf16 v[6:9], v[166:169], v[130:133], 0
	s_waitcnt vmcnt(22)
	s_barrier
	v_mfma_f32_16x16x32_bf16 v[10:13], v[170:173], v[130:133], 0
	s_add_i32 m0, s60, s62
	v_mfma_f32_16x16x32_bf16 v[26:29], v[170:173], v[134:137], 0
	global_load_lds_dwordx4 v226, s[54:55]
	v_mfma_f32_16x16x32_bf16 v[30:33], v[174:177], v[134:137], 0
	v_mfma_f32_16x16x32_bf16 v[14:17], v[174:177], v[130:133], 0
	v_mfma_f32_16x16x32_bf16 v[46:49], v[174:177], v[138:141], 0
	ds_read_b128 v[210:213], v241 offset:0
	v_mfma_f32_16x16x32_bf16 v[62:65], v[174:177], v[142:145], 0
	ds_read_b128 v[214:217], v241 offset:256
	v_mfma_f32_16x16x32_bf16 v[58:61], v[170:173], v[142:145], 0
	ds_read_b128 v[218:221], v241 offset:512
	global_load_lds_dwordx4 v226, s[54:55] offset:1024
	v_mfma_f32_16x16x32_bf16 v[42:45], v[170:173], v[138:141], 0
	ds_read_b128 v[222:225], v241 offset:768
	v_mfma_f32_16x16x32_bf16 v[38:41], v[166:169], v[138:141], 0
	ds_read_b128 v[178:181], v240 offset:0
	v_mfma_f32_16x16x32_bf16 v[54:57], v[166:169], v[142:145], 0
	ds_read_b128 v[182:185], v240 offset:1024
	v_mfma_f32_16x16x32_bf16 v[50:53], v[162:165], v[142:145], 0
	ds_read_b128 v[186:189], v240 offset:2048
	v_mfma_f32_16x16x32_bf16 v[34:37], v[162:165], v[138:141], 0
	ds_read_b128 v[190:193], v240 offset:3072
	global_load_lds_dwordx4 v226, s[54:55] offset:2048
	v_mfma_f32_16x16x32_bf16 v[66:69], v[162:165], v[146:149], 0
	ds_read_b128 v[194:197], v240 offset:4096
	v_mfma_f32_16x16x32_bf16 v[82:85], v[162:165], v[150:153], 0
	ds_read_b128 v[198:201], v240 offset:5120
	v_mfma_f32_16x16x32_bf16 v[86:89], v[166:169], v[150:153], 0
	ds_read_b128 v[202:205], v240 offset:6144
	v_mfma_f32_16x16x32_bf16 v[70:73], v[166:169], v[146:149], 0
	ds_read_b128 v[206:209], v240 offset:7168
	v_mfma_f32_16x16x32_bf16 v[74:77], v[170:173], v[146:149], 0
	global_load_lds_dwordx4 v226, s[54:55] offset:3072
	v_mfma_f32_16x16x32_bf16 v[90:93], v[170:173], v[150:153], 0
	v_mfma_f32_16x16x32_bf16 v[94:97], v[174:177], v[150:153], 0
	v_mfma_f32_16x16x32_bf16 v[78:81], v[174:177], v[146:149], 0
	v_mfma_f32_16x16x32_bf16 v[110:113], v[174:177], v[154:157], 0
	s_add_i32 m0, s60, s63
	v_mfma_f32_16x16x32_bf16 v[126:129], v[174:177], v[158:161], 0
	global_load_lds_dwordx4 v230, s[56:57]
	v_mfma_f32_16x16x32_bf16 v[122:125], v[170:173], v[158:161], 0
	v_mfma_f32_16x16x32_bf16 v[106:109], v[170:173], v[154:157], 0
	v_mfma_f32_16x16x32_bf16 v[102:105], v[166:169], v[154:157], 0
	v_mfma_f32_16x16x32_bf16 v[118:121], v[166:169], v[158:161], 0
	v_mfma_f32_16x16x32_bf16 v[114:117], v[162:165], v[158:161], 0
	global_load_lds_dwordx4 v231, s[56:57] offset:1024
	v_mfma_f32_16x16x32_bf16 v[98:101], v[162:165], v[154:157], 0
	s_setprio 0
	s_add_i32 s60, s60, 0x6000
	s_cmp_eq_u32 s60, 0x12000
	s_cselect_b32 s60, 0, s60
	s_add_u32 s54, s54, s72
	s_addc_u32 s55, s55, 0
	s_add_u32 s56, s56, s73
	s_addc_u32 s57, s57, 0
	s_add_i32 s61, s61, 0x6000
	s_cmp_eq_u32 s61, 0x12000
	s_cselect_b32 s61, 0, s61
	s_waitcnt lgkmcnt(0)
	v_add_u32_e32 v240, s61, v238
	v_add_u32_e32 v241, s61, v239
	s_setprio 1
	v_mfma_f32_16x16x32_bf16 v[2:5], v[210:213], v[178:181], v[2:5]
	v_mfma_f32_16x16x32_bf16 v[18:21], v[210:213], v[182:185], v[18:21]
	v_mfma_f32_16x16x32_bf16 v[22:25], v[214:217], v[182:185], v[22:25]
	v_mfma_f32_16x16x32_bf16 v[6:9], v[214:217], v[178:181], v[6:9]
	s_waitcnt vmcnt(22)
	s_barrier
	v_mfma_f32_16x16x32_bf16 v[10:13], v[218:221], v[178:181], v[10:13]
	s_add_i32 m0, s60, s62
	v_mfma_f32_16x16x32_bf16 v[26:29], v[218:221], v[182:185], v[26:29]
	global_load_lds_dwordx4 v226, s[54:55]
	v_mfma_f32_16x16x32_bf16 v[30:33], v[222:225], v[182:185], v[30:33]
	v_mfma_f32_16x16x32_bf16 v[14:17], v[222:225], v[178:181], v[14:17]
	v_mfma_f32_16x16x32_bf16 v[46:49], v[222:225], v[186:189], v[46:49]
	ds_read_b128 v[162:165], v241 offset:0
	v_mfma_f32_16x16x32_bf16 v[62:65], v[222:225], v[190:193], v[62:65]
	ds_read_b128 v[166:169], v241 offset:256
	v_mfma_f32_16x16x32_bf16 v[58:61], v[218:221], v[190:193], v[58:61]
	ds_read_b128 v[170:173], v241 offset:512
	global_load_lds_dwordx4 v226, s[54:55] offset:1024
	v_mfma_f32_16x16x32_bf16 v[42:45], v[218:221], v[186:189], v[42:45]
	ds_read_b128 v[174:177], v241 offset:768
	v_mfma_f32_16x16x32_bf16 v[38:41], v[214:217], v[186:189], v[38:41]
	ds_read_b128 v[130:133], v240 offset:0
	v_mfma_f32_16x16x32_bf16 v[54:57], v[214:217], v[190:193], v[54:57]
	ds_read_b128 v[134:137], v240 offset:1024
	v_mfma_f32_16x16x32_bf16 v[50:53], v[210:213], v[190:193], v[50:53]
	ds_read_b128 v[138:141], v240 offset:2048
	v_mfma_f32_16x16x32_bf16 v[34:37], v[210:213], v[186:189], v[34:37]
	ds_read_b128 v[142:145], v240 offset:3072
	global_load_lds_dwordx4 v226, s[54:55] offset:2048
	v_mfma_f32_16x16x32_bf16 v[66:69], v[210:213], v[194:197], v[66:69]
	ds_read_b128 v[146:149], v240 offset:4096
	v_mfma_f32_16x16x32_bf16 v[82:85], v[210:213], v[198:201], v[82:85]
	ds_read_b128 v[150:153], v240 offset:5120
	v_mfma_f32_16x16x32_bf16 v[86:89], v[214:217], v[198:201], v[86:89]
	ds_read_b128 v[154:157], v240 offset:6144
	v_mfma_f32_16x16x32_bf16 v[70:73], v[214:217], v[194:197], v[70:73]
	ds_read_b128 v[158:161], v240 offset:7168
	v_mfma_f32_16x16x32_bf16 v[74:77], v[218:221], v[194:197], v[74:77]
	global_load_lds_dwordx4 v226, s[54:55] offset:3072
	v_mfma_f32_16x16x32_bf16 v[90:93], v[218:221], v[198:201], v[90:93]
	v_mfma_f32_16x16x32_bf16 v[94:97], v[222:225], v[198:201], v[94:97]
	v_mfma_f32_16x16x32_bf16 v[78:81], v[222:225], v[194:197], v[78:81]
	v_mfma_f32_16x16x32_bf16 v[110:113], v[222:225], v[202:205], v[110:113]
	s_add_i32 m0, s60, s63
	v_mfma_f32_16x16x32_bf16 v[126:129], v[222:225], v[206:209], v[126:129]
	global_load_lds_dwordx4 v230, s[56:57]
	v_mfma_f32_16x16x32_bf16 v[122:125], v[218:221], v[206:209], v[122:125]
	v_mfma_f32_16x16x32_bf16 v[106:109], v[218:221], v[202:205], v[106:109]
	v_mfma_f32_16x16x32_bf16 v[102:105], v[214:217], v[202:205], v[102:105]
	v_mfma_f32_16x16x32_bf16 v[118:121], v[214:217], v[206:209], v[118:121]
	v_mfma_f32_16x16x32_bf16 v[114:117], v[210:213], v[206:209], v[114:117]
	global_load_lds_dwordx4 v231, s[56:57] offset:1024
	v_mfma_f32_16x16x32_bf16 v[98:101], v[210:213], v[202:205], v[98:101]
	s_setprio 0
	s_add_i32 s60, s60, 0x6000
	s_cmp_eq_u32 s60, 0x12000
	s_cselect_b32 s60, 0, s60
	s_add_u32 s54, s54, s72
	s_addc_u32 s55, s55, 0
	s_add_u32 s56, s56, s73
	s_addc_u32 s57, s57, 0
	s_add_i32 s61, s61, 0x6000
	s_cmp_eq_u32 s61, 0x12000
	s_cselect_b32 s61, 0, s61

.Lgy_kloop:
	s_waitcnt lgkmcnt(0)
	v_add_u32_e32 v240, s61, v238
	v_add_u32_e32 v241, s61, v239
	s_setprio 1
	v_mfma_f32_16x16x32_bf16 v[2:5], v[162:165], v[130:133], v[2:5]
	v_mfma_f32_16x16x32_bf16 v[18:21], v[162:165], v[134:137], v[18:21]
	v_mfma_f32_16x16x32_bf16 v[22:25], v[166:169], v[134:137], v[22:25]
	v_mfma_f32_16x16x32_bf16 v[6:9], v[166:169], v[130:133], v[6:9]
	s_waitcnt vmcnt(6)
	s_barrier
	v_mfma_f32_16x16x32_bf16 v[10:13], v[170:173], v[130:133], v[10:13]
	s_add_i32 m0, s60, s62
	v_mfma_f32_16x16x32_bf16 v[26:29], v[170:173], v[134:137], v[26:29]
	global_load_lds_dwordx4 v226, s[54:55]
	v_mfma_f32_16x16x32_bf16 v[30:33], v[174:177], v[134:137], v[30:33]
	v_mfma_f32_16x16x32_bf16 v[14:17], v[174:177], v[130:133], v[14:17]
	v_mfma_f32_16x16x32_bf16 v[46:49], v[174:177], v[138:141], v[46:49]
	ds_read_b128 v[210:213], v241 offset:0
	v_mfma_f32_16x16x32_bf16 v[62:65], v[174:177], v[142:145], v[62:65]
	ds_read_b128 v[214:217], v241 offset:256
	v_mfma_f32_16x16x32_bf16 v[58:61], v[170:173], v[142:145], v[58:61]
	ds_read_b128 v[218:221], v241 offset:512
	global_load_lds_dwordx4 v226, s[54:55] offset:1024
	v_mfma_f32_16x16x32_bf16 v[42:45], v[170:173], v[138:141], v[42:45]
	ds_read_b128 v[222:225], v241 offset:768
	v_mfma_f32_16x16x32_bf16 v[38:41], v[166:169], v[138:141], v[38:41]
	ds_read_b128 v[178:181], v240 offset:0
	v_mfma_f32_16x16x32_bf16 v[54:57], v[166:169], v[142:145], v[54:57]
	ds_read_b128 v[182:185], v240 offset:1024
	v_mfma_f32_16x16x32_bf16 v[50:53], v[162:165], v[142:145], v[50:53]
	ds_read_b128 v[186:189], v240 offset:2048
	v_mfma_f32_16x16x32_bf16 v[34:37], v[162:165], v[138:141], v[34:37]
	ds_read_b128 v[190:193], v240 offset:3072
	global_load_lds_dwordx4 v226, s[54:55] offset:2048
	v_mfma_f32_16x16x32_bf16 v[66:69], v[162:165], v[146:149], v[66:69]
	ds_read_b128 v[194:197], v240 offset:4096
	v_mfma_f32_16x16x32_bf16 v[82:85], v[162:165], v[150:153], v[82:85]
	ds_read_b128 v[198:201], v240 offset:5120
	v_mfma_f32_16x16x32_bf16 v[86:89], v[166:169], v[150:153], v[86:89]
	ds_read_b128 v[202:205], v240 offset:6144
	v_mfma_f32_16x16x32_bf16 v[70:73], v[166:169], v[146:149], v[70:73]
	ds_read_b128 v[206:209], v240 offset:7168
	v_mfma_f32_16x16x32_bf16 v[74:77], v[170:173], v[146:149], v[74:77]
	global_load_lds_dwordx4 v226, s[54:55] offset:3072
	v_mfma_f32_16x16x32_bf16 v[90:93], v[170:173], v[150:153], v[90:93]
	v_mfma_f32_16x16x32_bf16 v[94:97], v[174:177], v[150:153], v[94:97]
	v_mfma_f32_16x16x32_bf16 v[78:81], v[174:177], v[146:149], v[78:81]
	v_mfma_f32_16x16x32_bf16 v[110:113], v[174:177], v[154:157], v[110:113]
	s_add_i32 m0, s60, s63
	v_mfma_f32_16x16x32_bf16 v[126:129], v[174:177], v[158:161], v[126:129]
	global_load_lds_dwordx4 v230, s[56:57]
	v_mfma_f32_16x16x32_bf16 v[122:125], v[170:173], v[158:161], v[122:125]
	v_mfma_f32_16x16x32_bf16 v[106:109], v[170:173], v[154:157], v[106:109]
	v_mfma_f32_16x16x32_bf16 v[102:105], v[166:169], v[154:157], v[102:105]
	v_mfma_f32_16x16x32_bf16 v[118:121], v[166:169], v[158:161], v[118:121]
	v_mfma_f32_16x16x32_bf16 v[114:117], v[162:165], v[158:161], v[114:117]
	global_load_lds_dwordx4 v231, s[56:57] offset:1024
	v_mfma_f32_16x16x32_bf16 v[98:101], v[162:165], v[154:157], v[98:101]
	s_setprio 0
	s_add_i32 s60, s60, 0x6000
	s_cmp_eq_u32 s60, 0x12000
	s_cselect_b32 s60, 0, s60
	s_add_u32 s54, s54, s72
	s_addc_u32 s55, s55, 0
	s_add_u32 s56, s56, s73
	s_addc_u32 s57, s57, 0
	s_add_i32 s61, s61, 0x6000
	s_cmp_eq_u32 s61, 0x12000
	s_cselect_b32 s61, 0, s61
	s_waitcnt lgkmcnt(0)
	v_add_u32_e32 v240, s61, v238
	v_add_u32_e32 v241, s61, v239
	s_setprio 1
	v_mfma_f32_16x16x32_bf16 v[2:5], v[210:213], v[178:181], v[2:5]
	v_mfma_f32_16x16x32_bf16 v[18:21], v[210:213], v[182:185], v[18:21]
	v_mfma_f32_16x16x32_bf16 v[22:25], v[214:217], v[182:185], v[22:25]
	v_mfma_f32_16x16x32_bf16 v[6:9], v[214:217], v[178:181], v[6:9]
	s_waitcnt vmcnt(6)
	s_barrier
	v_mfma_f32_16x16x32_bf16 v[10:13], v[218:221], v[178:181], v[10:13]
	s_add_i32 m0, s60, s62
	v_mfma_f32_16x16x32_bf16 v[26:29], v[218:221], v[182:185], v[26:29]
	global_load_lds_dwordx4 v226, s[54:55]
	v_mfma_f32_16x16x32_bf16 v[30:33], v[222:225], v[182:185], v[30:33]
	v_mfma_f32_16x16x32_bf16 v[14:17], v[222:225], v[178:181], v[14:17]
	v_mfma_f32_16x16x32_bf16 v[46:49], v[222:225], v[186:189], v[46:49]
	ds_read_b128 v[162:165], v241 offset:0
	v_mfma_f32_16x16x32_bf16 v[62:65], v[222:225], v[190:193], v[62:65]
	ds_read_b128 v[166:169], v241 offset:256
	v_mfma_f32_16x16x32_bf16 v[58:61], v[218:221], v[190:193], v[58:61]
	ds_read_b128 v[170:173], v241 offset:512
	global_load_lds_dwordx4 v226, s[54:55] offset:1024
	v_mfma_f32_16x16x32_bf16 v[42:45], v[218:221], v[186:189], v[42:45]
	ds_read_b128 v[174:177], v241 offset:768
	v_mfma_f32_16x16x32_bf16 v[38:41], v[214:217], v[186:189], v[38:41]
	ds_read_b128 v[130:133], v240 offset:0
	v_mfma_f32_16x16x32_bf16 v[54:57], v[214:217], v[190:193], v[54:57]
	ds_read_b128 v[134:137], v240 offset:1024
	v_mfma_f32_16x16x32_bf16 v[50:53], v[210:213], v[190:193], v[50:53]
	ds_read_b128 v[138:141], v240 offset:2048
	v_mfma_f32_16x16x32_bf16 v[34:37], v[210:213], v[186:189], v[34:37]
	ds_read_b128 v[142:145], v240 offset:3072
	global_load_lds_dwordx4 v226, s[54:55] offset:2048
	v_mfma_f32_16x16x32_bf16 v[66:69], v[210:213], v[194:197], v[66:69]
	ds_read_b128 v[146:149], v240 offset:4096
	v_mfma_f32_16x16x32_bf16 v[82:85], v[210:213], v[198:201], v[82:85]
	ds_read_b128 v[150:153], v240 offset:5120
	v_mfma_f32_16x16x32_bf16 v[86:89], v[214:217], v[198:201], v[86:89]
	ds_read_b128 v[154:157], v240 offset:6144
	v_mfma_f32_16x16x32_bf16 v[70:73], v[214:217], v[194:197], v[70:73]
	ds_read_b128 v[158:161], v240 offset:7168
	v_mfma_f32_16x16x32_bf16 v[74:77], v[218:221], v[194:197], v[74:77]
	global_load_lds_dwordx4 v226, s[54:55] offset:3072
	v_mfma_f32_16x16x32_bf16 v[90:93], v[218:221], v[198:201], v[90:93]
	v_mfma_f32_16x16x32_bf16 v[94:97], v[222:225], v[198:201], v[94:97]
	v_mfma_f32_16x16x32_bf16 v[78:81], v[222:225], v[194:197], v[78:81]
	v_mfma_f32_16x16x32_bf16 v[110:113], v[222:225], v[202:205], v[110:113]
	s_add_i32 m0, s60, s63
	v_mfma_f32_16x16x32_bf16 v[126:129], v[222:225], v[206:209], v[126:129]
	global_load_lds_dwordx4 v230, s[56:57]
	v_mfma_f32_16x16x32_bf16 v[122:125], v[218:221], v[206:209], v[122:125]
	v_mfma_f32_16x16x32_bf16 v[106:109], v[218:221], v[202:205], v[106:109]
	v_mfma_f32_16x16x32_bf16 v[102:105], v[214:217], v[202:205], v[102:105]
	v_mfma_f32_16x16x32_bf16 v[118:121], v[214:217], v[206:209], v[118:121]
	v_mfma_f32_16x16x32_bf16 v[114:117], v[210:213], v[206:209], v[114:117]
	global_load_lds_dwordx4 v231, s[56:57] offset:1024
	v_mfma_f32_16x16x32_bf16 v[98:101], v[210:213], v[202:205], v[98:101]
	s_setprio 0
	s_add_i32 s60, s60, 0x6000
	s_cmp_eq_u32 s60, 0x12000
	s_cselect_b32 s60, 0, s60
	s_add_u32 s54, s54, s72
	s_addc_u32 s55, s55, 0
	s_add_u32 s56, s56, s73
	s_addc_u32 s57, s57, 0
	s_add_i32 s61, s61, 0x6000
	s_cmp_eq_u32 s61, 0x12000
	s_cselect_b32 s61, 0, s61
	s_add_i32 s40, s40, -1
	s_cmp_lg_u32 s40, 0
	s_cbranch_scc1 .Lgy_kloop
.Lgy_kdone:
	s_cmp_eq_u32 s37, 0
	s_cbranch_scc1 .Lgy_tail_last
	s_waitcnt lgkmcnt(0)
	v_add_u32_e32 v240, s61, v238
	v_add_u32_e32 v241, s61, v239
	s_setprio 1
	v_mfma_f32_16x16x32_bf16 v[2:5], v[162:165], v[130:133], v[2:5]
	v_mfma_f32_16x16x32_bf16 v[18:21], v[162:165], v[134:137], v[18:21]
	v_mfma_f32_16x16x32_bf16 v[22:25], v[166:169], v[134:137], v[22:25]
	v_mfma_f32_16x16x32_bf16 v[6:9], v[166:169], v[130:133], v[6:9]
	s_waitcnt vmcnt(6)
	s_barrier
	v_mfma_f32_16x16x32_bf16 v[10:13], v[170:173], v[130:133], v[10:13]
	s_add_i32 m0, s60, s62
	v_mfma_f32_16x16x32_bf16 v[26:29], v[170:173], v[134:137], v[26:29]
	global_load_lds_dwordx4 v226, s[54:55]
	v_mfma_f32_16x16x32_bf16 v[30:33], v[174:177], v[134:137], v[30:33]
	v_mfma_f32_16x16x32_bf16 v[14:17], v[174:177], v[130:133], v[14:17]
	v_mfma_f32_16x16x32_bf16 v[46:49], v[174:177], v[138:141], v[46:49]
	ds_read_b128 v[210:213], v241 offset:0
	v_mfma_f32_16x16x32_bf16 v[62:65], v[174:177], v[142:145], v[62:65]
	ds_read_b128 v[214:217], v241 offset:256
	v_mfma_f32_16x16x32_bf16 v[58:61], v[170:173], v[142:145], v[58:61]
	ds_read_b128 v[218:221], v241 offset:512
	global_load_lds_dwordx4 v226, s[54:55] offset:1024
	v_mfma_f32_16x16x32_bf16 v[42:45], v[170:173], v[138:141], v[42:45]
	ds_read_b128 v[222:225], v241 offset:768
	v_mfma_f32_16x16x32_bf16 v[38:41], v[166:169], v[138:141], v[38:41]
	ds_read_b128 v[178:181], v240 offset:0
	v_mfma_f32_16x16x32_bf16 v[54:57], v[166:169], v[142:145], v[54:57]
	ds_read_b128 v[182:185], v240 offset:1024
	v_mfma_f32_16x16x32_bf16 v[50:53], v[162:165], v[142:145], v[50:53]
	ds_read_b128 v[186:189], v240 offset:2048
	v_mfma_f32_16x16x32_bf16 v[34:37], v[162:165], v[138:141], v[34:37]
	ds_read_b128 v[190:193], v240 offset:3072
	global_load_lds_dwordx4 v226, s[54:55] offset:2048
	v_mfma_f32_16x16x32_bf16 v[66:69], v[162:165], v[146:149], v[66:69]
	ds_read_b128 v[194:197], v240 offset:4096
	v_mfma_f32_16x16x32_bf16 v[82:85], v[162:165], v[150:153], v[82:85]
	ds_read_b128 v[198:201], v240 offset:5120
	v_mfma_f32_16x16x32_bf16 v[86:89], v[166:169], v[150:153], v[86:89]
	ds_read_b128 v[202:205], v240 offset:6144
	v_mfma_f32_16x16x32_bf16 v[70:73], v[166:169], v[146:149], v[70:73]
	ds_read_b128 v[206:209], v240 offset:7168
	v_mfma_f32_16x16x32_bf16 v[74:77], v[170:173], v[146:149], v[74:77]
	global_load_lds_dwordx4 v226, s[54:55] offset:3072
	v_mfma_f32_16x16x32_bf16 v[90:93], v[170:173], v[150:153], v[90:93]
	v_mfma_f32_16x16x32_bf16 v[94:97], v[174:177], v[150:153], v[94:97]
	v_mfma_f32_16x16x32_bf16 v[78:81], v[174:177], v[146:149], v[78:81]
	v_mfma_f32_16x16x32_bf16 v[110:113], v[174:177], v[154:157], v[110:113]
	s_add_i32 m0, s60, s63
	v_mfma_f32_16x16x32_bf16 v[126:129], v[174:177], v[158:161], v[126:129]
	global_load_lds_dwordx4 v230, s[56:57]
	v_mfma_f32_16x16x32_bf16 v[122:125], v[170:173], v[158:161], v[122:125]
	v_mfma_f32_16x16x32_bf16 v[106:109], v[170:173], v[154:157], v[106:109]
	v_mfma_f32_16x16x32_bf16 v[102:105], v[166:169], v[154:157], v[102:105]
	v_mfma_f32_16x16x32_bf16 v[118:121], v[166:169], v[158:161], v[118:121]
	v_mfma_f32_16x16x32_bf16 v[114:117], v[162:165], v[158:161], v[114:117]
	global_load_lds_dwordx4 v231, s[56:57] offset:1024
	v_mfma_f32_16x16x32_bf16 v[98:101], v[162:165], v[154:157], v[98:101]
	s_setprio 0
	s_add_i32 s60, s60, 0x6000
	s_cmp_eq_u32 s60, 0x12000
	s_cselect_b32 s60, 0, s60
	s_add_u32 s54, s54, s72
	s_addc_u32 s55, s55, 0
	s_add_u32 s56, s56, s73
	s_addc_u32 s57, s57, 0
	s_add_i32 s61, s61, 0x6000
	s_cmp_eq_u32 s61, 0x12000
	s_cselect_b32 s61, 0, s61
	v_mov_b32_e32 v226, v232
	v_mov_b32_e32 v230, v236
	v_mov_b32_e32 v231, v237
	s_mov_b64 s[54:55], s[48:49]
	s_mov_b64 s[56:57], s[50:51]
	s_waitcnt lgkmcnt(0)
	v_add_u32_e32 v240, s61, v238
	v_add_u32_e32 v241, s61, v239
	s_setprio 1
	v_mfma_f32_16x16x32_bf16 v[2:5], v[210:213], v[178:181], v[2:5]
	v_mfma_f32_16x16x32_bf16 v[18:21], v[210:213], v[182:185], v[18:21]
	v_mfma_f32_16x16x32_bf16 v[22:25], v[214:217], v[182:185], v[22:25]
	v_mfma_f32_16x16x32_bf16 v[6:9], v[214:217], v[178:181], v[6:9]
	s_waitcnt vmcnt(6)
	s_barrier
	v_mfma_f32_16x16x32_bf16 v[10:13], v[218:221], v[178:181], v[10:13]
	s_add_i32 m0, s60, s62
	v_mfma_f32_16x16x32_bf16 v[26:29], v[218:221], v[182:185], v[26:29]
	global_load_lds_dwordx4 v226, s[54:55]
	v_mfma_f32_16x16x32_bf16 v[30:33], v[222:225], v[182:185], v[30:33]
	v_mfma_f32_16x16x32_bf16 v[14:17], v[222:225], v[178:181], v[14:17]
	v_mfma_f32_16x16x32_bf16 v[46:49], v[222:225], v[186:189], v[46:49]
	ds_read_b128 v[162:165], v241 offset:0
	v_mfma_f32_16x16x32_bf16 v[62:65], v[222:225], v[190:193], v[62:65]
	ds_read_b128 v[166:169], v241 offset:256
	v_mfma_f32_16x16x32_bf16 v[58:61], v[218:221], v[190:193], v[58:61]
	ds_read_b128 v[170:173], v241 offset:512
	global_load_lds_dwordx4 v226, s[54:55] offset:1024
	v_mfma_f32_16x16x32_bf16 v[42:45], v[218:221], v[186:189], v[42:45]
	ds_read_b128 v[174:177], v241 offset:768
	v_mfma_f32_16x16x32_bf16 v[38:41], v[214:217], v[186:189], v[38:41]
	ds_read_b128 v[130:133], v240 offset:0
	v_mfma_f32_16x16x32_bf16 v[54:57], v[214:217], v[190:193], v[54:57]
	ds_read_b128 v[134:137], v240 offset:1024
	v_mfma_f32_16x16x32_bf16 v[50:53], v[210:213], v[190:193], v[50:53]
	ds_read_b128 v[138:141], v240 offset:2048
	v_mfma_f32_16x16x32_bf16 v[34:37], v[210:213], v[186:189], v[34:37]
	ds_read_b128 v[142:145], v240 offset:3072
	global_load_lds_dwordx4 v226, s[54:55] offset:2048
	v_mfma_f32_16x16x32_bf16 v[66:69], v[210:213], v[194:197], v[66:69]
	ds_read_b128 v[146:149], v240 offset:4096
	v_mfma_f32_16x16x32_bf16 v[82:85], v[210:213], v[198:201], v[82:85]
	ds_read_b128 v[150:153], v240 offset:5120
	v_mfma_f32_16x16x32_bf16 v[86:89], v[214:217], v[198:201], v[86:89]
	ds_read_b128 v[154:157], v240 offset:6144
	v_mfma_f32_16x16x32_bf16 v[70:73], v[214:217], v[194:197], v[70:73]
	ds_read_b128 v[158:161], v240 offset:7168
	v_mfma_f32_16x16x32_bf16 v[74:77], v[218:221], v[194:197], v[74:77]
	global_load_lds_dwordx4 v226, s[54:55] offset:3072
	v_mfma_f32_16x16x32_bf16 v[90:93], v[218:221], v[198:201], v[90:93]
	v_mfma_f32_16x16x32_bf16 v[94:97], v[222:225], v[198:201], v[94:97]
	v_mfma_f32_16x16x32_bf16 v[78:81], v[222:225], v[194:197], v[78:81]
	v_mfma_f32_16x16x32_bf16 v[110:113], v[222:225], v[202:205], v[110:113]
	s_add_i32 m0, s60, s63
	v_mfma_f32_16x16x32_bf16 v[126:129], v[222:225], v[206:209], v[126:129]
	global_load_lds_dwordx4 v230, s[56:57]
	v_mfma_f32_16x16x32_bf16 v[122:125], v[218:221], v[206:209], v[122:125]
	v_mfma_f32_16x16x32_bf16 v[106:109], v[218:221], v[202:205], v[106:109]
	v_mfma_f32_16x16x32_bf16 v[102:105], v[214:217], v[202:205], v[102:105]
	v_mfma_f32_16x16x32_bf16 v[118:121], v[214:217], v[206:209], v[118:121]
	v_mfma_f32_16x16x32_bf16 v[114:117], v[210:213], v[206:209], v[114:117]
	global_load_lds_dwordx4 v231, s[56:57] offset:1024
	v_mfma_f32_16x16x32_bf16 v[98:101], v[210:213], v[202:205], v[98:101]
	s_setprio 0
	s_add_i32 s60, s60, 0x6000
	s_cmp_eq_u32 s60, 0x12000
	s_cselect_b32 s60, 0, s60
	s_add_u32 s54, s54, s72
	s_addc_u32 s55, s55, 0
	s_add_u32 s56, s56, s73
	s_addc_u32 s57, s57, 0
	s_add_i32 s61, s61, 0x6000
	s_cmp_eq_u32 s61, 0x12000
	s_cselect_b32 s61, 0, s61
	s_waitcnt lgkmcnt(0)
	v_add_u32_e32 v240, s61, v238
	v_add_u32_e32 v241, s61, v239
	s_setprio 1
	v_mfma_f32_16x16x32_bf16 v[2:5], v[162:165], v[130:133], v[2:5]
	v_mfma_f32_16x16x32_bf16 v[18:21], v[162:165], v[134:137], v[18:21]
	v_mfma_f32_16x16x32_bf16 v[22:25], v[166:169], v[134:137], v[22:25]
	v_mfma_f32_16x16x32_bf16 v[6:9], v[166:169], v[130:133], v[6:9]
	s_waitcnt vmcnt(6)
	s_barrier
	v_mfma_f32_16x16x32_bf16 v[10:13], v[170:173], v[130:133], v[10:13]
	s_add_i32 m0, s60, s62
	v_mfma_f32_16x16x32_bf16 v[26:29], v[170:173], v[134:137], v[26:29]
	global_load_lds_dwordx4 v226, s[54:55]
	v_mfma_f32_16x16x32_bf16 v[30:33], v[174:177], v[134:137], v[30:33]
	v_mfma_f32_16x16x32_bf16 v[14:17], v[174:177], v[130:133], v[14:17]
	v_mfma_f32_16x16x32_bf16 v[46:49], v[174:177], v[138:141], v[46:49]
	ds_read_b128 v[210:213], v241 offset:0
	v_mfma_f32_16x16x32_bf16 v[62:65], v[174:177], v[142:145], v[62:65]
	ds_read_b128 v[214:217], v241 offset:256
	v_mfma_f32_16x16x32_bf16 v[58:61], v[170:173], v[142:145], v[58:61]
	ds_read_b128 v[218:221], v241 offset:512
	global_load_lds_dwordx4 v226, s[54:55] offset:1024
	v_mfma_f32_16x16x32_bf16 v[42:45], v[170:173], v[138:141], v[42:45]
	ds_read_b128 v[222:225], v241 offset:768
	v_mfma_f32_16x16x32_bf16 v[38:41], v[166:169], v[138:141], v[38:41]
	ds_read_b128 v[178:181], v240 offset:0
	v_mfma_f32_16x16x32_bf16 v[54:57], v[166:169], v[142:145], v[54:57]
	ds_read_b128 v[182:185], v240 offset:1024
	v_mfma_f32_16x16x32_bf16 v[50:53], v[162:165], v[142:145], v[50:53]
	ds_read_b128 v[186:189], v240 offset:2048
	v_mfma_f32_16x16x32_bf16 v[34:37], v[162:165], v[138:141], v[34:37]
	ds_read_b128 v[190:193], v240 offset:3072
	global_load_lds_dwordx4 v226, s[54:55] offset:2048
	v_mfma_f32_16x16x32_bf16 v[66:69], v[162:165], v[146:149], v[66:69]
	ds_read_b128 v[194:197], v240 offset:4096
	v_mfma_f32_16x16x32_bf16 v[82:85], v[162:165], v[150:153], v[82:85]
	ds_read_b128 v[198:201], v240 offset:5120
	v_mfma_f32_16x16x32_bf16 v[86:89], v[166:169], v[150:153], v[86:89]
	ds_read_b128 v[202:205], v240 offset:6144
	v_mfma_f32_16x16x32_bf16 v[70:73], v[166:169], v[146:149], v[70:73]
	ds_read_b128 v[206:209], v240 offset:7168
	v_mfma_f32_16x16x32_bf16 v[74:77], v[170:173], v[146:149], v[74:77]
	global_load_lds_dwordx4 v226, s[54:55] offset:3072
	v_mfma_f32_16x16x32_bf16 v[90:93], v[170:173], v[150:153], v[90:93]
	v_mfma_f32_16x16x32_bf16 v[94:97], v[174:177], v[150:153], v[94:97]
	v_mfma_f32_16x16x32_bf16 v[78:81], v[174:177], v[146:149], v[78:81]
	v_mfma_f32_16x16x32_bf16 v[110:113], v[174:177], v[154:157], v[110:113]
	s_add_i32 m0, s60, s63
	v_mfma_f32_16x16x32_bf16 v[126:129], v[174:177], v[158:161], v[126:129]
	global_load_lds_dwordx4 v230, s[56:57]
	v_mfma_f32_16x16x32_bf16 v[122:125], v[170:173], v[158:161], v[122:125]
	v_mfma_f32_16x16x32_bf16 v[106:109], v[170:173], v[154:157], v[106:109]
	v_mfma_f32_16x16x32_bf16 v[102:105], v[166:169], v[154:157], v[102:105]
	v_mfma_f32_16x16x32_bf16 v[118:121], v[166:169], v[158:161], v[118:121]
	v_mfma_f32_16x16x32_bf16 v[114:117], v[162:165], v[158:161], v[114:117]
	global_load_lds_dwordx4 v231, s[56:57] offset:1024
	v_mfma_f32_16x16x32_bf16 v[98:101], v[162:165], v[154:157], v[98:101]
	s_setprio 0
	s_add_i32 s60, s60, 0x6000
	s_cmp_eq_u32 s60, 0x12000
	s_cselect_b32 s60, 0, s60
	s_add_u32 s54, s54, s72
	s_addc_u32 s55, s55, 0
	s_add_u32 s56, s56, s73
	s_addc_u32 s57, s57, 0
	s_add_i32 s61, s61, 0x6000
	s_cmp_eq_u32 s61, 0x12000
	s_cselect_b32 s61, 0, s61
	s_waitcnt lgkmcnt(0)
	v_add_u32_e32 v240, s61, v238
	v_add_u32_e32 v241, s61, v239
	s_setprio 1
	v_mfma_f32_16x16x32_bf16 v[2:5], v[210:213], v[178:181], v[2:5]
	v_mfma_f32_16x16x32_bf16 v[18:21], v[210:213], v[182:185], v[18:21]
	v_mfma_f32_16x16x32_bf16 v[22:25], v[214:217], v[182:185], v[22:25]
	v_mfma_f32_16x16x32_bf16 v[6:9], v[214:217], v[178:181], v[6:9]
	s_waitcnt vmcnt(6)
	s_barrier
	v_mfma_f32_16x16x32_bf16 v[10:13], v[218:221], v[178:181], v[10:13]
	s_add_i32 m0, s60, s62
	v_mfma_f32_16x16x32_bf16 v[26:29], v[218:221], v[182:185], v[26:29]
	global_load_lds_dwordx4 v226, s[54:55]
	v_mfma_f32_16x16x32_bf16 v[30:33], v[222:225], v[182:185], v[30:33]
	v_mfma_f32_16x16x32_bf16 v[14:17], v[222:225], v[178:181], v[14:17]
	v_mfma_f32_16x16x32_bf16 v[46:49], v[222:225], v[186:189], v[46:49]
	ds_read_b128 v[162:165], v241 offset:0
	v_mfma_f32_16x16x32_bf16 v[62:65], v[222:225], v[190:193], v[62:65]
	ds_read_b128 v[166:169], v241 offset:256
	v_mfma_f32_16x16x32_bf16 v[58:61], v[218:221], v[190:193], v[58:61]
	ds_read_b128 v[170:173], v241 offset:512
	global_load_lds_dwordx4 v226, s[54:55] offset:1024
	v_mfma_f32_16x16x32_bf16 v[42:45], v[218:221], v[186:189], v[42:45]
	ds_read_b128 v[174:177], v241 offset:768
	v_mfma_f32_16x16x32_bf16 v[38:41], v[214:217], v[186:189], v[38:41]
	ds_read_b128 v[130:133], v240 offset:0
	v_mfma_f32_16x16x32_bf16 v[54:57], v[214:217], v[190:193], v[54:57]
	ds_read_b128 v[134:137], v240 offset:1024
	v_mfma_f32_16x16x32_bf16 v[50:53], v[210:213], v[190:193], v[50:53]
	ds_read_b128 v[138:141], v240 offset:2048
	v_mfma_f32_16x16x32_bf16 v[34:37], v[210:213], v[186:189], v[34:37]
	ds_read_b128 v[142:145], v240 offset:3072
	global_load_lds_dwordx4 v226, s[54:55] offset:2048
	v_mfma_f32_16x16x32_bf16 v[66:69], v[210:213], v[194:197], v[66:69]
	ds_read_b128 v[146:149], v240 offset:4096
	v_mfma_f32_16x16x32_bf16 v[82:85], v[210:213], v[198:201], v[82:85]
	ds_read_b128 v[150:153], v240 offset:5120
	v_mfma_f32_16x16x32_bf16 v[86:89], v[214:217], v[198:201], v[86:89]
	ds_read_b128 v[154:157], v240 offset:6144
	v_mfma_f32_16x16x32_bf16 v[70:73], v[214:217], v[194:197], v[70:73]
	ds_read_b128 v[158:161], v240 offset:7168
	v_mfma_f32_16x16x32_bf16 v[74:77], v[218:221], v[194:197], v[74:77]
	global_load_lds_dwordx4 v226, s[54:55] offset:3072
	v_mfma_f32_16x16x32_bf16 v[90:93], v[218:221], v[198:201], v[90:93]
	v_mfma_f32_16x16x32_bf16 v[94:97], v[222:225], v[198:201], v[94:97]
	v_mfma_f32_16x16x32_bf16 v[78:81], v[222:225], v[194:197], v[78:81]
	v_mfma_f32_16x16x32_bf16 v[110:113], v[222:225], v[202:205], v[110:113]
	s_add_i32 m0, s60, s63
	v_mfma_f32_16x16x32_bf16 v[126:129], v[222:225], v[206:209], v[126:129]
	global_load_lds_dwordx4 v230, s[56:57]
	v_mfma_f32_16x16x32_bf16 v[122:125], v[218:221], v[206:209], v[122:125]
	v_mfma_f32_16x16x32_bf16 v[106:109], v[218:221], v[202:205], v[106:109]
	v_mfma_f32_16x16x32_bf16 v[102:105], v[214:217], v[202:205], v[102:105]
	v_mfma_f32_16x16x32_bf16 v[118:121], v[214:217], v[206:209], v[118:121]
	v_mfma_f32_16x16x32_bf16 v[114:117], v[210:213], v[206:209], v[114:117]
	global_load_lds_dwordx4 v231, s[56:57] offset:1024
	v_mfma_f32_16x16x32_bf16 v[98:101], v[210:213], v[202:205], v[98:101]
	s_setprio 0
	s_add_i32 s60, s60, 0x6000
	s_cmp_eq_u32 s60, 0x12000
	s_cselect_b32 s60, 0, s60
	s_add_u32 s54, s54, s72
	s_addc_u32 s55, s55, 0
	s_add_u32 s56, s56, s73
	s_addc_u32 s57, s57, 0
	s_add_i32 s61, s61, 0x6000
	s_cmp_eq_u32 s61, 0x12000
	s_cselect_b32 s61, 0, s61
	s_nop 7
	s_nop 1
	s_lshl_b32 s26, s35, 11
	s_lshl_b32 s27, s36, 1
	s_add_i32 s26, s26, s27
	s_add_u32 s18, s52, s26
	s_addc_u32 s19, s53, 0
	v_cvt_pk_bf16_f32 v2, v2, v3
	v_cvt_pk_bf16_f32 v3, v4, v5
	v_cvt_pk_bf16_f32 v4, v6, v7
	v_cvt_pk_bf16_f32 v5, v8, v9
	v_cvt_pk_bf16_f32 v6, v10, v11
	v_cvt_pk_bf16_f32 v7, v12, v13
	v_cvt_pk_bf16_f32 v8, v14, v15
	v_cvt_pk_bf16_f32 v9, v16, v17
	global_store_dwordx4 v242, v[2:5], s[18:19]
	global_store_dwordx4 v242, v[6:9], s[18:19] offset:16
	s_add_u32 s18, s18, 0x8000
	s_addc_u32 s19, s19, 0
	v_cvt_pk_bf16_f32 v18, v18, v19
	v_cvt_pk_bf16_f32 v19, v20, v21
	v_cvt_pk_bf16_f32 v20, v22, v23
	v_cvt_pk_bf16_f32 v21, v24, v25
	v_cvt_pk_bf16_f32 v22, v26, v27
	v_cvt_pk_bf16_f32 v23, v28, v29
	v_cvt_pk_bf16_f32 v24, v30, v31
	v_cvt_pk_bf16_f32 v25, v32, v33
	global_store_dwordx4 v242, v[18:21], s[18:19]
	global_store_dwordx4 v242, v[22:25], s[18:19] offset:16
	s_add_u32 s18, s18, 0x8000
	s_addc_u32 s19, s19, 0
	v_cvt_pk_bf16_f32 v34, v34, v35
	v_cvt_pk_bf16_f32 v35, v36, v37
	v_cvt_pk_bf16_f32 v36, v38, v39
	v_cvt_pk_bf16_f32 v37, v40, v41
	v_cvt_pk_bf16_f32 v38, v42, v43
	v_cvt_pk_bf16_f32 v39, v44, v45
	v_cvt_pk_bf16_f32 v40, v46, v47
	v_cvt_pk_bf16_f32 v41, v48, v49
	global_store_dwordx4 v242, v[34:37], s[18:19]
	global_store_dwordx4 v242, v[38:41], s[18:19] offset:16
	s_add_u32 s18, s18, 0x8000
	s_addc_u32 s19, s19, 0
	v_cvt_pk_bf16_f32 v50, v50, v51
	v_cvt_pk_bf16_f32 v51, v52, v53
	v_cvt_pk_bf16_f32 v52, v54, v55
	v_cvt_pk_bf16_f32 v53, v56, v57
	v_cvt_pk_bf16_f32 v54, v58, v59
	v_cvt_pk_bf16_f32 v55, v60, v61
	v_cvt_pk_bf16_f32 v56, v62, v63
	v_cvt_pk_bf16_f32 v57, v64, v65
	global_store_dwordx4 v242, v[50:53], s[18:19]
	global_store_dwordx4 v242, v[54:57], s[18:19] offset:16
	s_add_u32 s18, s18, 0x8000
	s_addc_u32 s19, s19, 0
	v_cvt_pk_bf16_f32 v66, v66, v67
	v_cvt_pk_bf16_f32 v67, v68, v69
	v_cvt_pk_bf16_f32 v68, v70, v71
	v_cvt_pk_bf16_f32 v69, v72, v73
	v_cvt_pk_bf16_f32 v70, v74, v75
	v_cvt_pk_bf16_f32 v71, v76, v77
	v_cvt_pk_bf16_f32 v72, v78, v79
	v_cvt_pk_bf16_f32 v73, v80, v81
	global_store_dwordx4 v242, v[66:69], s[18:19]
	global_store_dwordx4 v242, v[70:73], s[18:19] offset:16
	s_add_u32 s18, s18, 0x8000
	s_addc_u32 s19, s19, 0
	v_cvt_pk_bf16_f32 v82, v82, v83
	v_cvt_pk_bf16_f32 v83, v84, v85
	v_cvt_pk_bf16_f32 v84, v86, v87
	v_cvt_pk_bf16_f32 v85, v88, v89
	v_cvt_pk_bf16_f32 v86, v90, v91
	v_cvt_pk_bf16_f32 v87, v92, v93
	v_cvt_pk_bf16_f32 v88, v94, v95
	v_cvt_pk_bf16_f32 v89, v96, v97
	global_store_dwordx4 v242, v[82:85], s[18:19]
	global_store_dwordx4 v242, v[86:89], s[18:19] offset:16
	s_add_u32 s18, s18, 0x8000
	s_addc_u32 s19, s19, 0
	v_cvt_pk_bf16_f32 v98, v98, v99
	v_cvt_pk_bf16_f32 v99, v100, v101
	v_cvt_pk_bf16_f32 v100, v102, v103
	v_cvt_pk_bf16_f32 v101, v104, v105
	v_cvt_pk_bf16_f32 v102, v106, v107
	v_cvt_pk_bf16_f32 v103, v108, v109
	v_cvt_pk_bf16_f32 v104, v110, v111
	v_cvt_pk_bf16_f32 v105, v112, v113
	global_store_dwordx4 v242, v[98:101], s[18:19]
	global_store_dwordx4 v242, v[102:105], s[18:19] offset:16
	s_add_u32 s18, s18, 0x8000
	s_addc_u32 s19, s19, 0
	v_cvt_pk_bf16_f32 v114, v114, v115
	v_cvt_pk_bf16_f32 v115, v116, v117
	v_cvt_pk_bf16_f32 v116, v118, v119
	v_cvt_pk_bf16_f32 v117, v120, v121
	v_cvt_pk_bf16_f32 v118, v122, v123
	v_cvt_pk_bf16_f32 v119, v124, v125
	v_cvt_pk_bf16_f32 v120, v126, v127
	v_cvt_pk_bf16_f32 v121, v128, v129
	global_store_dwordx4 v242, v[114:117], s[18:19]
	global_store_dwordx4 v242, v[118:121], s[18:19] offset:16
	s_mov_b32 s34, s38
	s_mov_b32 s35, s30
	s_mov_b32 s36, s31
	s_branch .Lgy_tile
.Lgy_tail_last:
	s_waitcnt lgkmcnt(0)
	v_add_u32_e32 v240, s61, v238
	v_add_u32_e32 v241, s61, v239
	s_setprio 1
	v_mfma_f32_16x16x32_bf16 v[2:5], v[162:165], v[130:133], v[2:5]
	v_mfma_f32_16x16x32_bf16 v[18:21], v[162:165], v[134:137], v[18:21]
	v_mfma_f32_16x16x32_bf16 v[22:25], v[166:169], v[134:137], v[22:25]
	v_mfma_f32_16x16x32_bf16 v[6:9], v[166:169], v[130:133], v[6:9]
	s_waitcnt vmcnt(6)
	s_barrier
	v_mfma_f32_16x16x32_bf16 v[10:13], v[170:173], v[130:133], v[10:13]
	s_add_i32 m0, s60, s62
	v_mfma_f32_16x16x32_bf16 v[26:29], v[170:173], v[134:137], v[26:29]
	global_load_lds_dwordx4 v226, s[54:55]
	v_mfma_f32_16x16x32_bf16 v[30:33], v[174:177], v[134:137], v[30:33]
	v_mfma_f32_16x16x32_bf16 v[14:17], v[174:177], v[130:133], v[14:17]
	v_mfma_f32_16x16x32_bf16 v[46:49], v[174:177], v[138:141], v[46:49]
	ds_read_b128 v[210:213], v241 offset:0
	v_mfma_f32_16x16x32_bf16 v[62:65], v[174:177], v[142:145], v[62:65]
	ds_read_b128 v[214:217], v241 offset:256
	v_mfma_f32_16x16x32_bf16 v[58:61], v[170:173], v[142:145], v[58:61]
	ds_read_b128 v[218:221], v241 offset:512
	global_load_lds_dwordx4 v226, s[54:55] offset:1024
	v_mfma_f32_16x16x32_bf16 v[42:45], v[170:173], v[138:141], v[42:45]
	ds_read_b128 v[222:225], v241 offset:768
	v_mfma_f32_16x16x32_bf16 v[38:41], v[166:169], v[138:141], v[38:41]
	ds_read_b128 v[178:181], v240 offset:0
	v_mfma_f32_16x16x32_bf16 v[54:57], v[166:169], v[142:145], v[54:57]
	ds_read_b128 v[182:185], v240 offset:1024
	v_mfma_f32_16x16x32_bf16 v[50:53], v[162:165], v[142:145], v[50:53]
	ds_read_b128 v[186:189], v240 offset:2048
	v_mfma_f32_16x16x32_bf16 v[34:37], v[162:165], v[138:141], v[34:37]
	ds_read_b128 v[190:193], v240 offset:3072
	global_load_lds_dwordx4 v226, s[54:55] offset:2048
	v_mfma_f32_16x16x32_bf16 v[66:69], v[162:165], v[146:149], v[66:69]
	ds_read_b128 v[194:197], v240 offset:4096
	v_mfma_f32_16x16x32_bf16 v[82:85], v[162:165], v[150:153], v[82:85]
	ds_read_b128 v[198:201], v240 offset:5120
	v_mfma_f32_16x16x32_bf16 v[86:89], v[166:169], v[150:153], v[86:89]
	ds_read_b128 v[202:205], v240 offset:6144
	v_mfma_f32_16x16x32_bf16 v[70:73], v[166:169], v[146:149], v[70:73]
	ds_read_b128 v[206:209], v240 offset:7168
	v_mfma_f32_16x16x32_bf16 v[74:77], v[170:173], v[146:149], v[74:77]
	global_load_lds_dwordx4 v226, s[54:55] offset:3072
	v_mfma_f32_16x16x32_bf16 v[90:93], v[170:173], v[150:153], v[90:93]
	v_mfma_f32_16x16x32_bf16 v[94:97], v[174:177], v[150:153], v[94:97]
	v_mfma_f32_16x16x32_bf16 v[78:81], v[174:177], v[146:149], v[78:81]
	v_mfma_f32_16x16x32_bf16 v[110:113], v[174:177], v[154:157], v[110:113]
	s_add_i32 m0, s60, s63
	v_mfma_f32_16x16x32_bf16 v[126:129], v[174:177], v[158:161], v[126:129]
	global_load_lds_dwordx4 v230, s[56:57]
	v_mfma_f32_16x16x32_bf16 v[122:125], v[170:173], v[158:161], v[122:125]
	v_mfma_f32_16x16x32_bf16 v[106:109], v[170:173], v[154:157], v[106:109]
	v_mfma_f32_16x16x32_bf16 v[102:105], v[166:169], v[154:157], v[102:105]
	v_mfma_f32_16x16x32_bf16 v[118:121], v[166:169], v[158:161], v[118:121]
	v_mfma_f32_16x16x32_bf16 v[114:117], v[162:165], v[158:161], v[114:117]
	global_load_lds_dwordx4 v231, s[56:57] offset:1024
	v_mfma_f32_16x16x32_bf16 v[98:101], v[162:165], v[154:157], v[98:101]
	s_setprio 0
	s_add_i32 s60, s60, 0x6000
	s_cmp_eq_u32 s60, 0x12000
	s_cselect_b32 s60, 0, s60
	s_add_u32 s54, s54, s72
	s_addc_u32 s55, s55, 0
	s_add_u32 s56, s56, s73
	s_addc_u32 s57, s57, 0
	s_add_i32 s61, s61, 0x6000
	s_cmp_eq_u32 s61, 0x12000
	s_cselect_b32 s61, 0, s61
	s_waitcnt lgkmcnt(0)
	v_add_u32_e32 v240, s61, v238
	v_add_u32_e32 v241, s61, v239
	s_setprio 1
	v_mfma_f32_16x16x32_bf16 v[2:5], v[210:213], v[178:181], v[2:5]
	v_mfma_f32_16x16x32_bf16 v[18:21], v[210:213], v[182:185], v[18:21]
	v_mfma_f32_16x16x32_bf16 v[22:25], v[214:217], v[182:185], v[22:25]
	v_mfma_f32_16x16x32_bf16 v[6:9], v[214:217], v[178:181], v[6:9]
	s_waitcnt vmcnt(6)
	s_barrier
	v_mfma_f32_16x16x32_bf16 v[10:13], v[218:221], v[178:181], v[10:13]
	v_mfma_f32_16x16x32_bf16 v[26:29], v[218:221], v[182:185], v[26:29]
	v_mfma_f32_16x16x32_bf16 v[30:33], v[222:225], v[182:185], v[30:33]
	v_mfma_f32_16x16x32_bf16 v[14:17], v[222:225], v[178:181], v[14:17]
	v_mfma_f32_16x16x32_bf16 v[46:49], v[222:225], v[186:189], v[46:49]
	ds_read_b128 v[162:165], v241 offset:0
	v_mfma_f32_16x16x32_bf16 v[62:65], v[222:225], v[190:193], v[62:65]
	ds_read_b128 v[166:169], v241 offset:256
	v_mfma_f32_16x16x32_bf16 v[58:61], v[218:221], v[190:193], v[58:61]
	ds_read_b128 v[170:173], v241 offset:512
	v_mfma_f32_16x16x32_bf16 v[42:45], v[218:221], v[186:189], v[42:45]
	ds_read_b128 v[174:177], v241 offset:768
	v_mfma_f32_16x16x32_bf16 v[38:41], v[214:217], v[186:189], v[38:41]
	ds_read_b128 v[130:133], v240 offset:0
	v_mfma_f32_16x16x32_bf16 v[54:57], v[214:217], v[190:193], v[54:57]
	ds_read_b128 v[134:137], v240 offset:1024
	v_mfma_f32_16x16x32_bf16 v[50:53], v[210:213], v[190:193], v[50:53]
	ds_read_b128 v[138:141], v240 offset:2048
	v_mfma_f32_16x16x32_bf16 v[34:37], v[210:213], v[186:189], v[34:37]
	ds_read_b128 v[142:145], v240 offset:3072
	v_mfma_f32_16x16x32_bf16 v[66:69], v[210:213], v[194:197], v[66:69]
	ds_read_b128 v[146:149], v240 offset:4096
	v_mfma_f32_16x16x32_bf16 v[82:85], v[210:213], v[198:201], v[82:85]
	ds_read_b128 v[150:153], v240 offset:5120
	v_mfma_f32_16x16x32_bf16 v[86:89], v[214:217], v[198:201], v[86:89]
	ds_read_b128 v[154:157], v240 offset:6144
	v_mfma_f32_16x16x32_bf16 v[70:73], v[214:217], v[194:197], v[70:73]
	ds_read_b128 v[158:161], v240 offset:7168
	v_mfma_f32_16x16x32_bf16 v[74:77], v[218:221], v[194:197], v[74:77]
	v_mfma_f32_16x16x32_bf16 v[90:93], v[218:221], v[198:201], v[90:93]
	v_mfma_f32_16x16x32_bf16 v[94:97], v[222:225], v[198:201], v[94:97]
	v_mfma_f32_16x16x32_bf16 v[78:81], v[222:225], v[194:197], v[78:81]
	v_mfma_f32_16x16x32_bf16 v[110:113], v[222:225], v[202:205], v[110:113]
	v_mfma_f32_16x16x32_bf16 v[126:129], v[222:225], v[206:209], v[126:129]
	v_mfma_f32_16x16x32_bf16 v[122:125], v[218:221], v[206:209], v[122:125]
	v_mfma_f32_16x16x32_bf16 v[106:109], v[218:221], v[202:205], v[106:109]
	v_mfma_f32_16x16x32_bf16 v[102:105], v[214:217], v[202:205], v[102:105]
	v_mfma_f32_16x16x32_bf16 v[118:121], v[214:217], v[206:209], v[118:121]
	v_mfma_f32_16x16x32_bf16 v[114:117], v[210:213], v[206:209], v[114:117]
	v_mfma_f32_16x16x32_bf16 v[98:101], v[210:213], v[202:205], v[98:101]
	s_setprio 0
	s_add_i32 s61, s61, 0x6000
	s_cmp_eq_u32 s61, 0x12000
	s_cselect_b32 s61, 0, s61
	s_waitcnt lgkmcnt(0)
	v_add_u32_e32 v240, s61, v238
	v_add_u32_e32 v241, s61, v239
	s_setprio 1
	v_mfma_f32_16x16x32_bf16 v[2:5], v[162:165], v[130:133], v[2:5]
	v_mfma_f32_16x16x32_bf16 v[18:21], v[162:165], v[134:137], v[18:21]
	v_mfma_f32_16x16x32_bf16 v[22:25], v[166:169], v[134:137], v[22:25]
	v_mfma_f32_16x16x32_bf16 v[6:9], v[166:169], v[130:133], v[6:9]
	s_waitcnt vmcnt(0)
	s_barrier
	v_mfma_f32_16x16x32_bf16 v[10:13], v[170:173], v[130:133], v[10:13]
	v_mfma_f32_16x16x32_bf16 v[26:29], v[170:173], v[134:137], v[26:29]
	v_mfma_f32_16x16x32_bf16 v[30:33], v[174:177], v[134:137], v[30:33]
	v_mfma_f32_16x16x32_bf16 v[14:17], v[174:177], v[130:133], v[14:17]
	v_mfma_f32_16x16x32_bf16 v[46:49], v[174:177], v[138:141], v[46:49]
	ds_read_b128 v[210:213], v241 offset:0
	v_mfma_f32_16x16x32_bf16 v[62:65], v[174:177], v[142:145], v[62:65]
	ds_read_b128 v[214:217], v241 offset:256
	v_mfma_f32_16x16x32_bf16 v[58:61], v[170:173], v[142:145], v[58:61]
	ds_read_b128 v[218:221], v241 offset:512
	v_mfma_f32_16x16x32_bf16 v[42:45], v[170:173], v[138:141], v[42:45]
	ds_read_b128 v[222:225], v241 offset:768
	v_mfma_f32_16x16x32_bf16 v[38:41], v[166:169], v[138:141], v[38:41]
	ds_read_b128 v[178:181], v240 offset:0
	v_mfma_f32_16x16x32_bf16 v[54:57], v[166:169], v[142:145], v[54:57]
	ds_read_b128 v[182:185], v240 offset:1024
	v_mfma_f32_16x16x32_bf16 v[50:53], v[162:165], v[142:145], v[50:53]
	ds_read_b128 v[186:189], v240 offset:2048
	v_mfma_f32_16x16x32_bf16 v[34:37], v[162:165], v[138:141], v[34:37]
	ds_read_b128 v[190:193], v240 offset:3072
	v_mfma_f32_16x16x32_bf16 v[66:69], v[162:165], v[146:149], v[66:69]
	ds_read_b128 v[194:197], v240 offset:4096
	v_mfma_f32_16x16x32_bf16 v[82:85], v[162:165], v[150:153], v[82:85]
	ds_read_b128 v[198:201], v240 offset:5120
	v_mfma_f32_16x16x32_bf16 v[86:89], v[166:169], v[150:153], v[86:89]
	ds_read_b128 v[202:205], v240 offset:6144
	v_mfma_f32_16x16x32_bf16 v[70:73], v[166:169], v[146:149], v[70:73]
	ds_read_b128 v[206:209], v240 offset:7168
	v_mfma_f32_16x16x32_bf16 v[74:77], v[170:173], v[146:149], v[74:77]
	v_mfma_f32_16x16x32_bf16 v[90:93], v[170:173], v[150:153], v[90:93]
	v_mfma_f32_16x16x32_bf16 v[94:97], v[174:177], v[150:153], v[94:97]
	v_mfma_f32_16x16x32_bf16 v[78:81], v[174:177], v[146:149], v[78:81]
	v_mfma_f32_16x16x32_bf16 v[110:113], v[174:177], v[154:157], v[110:113]
	v_mfma_f32_16x16x32_bf16 v[126:129], v[174:177], v[158:161], v[126:129]
	v_mfma_f32_16x16x32_bf16 v[122:125], v[170:173], v[158:161], v[122:125]
	v_mfma_f32_16x16x32_bf16 v[106:109], v[170:173], v[154:157], v[106:109]
	v_mfma_f32_16x16x32_bf16 v[102:105], v[166:169], v[154:157], v[102:105]
	v_mfma_f32_16x16x32_bf16 v[118:121], v[166:169], v[158:161], v[118:121]
	v_mfma_f32_16x16x32_bf16 v[114:117], v[162:165], v[158:161], v[114:117]
	v_mfma_f32_16x16x32_bf16 v[98:101], v[162:165], v[154:157], v[98:101]
	s_setprio 0
	s_add_i32 s61, s61, 0x6000
	s_cmp_eq_u32 s61, 0x12000
	s_cselect_b32 s61, 0, s61
	s_waitcnt lgkmcnt(0)
	s_setprio 1
	v_mfma_f32_16x16x32_bf16 v[2:5], v[210:213], v[178:181], v[2:5]
	v_mfma_f32_16x16x32_bf16 v[18:21], v[210:213], v[182:185], v[18:21]
	v_mfma_f32_16x16x32_bf16 v[22:25], v[214:217], v[182:185], v[22:25]
	v_mfma_f32_16x16x32_bf16 v[6:9], v[214:217], v[178:181], v[6:9]
	s_barrier
	v_mfma_f32_16x16x32_bf16 v[10:13], v[218:221], v[178:181], v[10:13]
	v_mfma_f32_16x16x32_bf16 v[26:29], v[218:221], v[182:185], v[26:29]
	v_mfma_f32_16x16x32_bf16 v[30:33], v[222:225], v[182:185], v[30:33]
	v_mfma_f32_16x16x32_bf16 v[14:17], v[222:225], v[178:181], v[14:17]
	v_mfma_f32_16x16x32_bf16 v[46:49], v[222:225], v[186:189], v[46:49]
	v_mfma_f32_16x16x32_bf16 v[62:65], v[222:225], v[190:193], v[62:65]
	v_mfma_f32_16x16x32_bf16 v[58:61], v[218:221], v[190:193], v[58:61]
	v_mfma_f32_16x16x32_bf16 v[42:45], v[218:221], v[186:189], v[42:45]
	v_mfma_f32_16x16x32_bf16 v[38:41], v[214:217], v[186:189], v[38:41]
	v_mfma_f32_16x16x32_bf16 v[54:57], v[214:217], v[190:193], v[54:57]
	v_mfma_f32_16x16x32_bf16 v[50:53], v[210:213], v[190:193], v[50:53]
	v_mfma_f32_16x16x32_bf16 v[34:37], v[210:213], v[186:189], v[34:37]
	v_mfma_f32_16x16x32_bf16 v[66:69], v[210:213], v[194:197], v[66:69]
	v_mfma_f32_16x16x32_bf16 v[82:85], v[210:213], v[198:201], v[82:85]
	v_mfma_f32_16x16x32_bf16 v[86:89], v[214:217], v[198:201], v[86:89]
	v_mfma_f32_16x16x32_bf16 v[70:73], v[214:217], v[194:197], v[70:73]
	v_mfma_f32_16x16x32_bf16 v[74:77], v[218:221], v[194:197], v[74:77]
	v_mfma_f32_16x16x32_bf16 v[90:93], v[218:221], v[198:201], v[90:93]
	v_mfma_f32_16x16x32_bf16 v[94:97], v[222:225], v[198:201], v[94:97]
	v_mfma_f32_16x16x32_bf16 v[78:81], v[222:225], v[194:197], v[78:81]
	v_mfma_f32_16x16x32_bf16 v[110:113], v[222:225], v[202:205], v[110:113]
	v_mfma_f32_16x16x32_bf16 v[126:129], v[222:225], v[206:209], v[126:129]
	v_mfma_f32_16x16x32_bf16 v[122:125], v[218:221], v[206:209], v[122:125]
	v_mfma_f32_16x16x32_bf16 v[106:109], v[218:221], v[202:205], v[106:109]
	v_mfma_f32_16x16x32_bf16 v[102:105], v[214:217], v[202:205], v[102:105]
	v_mfma_f32_16x16x32_bf16 v[118:121], v[214:217], v[206:209], v[118:121]
	v_mfma_f32_16x16x32_bf16 v[114:117], v[210:213], v[206:209], v[114:117]
	v_mfma_f32_16x16x32_bf16 v[98:101], v[210:213], v[202:205], v[98:101]
	s_setprio 0
	s_nop 7
	s_nop 1
	s_lshl_b32 s26, s35, 11
	s_lshl_b32 s27, s36, 1
	s_add_i32 s26, s26, s27
	s_add_u32 s18, s52, s26
	s_addc_u32 s19, s53, 0
	v_cvt_pk_bf16_f32 v2, v2, v3
	v_cvt_pk_bf16_f32 v3, v4, v5
	v_cvt_pk_bf16_f32 v4, v6, v7
	v_cvt_pk_bf16_f32 v5, v8, v9
	v_cvt_pk_bf16_f32 v6, v10, v11
	v_cvt_pk_bf16_f32 v7, v12, v13
	v_cvt_pk_bf16_f32 v8, v14, v15
	v_cvt_pk_bf16_f32 v9, v16, v17
	global_store_dwordx4 v242, v[2:5], s[18:19]
	global_store_dwordx4 v242, v[6:9], s[18:19] offset:16
	s_add_u32 s18, s18, 0x8000
	s_addc_u32 s19, s19, 0
	v_cvt_pk_bf16_f32 v18, v18, v19
	v_cvt_pk_bf16_f32 v19, v20, v21
	v_cvt_pk_bf16_f32 v20, v22, v23
	v_cvt_pk_bf16_f32 v21, v24, v25
	v_cvt_pk_bf16_f32 v22, v26, v27
	v_cvt_pk_bf16_f32 v23, v28, v29
	v_cvt_pk_bf16_f32 v24, v30, v31
	v_cvt_pk_bf16_f32 v25, v32, v33
	global_store_dwordx4 v242, v[18:21], s[18:19]
	global_store_dwordx4 v242, v[22:25], s[18:19] offset:16
	s_add_u32 s18, s18, 0x8000
	s_addc_u32 s19, s19, 0
	v_cvt_pk_bf16_f32 v34, v34, v35
	v_cvt_pk_bf16_f32 v35, v36, v37
	v_cvt_pk_bf16_f32 v36, v38, v39
	v_cvt_pk_bf16_f32 v37, v40, v41
	v_cvt_pk_bf16_f32 v38, v42, v43
	v_cvt_pk_bf16_f32 v39, v44, v45
	v_cvt_pk_bf16_f32 v40, v46, v47
	v_cvt_pk_bf16_f32 v41, v48, v49
	global_store_dwordx4 v242, v[34:37], s[18:19]
	global_store_dwordx4 v242, v[38:41], s[18:19] offset:16
	s_add_u32 s18, s18, 0x8000
	s_addc_u32 s19, s19, 0
	v_cvt_pk_bf16_f32 v50, v50, v51
	v_cvt_pk_bf16_f32 v51, v52, v53
	v_cvt_pk_bf16_f32 v52, v54, v55
	v_cvt_pk_bf16_f32 v53, v56, v57
	v_cvt_pk_bf16_f32 v54, v58, v59
	v_cvt_pk_bf16_f32 v55, v60, v61
	v_cvt_pk_bf16_f32 v56, v62, v63
	v_cvt_pk_bf16_f32 v57, v64, v65
	global_store_dwordx4 v242, v[50:53], s[18:19]
	global_store_dwordx4 v242, v[54:57], s[18:19] offset:16
	s_add_u32 s18, s18, 0x8000
	s_addc_u32 s19, s19, 0
	v_cvt_pk_bf16_f32 v66, v66, v67
	v_cvt_pk_bf16_f32 v67, v68, v69
	v_cvt_pk_bf16_f32 v68, v70, v71
	v_cvt_pk_bf16_f32 v69, v72, v73
	v_cvt_pk_bf16_f32 v70, v74, v75
	v_cvt_pk_bf16_f32 v71, v76, v77
	v_cvt_pk_bf16_f32 v72, v78, v79
	v_cvt_pk_bf16_f32 v73, v80, v81
	global_store_dwordx4 v242, v[66:69], s[18:19]
	global_store_dwordx4 v242, v[70:73], s[18:19] offset:16
	s_add_u32 s18, s18, 0x8000
	s_addc_u32 s19, s19, 0
	v_cvt_pk_bf16_f32 v82, v82, v83
	v_cvt_pk_bf16_f32 v83, v84, v85
	v_cvt_pk_bf16_f32 v84, v86, v87
	v_cvt_pk_bf16_f32 v85, v88, v89
	v_cvt_pk_bf16_f32 v86, v90, v91
	v_cvt_pk_bf16_f32 v87, v92, v93
	v_cvt_pk_bf16_f32 v88, v94, v95
	v_cvt_pk_bf16_f32 v89, v96, v97
	global_store_dwordx4 v242, v[82:85], s[18:19]
	global_store_dwordx4 v242, v[86:89], s[18:19] offset:16
	s_add_u32 s18, s18, 0x8000
	s_addc_u32 s19, s19, 0
	v_cvt_pk_bf16_f32 v98, v98, v99
	v_cvt_pk_bf16_f32 v99, v100, v101
	v_cvt_pk_bf16_f32 v100, v102, v103
	v_cvt_pk_bf16_f32 v101, v104, v105
	v_cvt_pk_bf16_f32 v102, v106, v107
	v_cvt_pk_bf16_f32 v103, v108, v109
	v_cvt_pk_bf16_f32 v104, v110, v111
	v_cvt_pk_bf16_f32 v105, v112, v113
	global_store_dwordx4 v242, v[98:101], s[18:19]
	global_store_dwordx4 v242, v[102:105], s[18:19] offset:16
	s_add_u32 s18, s18, 0x8000
	s_addc_u32 s19, s19, 0
	v_cvt_pk_bf16_f32 v114, v114, v115
	v_cvt_pk_bf16_f32 v115, v116, v117
	v_cvt_pk_bf16_f32 v116, v118, v119
	v_cvt_pk_bf16_f32 v117, v120, v121
	v_cvt_pk_bf16_f32 v118, v122, v123
	v_cvt_pk_bf16_f32 v119, v124, v125
	v_cvt_pk_bf16_f32 v120, v126, v127
	v_cvt_pk_bf16_f32 v121, v128, v129
	global_store_dwordx4 v242, v[114:117], s[18:19]
	global_store_dwordx4 v242, v[118:121], s[18:19] offset:16

.Lup_nn_a:
	s_waitcnt lgkmcnt(0)
	v_add_u32_e32 v240, s61, v238
	v_add_u32_e32 v241, s61, v239
	s_setprio 1
	v_mfma_f32_16x16x32_bf16 v[2:5], v[162:165], v[130:133], 0
	v_mfma_f32_16x16x32_bf16 v[18:21], v[162:165], v[134:137], 0
	v_mfma_f32_16x16x32_bf16 v[22:25], v[166:169], v[134:137], 0
	v_mfma_f32_16x16x32_bf16 v[6:9], v[166:169], v[130:133], 0
	s_waitcnt vmcnt(6)
	s_barrier
	v_mfma_f32_16x16x32_bf16 v[10:13], v[170:173], v[130:133], 0
	s_add_i32 m0, s60, s62
	v_mfma_f32_16x16x32_bf16 v[26:29], v[170:173], v[134:137], 0
	global_load_lds_dwordx4 v226, s[54:55]
	v_mfma_f32_16x16x32_bf16 v[30:33], v[174:177], v[134:137], 0
	v_mfma_f32_16x16x32_bf16 v[14:17], v[174:177], v[130:133], 0
	v_mfma_f32_16x16x32_bf16 v[46:49], v[174:177], v[138:141], 0
	ds_read_b128 v[210:213], v241 offset:0
	v_mfma_f32_16x16x32_bf16 v[62:65], v[174:177], v[142:145], 0
	ds_read_b128 v[214:217], v241 offset:256
	v_mfma_f32_16x16x32_bf16 v[58:61], v[170:173], v[142:145], 0
	ds_read_b128 v[218:221], v241 offset:2048
	global_load_lds_dwordx4 v226, s[54:55] offset:1024
	v_mfma_f32_16x16x32_bf16 v[42:45], v[170:173], v[138:141], 0
	ds_read_b128 v[222:225], v241 offset:2304
	v_mfma_f32_16x16x32_bf16 v[38:41], v[166:169], v[138:141], 0
	ds_read_b128 v[178:181], v240 offset:0
	v_mfma_f32_16x16x32_bf16 v[54:57], v[166:169], v[142:145], 0
	ds_read_b128 v[182:185], v240 offset:1024
	v_mfma_f32_16x16x32_bf16 v[50:53], v[162:165], v[142:145], 0
	ds_read_b128 v[186:189], v240 offset:2048
	v_mfma_f32_16x16x32_bf16 v[34:37], v[162:165], v[138:141], 0
	ds_read_b128 v[190:193], v240 offset:3072
	global_load_lds_dwordx4 v226, s[54:55] offset:2048
	v_mfma_f32_16x16x32_bf16 v[66:69], v[162:165], v[146:149], 0
	ds_read_b128 v[194:197], v240 offset:4096
	v_mfma_f32_16x16x32_bf16 v[82:85], v[162:165], v[150:153], 0
	ds_read_b128 v[198:201], v240 offset:5120
	v_mfma_f32_16x16x32_bf16 v[86:89], v[166:169], v[150:153], 0
	ds_read_b128 v[202:205], v240 offset:6144
	v_mfma_f32_16x16x32_bf16 v[70:73], v[166:169], v[146:149], 0
	ds_read_b128 v[206:209], v240 offset:7168
	v_mfma_f32_16x16x32_bf16 v[74:77], v[170:173], v[146:149], 0
	global_load_lds_dwordx4 v226, s[54:55] offset:3072
	v_mfma_f32_16x16x32_bf16 v[90:93], v[170:173], v[150:153], 0
	v_mfma_f32_16x16x32_bf16 v[94:97], v[174:177], v[150:153], 0
	v_mfma_f32_16x16x32_bf16 v[78:81], v[174:177], v[146:149], 0
	v_mfma_f32_16x16x32_bf16 v[110:113], v[174:177], v[154:157], 0
	s_add_i32 m0, s60, s63
	v_mfma_f32_16x16x32_bf16 v[126:129], v[174:177], v[158:161], 0
	global_load_lds_dwordx4 v230, s[56:57]
	v_mfma_f32_16x16x32_bf16 v[122:125], v[170:173], v[158:161], 0
	v_mfma_f32_16x16x32_bf16 v[106:109], v[170:173], v[154:157], 0
	v_mfma_f32_16x16x32_bf16 v[102:105], v[166:169], v[154:157], 0
	v_mfma_f32_16x16x32_bf16 v[118:121], v[166:169], v[158:161], 0
	v_mfma_f32_16x16x32_bf16 v[114:117], v[162:165], v[158:161], 0
	global_load_lds_dwordx4 v231, s[56:57] offset:1024
	v_mfma_f32_16x16x32_bf16 v[98:101], v[162:165], v[154:157], 0
	s_setprio 0
	s_add_i32 s60, s60, 0x6000
	s_cmp_eq_u32 s60, 0x12000
	s_cselect_b32 s60, 0, s60
	s_add_u32 s54, s54, s72
	s_addc_u32 s55, s55, 0
	s_add_u32 s56, s56, s73
	s_addc_u32 s57, s57, 0
	s_add_i32 s61, s61, 0x6000
	s_cmp_eq_u32 s61, 0x12000
	s_cselect_b32 s61, 0, s61
	v_mbcnt_lo_u32_b32 v0, -1, 0
	v_lshlrev_b32_e32 v0, 4, v0
	s_lshl_b32 s26, s36, 1
	v_add_u32_e32 v0, s26, v0
	s_lshl_b32 s26, s41, 8
	s_add_i32 m0, s26, 0x13010
	s_mov_b64 exec, 0xffff
	global_load_lds_dwordx4 v0, s[82:83]
	s_mov_b64 exec, -1
	s_waitcnt lgkmcnt(0)
	v_add_u32_e32 v240, s61, v238
	v_add_u32_e32 v241, s61, v239
	s_setprio 1
	v_mfma_f32_16x16x32_bf16 v[2:5], v[210:213], v[178:181], v[2:5]
	v_mfma_f32_16x16x32_bf16 v[18:21], v[210:213], v[182:185], v[18:21]
	v_mfma_f32_16x16x32_bf16 v[22:25], v[214:217], v[182:185], v[22:25]
	v_mfma_f32_16x16x32_bf16 v[6:9], v[214:217], v[178:181], v[6:9]
	s_waitcnt vmcnt(6)
	s_barrier
	v_mfma_f32_16x16x32_bf16 v[10:13], v[218:221], v[178:181], v[10:13]
	s_add_i32 m0, s60, s62
	v_mfma_f32_16x16x32_bf16 v[26:29], v[218:221], v[182:185], v[26:29]
	global_load_lds_dwordx4 v226, s[54:55]
	v_mfma_f32_16x16x32_bf16 v[30:33], v[222:225], v[182:185], v[30:33]
	v_mfma_f32_16x16x32_bf16 v[14:17], v[222:225], v[178:181], v[14:17]
	v_mfma_f32_16x16x32_bf16 v[46:49], v[222:225], v[186:189], v[46:49]
	ds_read_b128 v[162:165], v241 offset:0
	v_mfma_f32_16x16x32_bf16 v[62:65], v[222:225], v[190:193], v[62:65]
	ds_read_b128 v[166:169], v241 offset:256
	v_mfma_f32_16x16x32_bf16 v[58:61], v[218:221], v[190:193], v[58:61]
	ds_read_b128 v[170:173], v241 offset:2048
	global_load_lds_dwordx4 v226, s[54:55] offset:1024
	v_mfma_f32_16x16x32_bf16 v[42:45], v[218:221], v[186:189], v[42:45]
	ds_read_b128 v[174:177], v241 offset:2304
	v_mfma_f32_16x16x32_bf16 v[38:41], v[214:217], v[186:189], v[38:41]
	ds_read_b128 v[130:133], v240 offset:0
	v_mfma_f32_16x16x32_bf16 v[54:57], v[214:217], v[190:193], v[54:57]
	ds_read_b128 v[134:137], v240 offset:1024
	v_mfma_f32_16x16x32_bf16 v[50:53], v[210:213], v[190:193], v[50:53]
	ds_read_b128 v[138:141], v240 offset:2048
	v_mfma_f32_16x16x32_bf16 v[34:37], v[210:213], v[186:189], v[34:37]
	ds_read_b128 v[142:145], v240 offset:3072
	global_load_lds_dwordx4 v226, s[54:55] offset:2048
	v_mfma_f32_16x16x32_bf16 v[66:69], v[210:213], v[194:197], v[66:69]
	ds_read_b128 v[146:149], v240 offset:4096
	v_mfma_f32_16x16x32_bf16 v[82:85], v[210:213], v[198:201], v[82:85]
	ds_read_b128 v[150:153], v240 offset:5120
	v_mfma_f32_16x16x32_bf16 v[86:89], v[214:217], v[198:201], v[86:89]
	ds_read_b128 v[154:157], v240 offset:6144
	v_mfma_f32_16x16x32_bf16 v[70:73], v[214:217], v[194:197], v[70:73]
	ds_read_b128 v[158:161], v240 offset:7168
	v_mfma_f32_16x16x32_bf16 v[74:77], v[218:221], v[194:197], v[74:77]
	global_load_lds_dwordx4 v226, s[54:55] offset:3072
	v_mfma_f32_16x16x32_bf16 v[90:93], v[218:221], v[198:201], v[90:93]
	v_mfma_f32_16x16x32_bf16 v[94:97], v[222:225], v[198:201], v[94:97]
	v_mfma_f32_16x16x32_bf16 v[78:81], v[222:225], v[194:197], v[78:81]
	v_mfma_f32_16x16x32_bf16 v[110:113], v[222:225], v[202:205], v[110:113]
	s_add_i32 m0, s60, s63
	v_mfma_f32_16x16x32_bf16 v[126:129], v[222:225], v[206:209], v[126:129]
	global_load_lds_dwordx4 v230, s[56:57]
	v_mfma_f32_16x16x32_bf16 v[122:125], v[218:221], v[206:209], v[122:125]
	v_mfma_f32_16x16x32_bf16 v[106:109], v[218:221], v[202:205], v[106:109]
	v_mfma_f32_16x16x32_bf16 v[102:105], v[214:217], v[202:205], v[102:105]
	v_mfma_f32_16x16x32_bf16 v[118:121], v[214:217], v[206:209], v[118:121]
	v_mfma_f32_16x16x32_bf16 v[114:117], v[210:213], v[206:209], v[114:117]
	global_load_lds_dwordx4 v231, s[56:57] offset:1024
	v_mfma_f32_16x16x32_bf16 v[98:101], v[210:213], v[202:205], v[98:101]
	s_setprio 0
	s_add_i32 s60, s60, 0x6000
	s_cmp_eq_u32 s60, 0x12000
	s_cselect_b32 s60, 0, s60
	s_add_u32 s54, s54, s72
	s_addc_u32 s55, s55, 0
	s_add_u32 s56, s56, s73
	s_addc_u32 s57, s57, 0
	s_add_i32 s61, s61, 0x6000
	s_cmp_eq_u32 s61, 0x12000
	s_cselect_b32 s61, 0, s61
	s_branch .Lup_main

.Lup_nn_b:
	s_waitcnt lgkmcnt(0)
	v_add_u32_e32 v240, s61, v238
	v_add_u32_e32 v241, s61, v239
	s_setprio 1
	v_mfma_f32_16x16x32_bf16 v[2:5], v[162:165], v[130:133], 0
	v_mfma_f32_16x16x32_bf16 v[18:21], v[162:165], v[134:137], 0
	v_mfma_f32_16x16x32_bf16 v[22:25], v[166:169], v[134:137], 0
	v_mfma_f32_16x16x32_bf16 v[6:9], v[166:169], v[130:133], 0
	s_waitcnt vmcnt(14)
	s_barrier
	v_mfma_f32_16x16x32_bf16 v[10:13], v[170:173], v[130:133], 0
	s_add_i32 m0, s60, s62
	v_mfma_f32_16x16x32_bf16 v[26:29], v[170:173], v[134:137], 0
	global_load_lds_dwordx4 v226, s[54:55]
	v_mfma_f32_16x16x32_bf16 v[30:33], v[174:177], v[134:137], 0
	v_mfma_f32_16x16x32_bf16 v[14:17], v[174:177], v[130:133], 0
	v_mfma_f32_16x16x32_bf16 v[46:49], v[174:177], v[138:141], 0
	ds_read_b128 v[210:213], v241 offset:0
	v_mfma_f32_16x16x32_bf16 v[62:65], v[174:177], v[142:145], 0
	ds_read_b128 v[214:217], v241 offset:256
	v_mfma_f32_16x16x32_bf16 v[58:61], v[170:173], v[142:145], 0
	ds_read_b128 v[218:221], v241 offset:2048
	global_load_lds_dwordx4 v226, s[54:55] offset:1024
	v_mfma_f32_16x16x32_bf16 v[42:45], v[170:173], v[138:141], 0
	ds_read_b128 v[222:225], v241 offset:2304
	v_mfma_f32_16x16x32_bf16 v[38:41], v[166:169], v[138:141], 0
	ds_read_b128 v[178:181], v240 offset:0
	v_mfma_f32_16x16x32_bf16 v[54:57], v[166:169], v[142:145], 0
	ds_read_b128 v[182:185], v240 offset:1024
	v_mfma_f32_16x16x32_bf16 v[50:53], v[162:165], v[142:145], 0
	ds_read_b128 v[186:189], v240 offset:2048
	v_mfma_f32_16x16x32_bf16 v[34:37], v[162:165], v[138:141], 0
	ds_read_b128 v[190:193], v240 offset:3072
	global_load_lds_dwordx4 v226, s[54:55] offset:2048
	v_mfma_f32_16x16x32_bf16 v[66:69], v[162:165], v[146:149], 0
	ds_read_b128 v[194:197], v240 offset:4096
	v_mfma_f32_16x16x32_bf16 v[82:85], v[162:165], v[150:153], 0
	ds_read_b128 v[198:201], v240 offset:5120
	v_mfma_f32_16x16x32_bf16 v[86:89], v[166:169], v[150:153], 0
	ds_read_b128 v[202:205], v240 offset:6144
	v_mfma_f32_16x16x32_bf16 v[70:73], v[166:169], v[146:149], 0
	ds_read_b128 v[206:209], v240 offset:7168
	v_mfma_f32_16x16x32_bf16 v[74:77], v[170:173], v[146:149], 0
	global_load_lds_dwordx4 v226, s[54:55] offset:3072
	v_mfma_f32_16x16x32_bf16 v[90:93], v[170:173], v[150:153], 0
	v_mfma_f32_16x16x32_bf16 v[94:97], v[174:177], v[150:153], 0
	v_mfma_f32_16x16x32_bf16 v[78:81], v[174:177], v[146:149], 0
	v_mfma_f32_16x16x32_bf16 v[110:113], v[174:177], v[154:157], 0
	s_add_i32 m0, s60, s63
	v_mfma_f32_16x16x32_bf16 v[126:129], v[174:177], v[158:161], 0
	global_load_lds_dwordx4 v230, s[56:57]
	v_mfma_f32_16x16x32_bf16 v[122:125], v[170:173], v[158:161], 0
	v_mfma_f32_16x16x32_bf16 v[106:109], v[170:173], v[154:157], 0
	v_mfma_f32_16x16x32_bf16 v[102:105], v[166:169], v[154:157], 0
	v_mfma_f32_16x16x32_bf16 v[118:121], v[166:169], v[158:161], 0
	v_mfma_f32_16x16x32_bf16 v[114:117], v[162:165], v[158:161], 0
	global_load_lds_dwordx4 v231, s[56:57] offset:1024
	v_mfma_f32_16x16x32_bf16 v[98:101], v[162:165], v[154:157], 0
	s_setprio 0
	s_add_i32 s60, s60, 0x6000
	s_cmp_eq_u32 s60, 0x12000
	s_cselect_b32 s60, 0, s60
	s_add_u32 s54, s54, s72
	s_addc_u32 s55, s55, 0
	s_add_u32 s56, s56, s73
	s_addc_u32 s57, s57, 0
	s_add_i32 s61, s61, 0x6000
	s_cmp_eq_u32 s61, 0x12000
	s_cselect_b32 s61, 0, s61
	v_mbcnt_lo_u32_b32 v0, -1, 0
	v_lshlrev_b32_e32 v0, 4, v0
	s_lshl_b32 s26, s36, 1
	v_add_u32_e32 v0, s26, v0
	s_lshl_b32 s26, s41, 8
	s_add_i32 m0, s26, 0x13010
	s_mov_b64 exec, 0xffff
	global_load_lds_dwordx4 v0, s[82:83]
	s_mov_b64 exec, -1
	s_waitcnt lgkmcnt(0)
	v_add_u32_e32 v240, s61, v238
	v_add_u32_e32 v241, s61, v239
	s_setprio 1
	v_mfma_f32_16x16x32_bf16 v[2:5], v[210:213], v[178:181], v[2:5]
	v_mfma_f32_16x16x32_bf16 v[18:21], v[210:213], v[182:185], v[18:21]
	v_mfma_f32_16x16x32_bf16 v[22:25], v[214:217], v[182:185], v[22:25]
	v_mfma_f32_16x16x32_bf16 v[6:9], v[214:217], v[178:181], v[6:9]
	s_waitcnt vmcnt(14)
	s_barrier
	v_mfma_f32_16x16x32_bf16 v[10:13], v[218:221], v[178:181], v[10:13]
	s_add_i32 m0, s60, s62
	v_mfma_f32_16x16x32_bf16 v[26:29], v[218:221], v[182:185], v[26:29]
	global_load_lds_dwordx4 v226, s[54:55]
	v_mfma_f32_16x16x32_bf16 v[30:33], v[222:225], v[182:185], v[30:33]
	v_mfma_f32_16x16x32_bf16 v[14:17], v[222:225], v[178:181], v[14:17]
	v_mfma_f32_16x16x32_bf16 v[46:49], v[222:225], v[186:189], v[46:49]
	ds_read_b128 v[162:165], v241 offset:0
	v_mfma_f32_16x16x32_bf16 v[62:65], v[222:225], v[190:193], v[62:65]
	ds_read_b128 v[166:169], v241 offset:256
	v_mfma_f32_16x16x32_bf16 v[58:61], v[218:221], v[190:193], v[58:61]
	ds_read_b128 v[170:173], v241 offset:2048
	global_load_lds_dwordx4 v226, s[54:55] offset:1024
	v_mfma_f32_16x16x32_bf16 v[42:45], v[218:221], v[186:189], v[42:45]
	ds_read_b128 v[174:177], v241 offset:2304
	v_mfma_f32_16x16x32_bf16 v[38:41], v[214:217], v[186:189], v[38:41]
	ds_read_b128 v[130:133], v240 offset:0
	v_mfma_f32_16x16x32_bf16 v[54:57], v[214:217], v[190:193], v[54:57]
	ds_read_b128 v[134:137], v240 offset:1024
	v_mfma_f32_16x16x32_bf16 v[50:53], v[210:213], v[190:193], v[50:53]
	ds_read_b128 v[138:141], v240 offset:2048
	v_mfma_f32_16x16x32_bf16 v[34:37], v[210:213], v[186:189], v[34:37]
	ds_read_b128 v[142:145], v240 offset:3072
	global_load_lds_dwordx4 v226, s[54:55] offset:2048
	v_mfma_f32_16x16x32_bf16 v[66:69], v[210:213], v[194:197], v[66:69]
	ds_read_b128 v[146:149], v240 offset:4096
	v_mfma_f32_16x16x32_bf16 v[82:85], v[210:213], v[198:201], v[82:85]
	ds_read_b128 v[150:153], v240 offset:5120
	v_mfma_f32_16x16x32_bf16 v[86:89], v[214:217], v[198:201], v[86:89]
	ds_read_b128 v[154:157], v240 offset:6144
	v_mfma_f32_16x16x32_bf16 v[70:73], v[214:217], v[194:197], v[70:73]
	ds_read_b128 v[158:161], v240 offset:7168
	v_mfma_f32_16x16x32_bf16 v[74:77], v[218:221], v[194:197], v[74:77]
	global_load_lds_dwordx4 v226, s[54:55] offset:3072
	v_mfma_f32_16x16x32_bf16 v[90:93], v[218:221], v[198:201], v[90:93]
	v_mfma_f32_16x16x32_bf16 v[94:97], v[222:225], v[198:201], v[94:97]
	v_mfma_f32_16x16x32_bf16 v[78:81], v[222:225], v[194:197], v[78:81]
	v_mfma_f32_16x16x32_bf16 v[110:113], v[222:225], v[202:205], v[110:113]
	s_add_i32 m0, s60, s63
	v_mfma_f32_16x16x32_bf16 v[126:129], v[222:225], v[206:209], v[126:129]
	global_load_lds_dwordx4 v230, s[56:57]
	v_mfma_f32_16x16x32_bf16 v[122:125], v[218:221], v[206:209], v[122:125]
	v_mfma_f32_16x16x32_bf16 v[106:109], v[218:221], v[202:205], v[106:109]
	v_mfma_f32_16x16x32_bf16 v[102:105], v[214:217], v[202:205], v[102:105]
	v_mfma_f32_16x16x32_bf16 v[118:121], v[214:217], v[206:209], v[118:121]
	v_mfma_f32_16x16x32_bf16 v[114:117], v[210:213], v[206:209], v[114:117]
	global_load_lds_dwordx4 v231, s[56:57] offset:1024
	v_mfma_f32_16x16x32_bf16 v[98:101], v[210:213], v[202:205], v[98:101]
	s_setprio 0
	s_add_i32 s60, s60, 0x6000
	s_cmp_eq_u32 s60, 0x12000
	s_cselect_b32 s60, 0, s60
	s_add_u32 s54, s54, s72
	s_addc_u32 s55, s55, 0
	s_add_u32 s56, s56, s73
	s_addc_u32 s57, s57, 0
	s_add_i32 s61, s61, 0x6000
	s_cmp_eq_u32 s61, 0x12000
	s_cselect_b32 s61, 0, s61

.Lup_kloop:
	s_waitcnt lgkmcnt(0)
	v_add_u32_e32 v240, s61, v238
	v_add_u32_e32 v241, s61, v239
	s_setprio 1
	v_mfma_f32_16x16x32_bf16 v[2:5], v[162:165], v[130:133], v[2:5]
	v_mfma_f32_16x16x32_bf16 v[18:21], v[162:165], v[134:137], v[18:21]
	v_mfma_f32_16x16x32_bf16 v[22:25], v[166:169], v[134:137], v[22:25]
	v_mfma_f32_16x16x32_bf16 v[6:9], v[166:169], v[130:133], v[6:9]
	s_waitcnt vmcnt(6)
	s_barrier
	v_mfma_f32_16x16x32_bf16 v[10:13], v[170:173], v[130:133], v[10:13]
	s_add_i32 m0, s60, s62
	v_mfma_f32_16x16x32_bf16 v[26:29], v[170:173], v[134:137], v[26:29]
	global_load_lds_dwordx4 v226, s[54:55]
	v_mfma_f32_16x16x32_bf16 v[30:33], v[174:177], v[134:137], v[30:33]
	v_mfma_f32_16x16x32_bf16 v[14:17], v[174:177], v[130:133], v[14:17]
	v_mfma_f32_16x16x32_bf16 v[46:49], v[174:177], v[138:141], v[46:49]
	ds_read_b128 v[210:213], v241 offset:0
	v_mfma_f32_16x16x32_bf16 v[62:65], v[174:177], v[142:145], v[62:65]
	ds_read_b128 v[214:217], v241 offset:256
	v_mfma_f32_16x16x32_bf16 v[58:61], v[170:173], v[142:145], v[58:61]
	ds_read_b128 v[218:221], v241 offset:2048
	global_load_lds_dwordx4 v226, s[54:55] offset:1024
	v_mfma_f32_16x16x32_bf16 v[42:45], v[170:173], v[138:141], v[42:45]
	ds_read_b128 v[222:225], v241 offset:2304
	v_mfma_f32_16x16x32_bf16 v[38:41], v[166:169], v[138:141], v[38:41]
	ds_read_b128 v[178:181], v240 offset:0
	v_mfma_f32_16x16x32_bf16 v[54:57], v[166:169], v[142:145], v[54:57]
	ds_read_b128 v[182:185], v240 offset:1024
	v_mfma_f32_16x16x32_bf16 v[50:53], v[162:165], v[142:145], v[50:53]
	ds_read_b128 v[186:189], v240 offset:2048
	v_mfma_f32_16x16x32_bf16 v[34:37], v[162:165], v[138:141], v[34:37]
	ds_read_b128 v[190:193], v240 offset:3072
	global_load_lds_dwordx4 v226, s[54:55] offset:2048
	v_mfma_f32_16x16x32_bf16 v[66:69], v[162:165], v[146:149], v[66:69]
	ds_read_b128 v[194:197], v240 offset:4096
	v_mfma_f32_16x16x32_bf16 v[82:85], v[162:165], v[150:153], v[82:85]
	ds_read_b128 v[198:201], v240 offset:5120
	v_mfma_f32_16x16x32_bf16 v[86:89], v[166:169], v[150:153], v[86:89]
	ds_read_b128 v[202:205], v240 offset:6144
	v_mfma_f32_16x16x32_bf16 v[70:73], v[166:169], v[146:149], v[70:73]
	ds_read_b128 v[206:209], v240 offset:7168
	v_mfma_f32_16x16x32_bf16 v[74:77], v[170:173], v[146:149], v[74:77]
	global_load_lds_dwordx4 v226, s[54:55] offset:3072
	v_mfma_f32_16x16x32_bf16 v[90:93], v[170:173], v[150:153], v[90:93]
	v_mfma_f32_16x16x32_bf16 v[94:97], v[174:177], v[150:153], v[94:97]
	v_mfma_f32_16x16x32_bf16 v[78:81], v[174:177], v[146:149], v[78:81]
	v_mfma_f32_16x16x32_bf16 v[110:113], v[174:177], v[154:157], v[110:113]
	s_add_i32 m0, s60, s63
	v_mfma_f32_16x16x32_bf16 v[126:129], v[174:177], v[158:161], v[126:129]
	global_load_lds_dwordx4 v230, s[56:57]
	v_mfma_f32_16x16x32_bf16 v[122:125], v[170:173], v[158:161], v[122:125]
	v_mfma_f32_16x16x32_bf16 v[106:109], v[170:173], v[154:157], v[106:109]
	v_mfma_f32_16x16x32_bf16 v[102:105], v[166:169], v[154:157], v[102:105]
	v_mfma_f32_16x16x32_bf16 v[118:121], v[166:169], v[158:161], v[118:121]
	v_mfma_f32_16x16x32_bf16 v[114:117], v[162:165], v[158:161], v[114:117]
	global_load_lds_dwordx4 v231, s[56:57] offset:1024
	v_mfma_f32_16x16x32_bf16 v[98:101], v[162:165], v[154:157], v[98:101]
	s_setprio 0
	s_add_i32 s60, s60, 0x6000
	s_cmp_eq_u32 s60, 0x12000
	s_cselect_b32 s60, 0, s60
	s_add_u32 s54, s54, s72
	s_addc_u32 s55, s55, 0
	s_add_u32 s56, s56, s73
	s_addc_u32 s57, s57, 0
	s_add_i32 s61, s61, 0x6000
	s_cmp_eq_u32 s61, 0x12000
	s_cselect_b32 s61, 0, s61
	s_waitcnt lgkmcnt(0)
	v_add_u32_e32 v240, s61, v238
	v_add_u32_e32 v241, s61, v239
	s_setprio 1
	v_mfma_f32_16x16x32_bf16 v[2:5], v[210:213], v[178:181], v[2:5]
	v_mfma_f32_16x16x32_bf16 v[18:21], v[210:213], v[182:185], v[18:21]
	v_mfma_f32_16x16x32_bf16 v[22:25], v[214:217], v[182:185], v[22:25]
	v_mfma_f32_16x16x32_bf16 v[6:9], v[214:217], v[178:181], v[6:9]
	s_waitcnt vmcnt(6)
	s_barrier
	v_mfma_f32_16x16x32_bf16 v[10:13], v[218:221], v[178:181], v[10:13]
	s_add_i32 m0, s60, s62
	v_mfma_f32_16x16x32_bf16 v[26:29], v[218:221], v[182:185], v[26:29]
	global_load_lds_dwordx4 v226, s[54:55]
	v_mfma_f32_16x16x32_bf16 v[30:33], v[222:225], v[182:185], v[30:33]
	v_mfma_f32_16x16x32_bf16 v[14:17], v[222:225], v[178:181], v[14:17]
	v_mfma_f32_16x16x32_bf16 v[46:49], v[222:225], v[186:189], v[46:49]
	ds_read_b128 v[162:165], v241 offset:0
	v_mfma_f32_16x16x32_bf16 v[62:65], v[222:225], v[190:193], v[62:65]
	ds_read_b128 v[166:169], v241 offset:256
	v_mfma_f32_16x16x32_bf16 v[58:61], v[218:221], v[190:193], v[58:61]
	ds_read_b128 v[170:173], v241 offset:2048
	global_load_lds_dwordx4 v226, s[54:55] offset:1024
	v_mfma_f32_16x16x32_bf16 v[42:45], v[218:221], v[186:189], v[42:45]
	ds_read_b128 v[174:177], v241 offset:2304
	v_mfma_f32_16x16x32_bf16 v[38:41], v[214:217], v[186:189], v[38:41]
	ds_read_b128 v[130:133], v240 offset:0
	v_mfma_f32_16x16x32_bf16 v[54:57], v[214:217], v[190:193], v[54:57]
	ds_read_b128 v[134:137], v240 offset:1024
	v_mfma_f32_16x16x32_bf16 v[50:53], v[210:213], v[190:193], v[50:53]
	ds_read_b128 v[138:141], v240 offset:2048
	v_mfma_f32_16x16x32_bf16 v[34:37], v[210:213], v[186:189], v[34:37]
	ds_read_b128 v[142:145], v240 offset:3072
	global_load_lds_dwordx4 v226, s[54:55] offset:2048
	v_mfma_f32_16x16x32_bf16 v[66:69], v[210:213], v[194:197], v[66:69]
	ds_read_b128 v[146:149], v240 offset:4096
	v_mfma_f32_16x16x32_bf16 v[82:85], v[210:213], v[198:201], v[82:85]
	ds_read_b128 v[150:153], v240 offset:5120
	v_mfma_f32_16x16x32_bf16 v[86:89], v[214:217], v[198:201], v[86:89]
	ds_read_b128 v[154:157], v240 offset:6144
	v_mfma_f32_16x16x32_bf16 v[70:73], v[214:217], v[194:197], v[70:73]
	ds_read_b128 v[158:161], v240 offset:7168
	v_mfma_f32_16x16x32_bf16 v[74:77], v[218:221], v[194:197], v[74:77]
	global_load_lds_dwordx4 v226, s[54:55] offset:3072
	v_mfma_f32_16x16x32_bf16 v[90:93], v[218:221], v[198:201], v[90:93]
	v_mfma_f32_16x16x32_bf16 v[94:97], v[222:225], v[198:201], v[94:97]
	v_mfma_f32_16x16x32_bf16 v[78:81], v[222:225], v[194:197], v[78:81]
	v_mfma_f32_16x16x32_bf16 v[110:113], v[222:225], v[202:205], v[110:113]
	s_add_i32 m0, s60, s63
	v_mfma_f32_16x16x32_bf16 v[126:129], v[222:225], v[206:209], v[126:129]
	global_load_lds_dwordx4 v230, s[56:57]
	v_mfma_f32_16x16x32_bf16 v[122:125], v[218:221], v[206:209], v[122:125]
	v_mfma_f32_16x16x32_bf16 v[106:109], v[218:221], v[202:205], v[106:109]
	v_mfma_f32_16x16x32_bf16 v[102:105], v[214:217], v[202:205], v[102:105]
	v_mfma_f32_16x16x32_bf16 v[118:121], v[214:217], v[206:209], v[118:121]
	v_mfma_f32_16x16x32_bf16 v[114:117], v[210:213], v[206:209], v[114:117]
	global_load_lds_dwordx4 v231, s[56:57] offset:1024
	v_mfma_f32_16x16x32_bf16 v[98:101], v[210:213], v[202:205], v[98:101]
	s_setprio 0
	s_add_i32 s60, s60, 0x6000
	s_cmp_eq_u32 s60, 0x12000
	s_cselect_b32 s60, 0, s60
	s_add_u32 s54, s54, s72
	s_addc_u32 s55, s55, 0
	s_add_u32 s56, s56, s73
	s_addc_u32 s57, s57, 0
	s_add_i32 s61, s61, 0x6000
	s_cmp_eq_u32 s61, 0x12000
	s_cselect_b32 s61, 0, s61
	s_add_i32 s40, s40, -1
	s_cmp_lg_u32 s40, 0
	s_cbranch_scc1 .Lup_kloop
.Lup_kdone:
	s_cmp_eq_u32 s37, 0
	s_cbranch_scc1 .Lup_tail_last
	s_waitcnt lgkmcnt(0)
	v_add_u32_e32 v240, s61, v238
	v_add_u32_e32 v241, s61, v239
	s_setprio 1
	v_mfma_f32_16x16x32_bf16 v[2:5], v[162:165], v[130:133], v[2:5]
	v_mfma_f32_16x16x32_bf16 v[18:21], v[162:165], v[134:137], v[18:21]
	v_mfma_f32_16x16x32_bf16 v[22:25], v[166:169], v[134:137], v[22:25]
	v_mfma_f32_16x16x32_bf16 v[6:9], v[166:169], v[130:133], v[6:9]
	s_waitcnt vmcnt(6)
	s_barrier
	v_mfma_f32_16x16x32_bf16 v[10:13], v[170:173], v[130:133], v[10:13]
	s_add_i32 m0, s60, s62
	v_mfma_f32_16x16x32_bf16 v[26:29], v[170:173], v[134:137], v[26:29]
	global_load_lds_dwordx4 v226, s[54:55]
	v_mfma_f32_16x16x32_bf16 v[30:33], v[174:177], v[134:137], v[30:33]
	v_mfma_f32_16x16x32_bf16 v[14:17], v[174:177], v[130:133], v[14:17]
	v_mfma_f32_16x16x32_bf16 v[46:49], v[174:177], v[138:141], v[46:49]
	ds_read_b128 v[210:213], v241 offset:0
	v_mfma_f32_16x16x32_bf16 v[62:65], v[174:177], v[142:145], v[62:65]
	ds_read_b128 v[214:217], v241 offset:256
	v_mfma_f32_16x16x32_bf16 v[58:61], v[170:173], v[142:145], v[58:61]
	ds_read_b128 v[218:221], v241 offset:2048
	global_load_lds_dwordx4 v226, s[54:55] offset:1024
	v_mfma_f32_16x16x32_bf16 v[42:45], v[170:173], v[138:141], v[42:45]
	ds_read_b128 v[222:225], v241 offset:2304
	v_mfma_f32_16x16x32_bf16 v[38:41], v[166:169], v[138:141], v[38:41]
	ds_read_b128 v[178:181], v240 offset:0
	v_mfma_f32_16x16x32_bf16 v[54:57], v[166:169], v[142:145], v[54:57]
	ds_read_b128 v[182:185], v240 offset:1024
	v_mfma_f32_16x16x32_bf16 v[50:53], v[162:165], v[142:145], v[50:53]
	ds_read_b128 v[186:189], v240 offset:2048
	v_mfma_f32_16x16x32_bf16 v[34:37], v[162:165], v[138:141], v[34:37]
	ds_read_b128 v[190:193], v240 offset:3072
	global_load_lds_dwordx4 v226, s[54:55] offset:2048
	v_mfma_f32_16x16x32_bf16 v[66:69], v[162:165], v[146:149], v[66:69]
	ds_read_b128 v[194:197], v240 offset:4096
	v_mfma_f32_16x16x32_bf16 v[82:85], v[162:165], v[150:153], v[82:85]
	ds_read_b128 v[198:201], v240 offset:5120
	v_mfma_f32_16x16x32_bf16 v[86:89], v[166:169], v[150:153], v[86:89]
	ds_read_b128 v[202:205], v240 offset:6144
	v_mfma_f32_16x16x32_bf16 v[70:73], v[166:169], v[146:149], v[70:73]
	ds_read_b128 v[206:209], v240 offset:7168
	v_mfma_f32_16x16x32_bf16 v[74:77], v[170:173], v[146:149], v[74:77]
	global_load_lds_dwordx4 v226, s[54:55] offset:3072
	v_mfma_f32_16x16x32_bf16 v[90:93], v[170:173], v[150:153], v[90:93]
	v_mfma_f32_16x16x32_bf16 v[94:97], v[174:177], v[150:153], v[94:97]
	v_mfma_f32_16x16x32_bf16 v[78:81], v[174:177], v[146:149], v[78:81]
	v_mfma_f32_16x16x32_bf16 v[110:113], v[174:177], v[154:157], v[110:113]
	s_add_i32 m0, s60, s63
	v_mfma_f32_16x16x32_bf16 v[126:129], v[174:177], v[158:161], v[126:129]
	global_load_lds_dwordx4 v230, s[56:57]
	v_mfma_f32_16x16x32_bf16 v[122:125], v[170:173], v[158:161], v[122:125]
	v_mfma_f32_16x16x32_bf16 v[106:109], v[170:173], v[154:157], v[106:109]
	v_mfma_f32_16x16x32_bf16 v[102:105], v[166:169], v[154:157], v[102:105]
	v_mfma_f32_16x16x32_bf16 v[118:121], v[166:169], v[158:161], v[118:121]
	v_mfma_f32_16x16x32_bf16 v[114:117], v[162:165], v[158:161], v[114:117]
	global_load_lds_dwordx4 v231, s[56:57] offset:1024
	v_mfma_f32_16x16x32_bf16 v[98:101], v[162:165], v[154:157], v[98:101]
	s_setprio 0
	s_add_i32 s60, s60, 0x6000
	s_cmp_eq_u32 s60, 0x12000
	s_cselect_b32 s60, 0, s60
	s_add_u32 s54, s54, s72
	s_addc_u32 s55, s55, 0
	s_add_u32 s56, s56, s73
	s_addc_u32 s57, s57, 0
	s_add_i32 s61, s61, 0x6000
	s_cmp_eq_u32 s61, 0x12000
	s_cselect_b32 s61, 0, s61
	v_mov_b32_e32 v226, v232
	v_mov_b32_e32 v230, v236
	v_mov_b32_e32 v231, v237
	s_mov_b64 s[54:55], s[48:49]
	s_mov_b64 s[56:57], s[50:51]
	s_waitcnt lgkmcnt(0)
	v_add_u32_e32 v240, s61, v238
	v_add_u32_e32 v241, s61, v239
	s_setprio 1
	v_mfma_f32_16x16x32_bf16 v[2:5], v[210:213], v[178:181], v[2:5]
	v_mfma_f32_16x16x32_bf16 v[18:21], v[210:213], v[182:185], v[18:21]
	v_mfma_f32_16x16x32_bf16 v[22:25], v[214:217], v[182:185], v[22:25]
	v_mfma_f32_16x16x32_bf16 v[6:9], v[214:217], v[178:181], v[6:9]
	s_waitcnt vmcnt(6)
	s_barrier
	v_mfma_f32_16x16x32_bf16 v[10:13], v[218:221], v[178:181], v[10:13]
	s_add_i32 m0, s60, s62
	v_mfma_f32_16x16x32_bf16 v[26:29], v[218:221], v[182:185], v[26:29]
	global_load_lds_dwordx4 v226, s[54:55]
	v_mfma_f32_16x16x32_bf16 v[30:33], v[222:225], v[182:185], v[30:33]
	v_mfma_f32_16x16x32_bf16 v[14:17], v[222:225], v[178:181], v[14:17]
	v_mfma_f32_16x16x32_bf16 v[46:49], v[222:225], v[186:189], v[46:49]
	ds_read_b128 v[162:165], v241 offset:0
	v_mfma_f32_16x16x32_bf16 v[62:65], v[222:225], v[190:193], v[62:65]
	ds_read_b128 v[166:169], v241 offset:256
	v_mfma_f32_16x16x32_bf16 v[58:61], v[218:221], v[190:193], v[58:61]
	ds_read_b128 v[170:173], v241 offset:2048
	global_load_lds_dwordx4 v226, s[54:55] offset:1024
	v_mfma_f32_16x16x32_bf16 v[42:45], v[218:221], v[186:189], v[42:45]
	ds_read_b128 v[174:177], v241 offset:2304
	v_mfma_f32_16x16x32_bf16 v[38:41], v[214:217], v[186:189], v[38:41]
	ds_read_b128 v[130:133], v240 offset:0
	v_mfma_f32_16x16x32_bf16 v[54:57], v[214:217], v[190:193], v[54:57]
	ds_read_b128 v[134:137], v240 offset:1024
	v_mfma_f32_16x16x32_bf16 v[50:53], v[210:213], v[190:193], v[50:53]
	ds_read_b128 v[138:141], v240 offset:2048
	v_mfma_f32_16x16x32_bf16 v[34:37], v[210:213], v[186:189], v[34:37]
	ds_read_b128 v[142:145], v240 offset:3072
	global_load_lds_dwordx4 v226, s[54:55] offset:2048
	v_mfma_f32_16x16x32_bf16 v[66:69], v[210:213], v[194:197], v[66:69]
	ds_read_b128 v[146:149], v240 offset:4096
	v_mfma_f32_16x16x32_bf16 v[82:85], v[210:213], v[198:201], v[82:85]
	ds_read_b128 v[150:153], v240 offset:5120
	v_mfma_f32_16x16x32_bf16 v[86:89], v[214:217], v[198:201], v[86:89]
	ds_read_b128 v[154:157], v240 offset:6144
	v_mfma_f32_16x16x32_bf16 v[70:73], v[214:217], v[194:197], v[70:73]
	ds_read_b128 v[158:161], v240 offset:7168
	v_mfma_f32_16x16x32_bf16 v[74:77], v[218:221], v[194:197], v[74:77]
	global_load_lds_dwordx4 v226, s[54:55] offset:3072
	v_mfma_f32_16x16x32_bf16 v[90:93], v[218:221], v[198:201], v[90:93]
	v_mfma_f32_16x16x32_bf16 v[94:97], v[222:225], v[198:201], v[94:97]
	v_mfma_f32_16x16x32_bf16 v[78:81], v[222:225], v[194:197], v[78:81]
	v_mfma_f32_16x16x32_bf16 v[110:113], v[222:225], v[202:205], v[110:113]
	s_add_i32 m0, s60, s63
	v_mfma_f32_16x16x32_bf16 v[126:129], v[222:225], v[206:209], v[126:129]
	global_load_lds_dwordx4 v230, s[56:57]
	v_mfma_f32_16x16x32_bf16 v[122:125], v[218:221], v[206:209], v[122:125]
	v_mfma_f32_16x16x32_bf16 v[106:109], v[218:221], v[202:205], v[106:109]
	v_mfma_f32_16x16x32_bf16 v[102:105], v[214:217], v[202:205], v[102:105]
	v_mfma_f32_16x16x32_bf16 v[118:121], v[214:217], v[206:209], v[118:121]
	v_mfma_f32_16x16x32_bf16 v[114:117], v[210:213], v[206:209], v[114:117]
	global_load_lds_dwordx4 v231, s[56:57] offset:1024
	v_mfma_f32_16x16x32_bf16 v[98:101], v[210:213], v[202:205], v[98:101]
	s_setprio 0
	s_add_i32 s60, s60, 0x6000
	s_cmp_eq_u32 s60, 0x12000
	s_cselect_b32 s60, 0, s60
	s_add_u32 s54, s54, s72
	s_addc_u32 s55, s55, 0
	s_add_u32 s56, s56, s73
	s_addc_u32 s57, s57, 0
	s_add_i32 s61, s61, 0x6000
	s_cmp_eq_u32 s61, 0x12000
	s_cselect_b32 s61, 0, s61
	s_waitcnt lgkmcnt(0)
	v_add_u32_e32 v240, s61, v238
	v_add_u32_e32 v241, s61, v239
	s_setprio 1
	v_mfma_f32_16x16x32_bf16 v[2:5], v[162:165], v[130:133], v[2:5]
	v_mfma_f32_16x16x32_bf16 v[18:21], v[162:165], v[134:137], v[18:21]
	v_mfma_f32_16x16x32_bf16 v[22:25], v[166:169], v[134:137], v[22:25]
	v_mfma_f32_16x16x32_bf16 v[6:9], v[166:169], v[130:133], v[6:9]
	s_waitcnt vmcnt(6)
	s_barrier
	v_mfma_f32_16x16x32_bf16 v[10:13], v[170:173], v[130:133], v[10:13]
	s_add_i32 m0, s60, s62
	v_mfma_f32_16x16x32_bf16 v[26:29], v[170:173], v[134:137], v[26:29]
	global_load_lds_dwordx4 v226, s[54:55]
	v_mfma_f32_16x16x32_bf16 v[30:33], v[174:177], v[134:137], v[30:33]
	v_mfma_f32_16x16x32_bf16 v[14:17], v[174:177], v[130:133], v[14:17]
	v_mfma_f32_16x16x32_bf16 v[46:49], v[174:177], v[138:141], v[46:49]
	ds_read_b128 v[210:213], v241 offset:0
	v_mfma_f32_16x16x32_bf16 v[62:65], v[174:177], v[142:145], v[62:65]
	ds_read_b128 v[214:217], v241 offset:256
	v_mfma_f32_16x16x32_bf16 v[58:61], v[170:173], v[142:145], v[58:61]
	ds_read_b128 v[218:221], v241 offset:2048
	global_load_lds_dwordx4 v226, s[54:55] offset:1024
	v_mfma_f32_16x16x32_bf16 v[42:45], v[170:173], v[138:141], v[42:45]
	ds_read_b128 v[222:225], v241 offset:2304
	v_mfma_f32_16x16x32_bf16 v[38:41], v[166:169], v[138:141], v[38:41]
	ds_read_b128 v[178:181], v240 offset:0
	v_mfma_f32_16x16x32_bf16 v[54:57], v[166:169], v[142:145], v[54:57]
	ds_read_b128 v[182:185], v240 offset:1024
	v_mfma_f32_16x16x32_bf16 v[50:53], v[162:165], v[142:145], v[50:53]
	ds_read_b128 v[186:189], v240 offset:2048
	v_mfma_f32_16x16x32_bf16 v[34:37], v[162:165], v[138:141], v[34:37]
	ds_read_b128 v[190:193], v240 offset:3072
	global_load_lds_dwordx4 v226, s[54:55] offset:2048
	v_mfma_f32_16x16x32_bf16 v[66:69], v[162:165], v[146:149], v[66:69]
	ds_read_b128 v[194:197], v240 offset:4096
	v_mfma_f32_16x16x32_bf16 v[82:85], v[162:165], v[150:153], v[82:85]
	ds_read_b128 v[198:201], v240 offset:5120
	v_mfma_f32_16x16x32_bf16 v[86:89], v[166:169], v[150:153], v[86:89]
	ds_read_b128 v[202:205], v240 offset:6144
	v_mfma_f32_16x16x32_bf16 v[70:73], v[166:169], v[146:149], v[70:73]
	ds_read_b128 v[206:209], v240 offset:7168
	v_mfma_f32_16x16x32_bf16 v[74:77], v[170:173], v[146:149], v[74:77]
	global_load_lds_dwordx4 v226, s[54:55] offset:3072
	v_mfma_f32_16x16x32_bf16 v[90:93], v[170:173], v[150:153], v[90:93]
	v_mfma_f32_16x16x32_bf16 v[94:97], v[174:177], v[150:153], v[94:97]
	v_mfma_f32_16x16x32_bf16 v[78:81], v[174:177], v[146:149], v[78:81]
	v_mfma_f32_16x16x32_bf16 v[110:113], v[174:177], v[154:157], v[110:113]
	s_add_i32 m0, s60, s63
	v_mfma_f32_16x16x32_bf16 v[126:129], v[174:177], v[158:161], v[126:129]
	global_load_lds_dwordx4 v230, s[56:57]
	v_mfma_f32_16x16x32_bf16 v[122:125], v[170:173], v[158:161], v[122:125]
	v_mfma_f32_16x16x32_bf16 v[106:109], v[170:173], v[154:157], v[106:109]
	v_mfma_f32_16x16x32_bf16 v[102:105], v[166:169], v[154:157], v[102:105]
	v_mfma_f32_16x16x32_bf16 v[118:121], v[166:169], v[158:161], v[118:121]
	v_mfma_f32_16x16x32_bf16 v[114:117], v[162:165], v[158:161], v[114:117]
	global_load_lds_dwordx4 v231, s[56:57] offset:1024
	v_mfma_f32_16x16x32_bf16 v[98:101], v[162:165], v[154:157], v[98:101]
	s_setprio 0
	s_add_i32 s60, s60, 0x6000
	s_cmp_eq_u32 s60, 0x12000
	s_cselect_b32 s60, 0, s60
	s_add_u32 s54, s54, s72
	s_addc_u32 s55, s55, 0
	s_add_u32 s56, s56, s73
	s_addc_u32 s57, s57, 0
	s_add_i32 s61, s61, 0x6000
	s_cmp_eq_u32 s61, 0x12000
	s_cselect_b32 s61, 0, s61
	s_waitcnt lgkmcnt(0)
	v_add_u32_e32 v240, s61, v238
	v_add_u32_e32 v241, s61, v239
	s_setprio 1
	v_mfma_f32_16x16x32_bf16 v[2:5], v[210:213], v[178:181], v[2:5]
	v_mfma_f32_16x16x32_bf16 v[18:21], v[210:213], v[182:185], v[18:21]
	v_mfma_f32_16x16x32_bf16 v[22:25], v[214:217], v[182:185], v[22:25]
	v_mfma_f32_16x16x32_bf16 v[6:9], v[214:217], v[178:181], v[6:9]
	s_waitcnt vmcnt(6)
	s_barrier
	v_mfma_f32_16x16x32_bf16 v[10:13], v[218:221], v[178:181], v[10:13]
	s_add_i32 m0, s60, s62
	v_mfma_f32_16x16x32_bf16 v[26:29], v[218:221], v[182:185], v[26:29]
	global_load_lds_dwordx4 v226, s[54:55]
	v_mfma_f32_16x16x32_bf16 v[30:33], v[222:225], v[182:185], v[30:33]
	v_mfma_f32_16x16x32_bf16 v[14:17], v[222:225], v[178:181], v[14:17]
	v_mfma_f32_16x16x32_bf16 v[46:49], v[222:225], v[186:189], v[46:49]
	ds_read_b128 v[162:165], v241 offset:0
	v_mfma_f32_16x16x32_bf16 v[62:65], v[222:225], v[190:193], v[62:65]
	ds_read_b128 v[166:169], v241 offset:256
	v_mfma_f32_16x16x32_bf16 v[58:61], v[218:221], v[190:193], v[58:61]
	ds_read_b128 v[170:173], v241 offset:2048
	global_load_lds_dwordx4 v226, s[54:55] offset:1024
	v_mfma_f32_16x16x32_bf16 v[42:45], v[218:221], v[186:189], v[42:45]
	ds_read_b128 v[174:177], v241 offset:2304
	v_mfma_f32_16x16x32_bf16 v[38:41], v[214:217], v[186:189], v[38:41]
	ds_read_b128 v[130:133], v240 offset:0
	v_mfma_f32_16x16x32_bf16 v[54:57], v[214:217], v[190:193], v[54:57]
	ds_read_b128 v[134:137], v240 offset:1024
	v_mfma_f32_16x16x32_bf16 v[50:53], v[210:213], v[190:193], v[50:53]
	ds_read_b128 v[138:141], v240 offset:2048
	v_mfma_f32_16x16x32_bf16 v[34:37], v[210:213], v[186:189], v[34:37]
	ds_read_b128 v[142:145], v240 offset:3072
	global_load_lds_dwordx4 v226, s[54:55] offset:2048
	v_mfma_f32_16x16x32_bf16 v[66:69], v[210:213], v[194:197], v[66:69]
	ds_read_b128 v[146:149], v240 offset:4096
	v_mfma_f32_16x16x32_bf16 v[82:85], v[210:213], v[198:201], v[82:85]
	ds_read_b128 v[150:153], v240 offset:5120
	v_mfma_f32_16x16x32_bf16 v[86:89], v[214:217], v[198:201], v[86:89]
	ds_read_b128 v[154:157], v240 offset:6144
	v_mfma_f32_16x16x32_bf16 v[70:73], v[214:217], v[194:197], v[70:73]
	ds_read_b128 v[158:161], v240 offset:7168
	v_mfma_f32_16x16x32_bf16 v[74:77], v[218:221], v[194:197], v[74:77]
	global_load_lds_dwordx4 v226, s[54:55] offset:3072
	v_mfma_f32_16x16x32_bf16 v[90:93], v[218:221], v[198:201], v[90:93]
	v_mfma_f32_16x16x32_bf16 v[94:97], v[222:225], v[198:201], v[94:97]
	v_mfma_f32_16x16x32_bf16 v[78:81], v[222:225], v[194:197], v[78:81]
	v_mfma_f32_16x16x32_bf16 v[110:113], v[222:225], v[202:205], v[110:113]
	s_add_i32 m0, s60, s63
	v_mfma_f32_16x16x32_bf16 v[126:129], v[222:225], v[206:209], v[126:129]
	global_load_lds_dwordx4 v230, s[56:57]
	v_mfma_f32_16x16x32_bf16 v[122:125], v[218:221], v[206:209], v[122:125]
	v_mfma_f32_16x16x32_bf16 v[106:109], v[218:221], v[202:205], v[106:109]
	v_mfma_f32_16x16x32_bf16 v[102:105], v[214:217], v[202:205], v[102:105]
	v_mfma_f32_16x16x32_bf16 v[118:121], v[214:217], v[206:209], v[118:121]
	v_mfma_f32_16x16x32_bf16 v[114:117], v[210:213], v[206:209], v[114:117]
	global_load_lds_dwordx4 v231, s[56:57] offset:1024
	v_mfma_f32_16x16x32_bf16 v[98:101], v[210:213], v[202:205], v[98:101]
	s_setprio 0
	s_add_i32 s60, s60, 0x6000
	s_cmp_eq_u32 s60, 0x12000
	s_cselect_b32 s60, 0, s60
	s_add_u32 s54, s54, s72
	s_addc_u32 s55, s55, 0
	s_add_u32 s56, s56, s73
	s_addc_u32 s57, s57, 0
	s_add_i32 s61, s61, 0x6000
	s_cmp_eq_u32 s61, 0x12000
	s_cselect_b32 s61, 0, s61
	s_and_b32 s39, s35, 0xfff
	s_lshr_b32 s21, s36, 7
	s_waitcnt vmcnt(18)
	v_mbcnt_lo_u32_b32 v217, -1, 0
	v_mbcnt_hi_u32_b32 v217, -1, v217
	v_lshlrev_b32_e32 v217, 5, v217
	s_lshl_b32 s26, s43, 11
	v_add_u32_e32 v248, s26, v217
	s_add_i32 s26, s26, 0x12010
	v_add_u32_e32 v217, s26, v217
	s_cmp_eq_u32 s42, 0
	s_cbranch_scc0 .Lup_en_nowr
	ds_write_b128 v217, v[114:117]
	ds_write_b128 v217, v[118:121] offset:16
	s_branch .Lup_en_wrd

.Lup_tail_last:
	s_waitcnt lgkmcnt(0)
	v_add_u32_e32 v240, s61, v238
	v_add_u32_e32 v241, s61, v239
	s_setprio 1
	v_mfma_f32_16x16x32_bf16 v[2:5], v[162:165], v[130:133], v[2:5]
	v_mfma_f32_16x16x32_bf16 v[18:21], v[162:165], v[134:137], v[18:21]
	v_mfma_f32_16x16x32_bf16 v[22:25], v[166:169], v[134:137], v[22:25]
	v_mfma_f32_16x16x32_bf16 v[6:9], v[166:169], v[130:133], v[6:9]
	s_waitcnt vmcnt(6)
	s_barrier
	v_mfma_f32_16x16x32_bf16 v[10:13], v[170:173], v[130:133], v[10:13]
	s_add_i32 m0, s60, s62
	v_mfma_f32_16x16x32_bf16 v[26:29], v[170:173], v[134:137], v[26:29]
	global_load_lds_dwordx4 v226, s[54:55]
	v_mfma_f32_16x16x32_bf16 v[30:33], v[174:177], v[134:137], v[30:33]
	v_mfma_f32_16x16x32_bf16 v[14:17], v[174:177], v[130:133], v[14:17]
	v_mfma_f32_16x16x32_bf16 v[46:49], v[174:177], v[138:141], v[46:49]
	ds_read_b128 v[210:213], v241 offset:0
	v_mfma_f32_16x16x32_bf16 v[62:65], v[174:177], v[142:145], v[62:65]
	ds_read_b128 v[214:217], v241 offset:256
	v_mfma_f32_16x16x32_bf16 v[58:61], v[170:173], v[142:145], v[58:61]
	ds_read_b128 v[218:221], v241 offset:2048
	global_load_lds_dwordx4 v226, s[54:55] offset:1024
	v_mfma_f32_16x16x32_bf16 v[42:45], v[170:173], v[138:141], v[42:45]
	ds_read_b128 v[222:225], v241 offset:2304
	v_mfma_f32_16x16x32_bf16 v[38:41], v[166:169], v[138:141], v[38:41]
	ds_read_b128 v[178:181], v240 offset:0
	v_mfma_f32_16x16x32_bf16 v[54:57], v[166:169], v[142:145], v[54:57]
	ds_read_b128 v[182:185], v240 offset:1024
	v_mfma_f32_16x16x32_bf16 v[50:53], v[162:165], v[142:145], v[50:53]
	ds_read_b128 v[186:189], v240 offset:2048
	v_mfma_f32_16x16x32_bf16 v[34:37], v[162:165], v[138:141], v[34:37]
	ds_read_b128 v[190:193], v240 offset:3072
	global_load_lds_dwordx4 v226, s[54:55] offset:2048
	v_mfma_f32_16x16x32_bf16 v[66:69], v[162:165], v[146:149], v[66:69]
	ds_read_b128 v[194:197], v240 offset:4096
	v_mfma_f32_16x16x32_bf16 v[82:85], v[162:165], v[150:153], v[82:85]
	ds_read_b128 v[198:201], v240 offset:5120
	v_mfma_f32_16x16x32_bf16 v[86:89], v[166:169], v[150:153], v[86:89]
	ds_read_b128 v[202:205], v240 offset:6144
	v_mfma_f32_16x16x32_bf16 v[70:73], v[166:169], v[146:149], v[70:73]
	ds_read_b128 v[206:209], v240 offset:7168
	v_mfma_f32_16x16x32_bf16 v[74:77], v[170:173], v[146:149], v[74:77]
	global_load_lds_dwordx4 v226, s[54:55] offset:3072
	v_mfma_f32_16x16x32_bf16 v[90:93], v[170:173], v[150:153], v[90:93]
	v_mfma_f32_16x16x32_bf16 v[94:97], v[174:177], v[150:153], v[94:97]
	v_mfma_f32_16x16x32_bf16 v[78:81], v[174:177], v[146:149], v[78:81]
	v_mfma_f32_16x16x32_bf16 v[110:113], v[174:177], v[154:157], v[110:113]
	s_add_i32 m0, s60, s63
	v_mfma_f32_16x16x32_bf16 v[126:129], v[174:177], v[158:161], v[126:129]
	global_load_lds_dwordx4 v230, s[56:57]
	v_mfma_f32_16x16x32_bf16 v[122:125], v[170:173], v[158:161], v[122:125]
	v_mfma_f32_16x16x32_bf16 v[106:109], v[170:173], v[154:157], v[106:109]
	v_mfma_f32_16x16x32_bf16 v[102:105], v[166:169], v[154:157], v[102:105]
	v_mfma_f32_16x16x32_bf16 v[118:121], v[166:169], v[158:161], v[118:121]
	v_mfma_f32_16x16x32_bf16 v[114:117], v[162:165], v[158:161], v[114:117]
	global_load_lds_dwordx4 v231, s[56:57] offset:1024
	v_mfma_f32_16x16x32_bf16 v[98:101], v[162:165], v[154:157], v[98:101]
	s_setprio 0
	s_add_i32 s60, s60, 0x6000
	s_cmp_eq_u32 s60, 0x12000
	s_cselect_b32 s60, 0, s60
	s_add_u32 s54, s54, s72
	s_addc_u32 s55, s55, 0
	s_add_u32 s56, s56, s73
	s_addc_u32 s57, s57, 0
	s_add_i32 s61, s61, 0x6000
	s_cmp_eq_u32 s61, 0x12000
	s_cselect_b32 s61, 0, s61
	s_waitcnt lgkmcnt(0)
	v_add_u32_e32 v240, s61, v238
	v_add_u32_e32 v241, s61, v239
	s_setprio 1
	v_mfma_f32_16x16x32_bf16 v[2:5], v[210:213], v[178:181], v[2:5]
	v_mfma_f32_16x16x32_bf16 v[18:21], v[210:213], v[182:185], v[18:21]
	v_mfma_f32_16x16x32_bf16 v[22:25], v[214:217], v[182:185], v[22:25]
	v_mfma_f32_16x16x32_bf16 v[6:9], v[214:217], v[178:181], v[6:9]
	s_waitcnt vmcnt(6)
	s_barrier
	v_mfma_f32_16x16x32_bf16 v[10:13], v[218:221], v[178:181], v[10:13]
	v_mfma_f32_16x16x32_bf16 v[26:29], v[218:221], v[182:185], v[26:29]
	v_mfma_f32_16x16x32_bf16 v[30:33], v[222:225], v[182:185], v[30:33]
	v_mfma_f32_16x16x32_bf16 v[14:17], v[222:225], v[178:181], v[14:17]
	v_mfma_f32_16x16x32_bf16 v[46:49], v[222:225], v[186:189], v[46:49]
	ds_read_b128 v[162:165], v241 offset:0
	v_mfma_f32_16x16x32_bf16 v[62:65], v[222:225], v[190:193], v[62:65]
	ds_read_b128 v[166:169], v241 offset:256
	v_mfma_f32_16x16x32_bf16 v[58:61], v[218:221], v[190:193], v[58:61]
	ds_read_b128 v[170:173], v241 offset:2048
	v_mfma_f32_16x16x32_bf16 v[42:45], v[218:221], v[186:189], v[42:45]
	ds_read_b128 v[174:177], v241 offset:2304
	v_mfma_f32_16x16x32_bf16 v[38:41], v[214:217], v[186:189], v[38:41]
	ds_read_b128 v[130:133], v240 offset:0
	v_mfma_f32_16x16x32_bf16 v[54:57], v[214:217], v[190:193], v[54:57]
	ds_read_b128 v[134:137], v240 offset:1024
	v_mfma_f32_16x16x32_bf16 v[50:53], v[210:213], v[190:193], v[50:53]
	ds_read_b128 v[138:141], v240 offset:2048
	v_mfma_f32_16x16x32_bf16 v[34:37], v[210:213], v[186:189], v[34:37]
	ds_read_b128 v[142:145], v240 offset:3072
	v_mfma_f32_16x16x32_bf16 v[66:69], v[210:213], v[194:197], v[66:69]
	ds_read_b128 v[146:149], v240 offset:4096
	v_mfma_f32_16x16x32_bf16 v[82:85], v[210:213], v[198:201], v[82:85]
	ds_read_b128 v[150:153], v240 offset:5120
	v_mfma_f32_16x16x32_bf16 v[86:89], v[214:217], v[198:201], v[86:89]
	ds_read_b128 v[154:157], v240 offset:6144
	v_mfma_f32_16x16x32_bf16 v[70:73], v[214:217], v[194:197], v[70:73]
	ds_read_b128 v[158:161], v240 offset:7168
	v_mfma_f32_16x16x32_bf16 v[74:77], v[218:221], v[194:197], v[74:77]
	v_mfma_f32_16x16x32_bf16 v[90:93], v[218:221], v[198:201], v[90:93]
	v_mfma_f32_16x16x32_bf16 v[94:97], v[222:225], v[198:201], v[94:97]
	v_mfma_f32_16x16x32_bf16 v[78:81], v[222:225], v[194:197], v[78:81]
	v_mfma_f32_16x16x32_bf16 v[110:113], v[222:225], v[202:205], v[110:113]
	v_mfma_f32_16x16x32_bf16 v[126:129], v[222:225], v[206:209], v[126:129]
	v_mfma_f32_16x16x32_bf16 v[122:125], v[218:221], v[206:209], v[122:125]
	v_mfma_f32_16x16x32_bf16 v[106:109], v[218:221], v[202:205], v[106:109]
	v_mfma_f32_16x16x32_bf16 v[102:105], v[214:217], v[202:205], v[102:105]
	v_mfma_f32_16x16x32_bf16 v[118:121], v[214:217], v[206:209], v[118:121]
	v_mfma_f32_16x16x32_bf16 v[114:117], v[210:213], v[206:209], v[114:117]
	v_mfma_f32_16x16x32_bf16 v[98:101], v[210:213], v[202:205], v[98:101]
	s_setprio 0
	s_add_i32 s61, s61, 0x6000
	s_cmp_eq_u32 s61, 0x12000
	s_cselect_b32 s61, 0, s61
	s_waitcnt lgkmcnt(0)
	v_add_u32_e32 v240, s61, v238
	v_add_u32_e32 v241, s61, v239
	s_setprio 1
	v_mfma_f32_16x16x32_bf16 v[2:5], v[162:165], v[130:133], v[2:5]
	v_mfma_f32_16x16x32_bf16 v[18:21], v[162:165], v[134:137], v[18:21]
	v_mfma_f32_16x16x32_bf16 v[22:25], v[166:169], v[134:137], v[22:25]
	v_mfma_f32_16x16x32_bf16 v[6:9], v[166:169], v[130:133], v[6:9]
	s_waitcnt vmcnt(0)
	s_barrier
	v_mfma_f32_16x16x32_bf16 v[10:13], v[170:173], v[130:133], v[10:13]
	v_mfma_f32_16x16x32_bf16 v[26:29], v[170:173], v[134:137], v[26:29]
	v_mfma_f32_16x16x32_bf16 v[30:33], v[174:177], v[134:137], v[30:33]
	v_mfma_f32_16x16x32_bf16 v[14:17], v[174:177], v[130:133], v[14:17]
	v_mfma_f32_16x16x32_bf16 v[46:49], v[174:177], v[138:141], v[46:49]
	ds_read_b128 v[210:213], v241 offset:0
	v_mfma_f32_16x16x32_bf16 v[62:65], v[174:177], v[142:145], v[62:65]
	ds_read_b128 v[214:217], v241 offset:256
	v_mfma_f32_16x16x32_bf16 v[58:61], v[170:173], v[142:145], v[58:61]
	ds_read_b128 v[218:221], v241 offset:2048
	v_mfma_f32_16x16x32_bf16 v[42:45], v[170:173], v[138:141], v[42:45]
	ds_read_b128 v[222:225], v241 offset:2304
	v_mfma_f32_16x16x32_bf16 v[38:41], v[166:169], v[138:141], v[38:41]
	ds_read_b128 v[178:181], v240 offset:0
	v_mfma_f32_16x16x32_bf16 v[54:57], v[166:169], v[142:145], v[54:57]
	ds_read_b128 v[182:185], v240 offset:1024
	v_mfma_f32_16x16x32_bf16 v[50:53], v[162:165], v[142:145], v[50:53]
	ds_read_b128 v[186:189], v240 offset:2048
	v_mfma_f32_16x16x32_bf16 v[34:37], v[162:165], v[138:141], v[34:37]
	ds_read_b128 v[190:193], v240 offset:3072
	v_mfma_f32_16x16x32_bf16 v[66:69], v[162:165], v[146:149], v[66:69]
	ds_read_b128 v[194:197], v240 offset:4096
	v_mfma_f32_16x16x32_bf16 v[82:85], v[162:165], v[150:153], v[82:85]
	ds_read_b128 v[198:201], v240 offset:5120
	v_mfma_f32_16x16x32_bf16 v[86:89], v[166:169], v[150:153], v[86:89]
	ds_read_b128 v[202:205], v240 offset:6144
	v_mfma_f32_16x16x32_bf16 v[70:73], v[166:169], v[146:149], v[70:73]
	ds_read_b128 v[206:209], v240 offset:7168
	v_mfma_f32_16x16x32_bf16 v[74:77], v[170:173], v[146:149], v[74:77]
	v_mfma_f32_16x16x32_bf16 v[90:93], v[170:173], v[150:153], v[90:93]
	v_mfma_f32_16x16x32_bf16 v[94:97], v[174:177], v[150:153], v[94:97]
	v_mfma_f32_16x16x32_bf16 v[78:81], v[174:177], v[146:149], v[78:81]
	v_mfma_f32_16x16x32_bf16 v[110:113], v[174:177], v[154:157], v[110:113]
	v_mfma_f32_16x16x32_bf16 v[126:129], v[174:177], v[158:161], v[126:129]
	v_mfma_f32_16x16x32_bf16 v[122:125], v[170:173], v[158:161], v[122:125]
	v_mfma_f32_16x16x32_bf16 v[106:109], v[170:173], v[154:157], v[106:109]
	v_mfma_f32_16x16x32_bf16 v[102:105], v[166:169], v[154:157], v[102:105]
	v_mfma_f32_16x16x32_bf16 v[118:121], v[166:169], v[158:161], v[118:121]
	v_mfma_f32_16x16x32_bf16 v[114:117], v[162:165], v[158:161], v[114:117]
	v_mfma_f32_16x16x32_bf16 v[98:101], v[162:165], v[154:157], v[98:101]
	s_setprio 0
	s_add_i32 s61, s61, 0x6000
	s_cmp_eq_u32 s61, 0x12000
	s_cselect_b32 s61, 0, s61
	s_waitcnt lgkmcnt(0)
	s_setprio 1
	v_mfma_f32_16x16x32_bf16 v[2:5], v[210:213], v[178:181], v[2:5]
	v_mfma_f32_16x16x32_bf16 v[18:21], v[210:213], v[182:185], v[18:21]
	v_mfma_f32_16x16x32_bf16 v[22:25], v[214:217], v[182:185], v[22:25]
	v_mfma_f32_16x16x32_bf16 v[6:9], v[214:217], v[178:181], v[6:9]
	s_barrier
	v_mfma_f32_16x16x32_bf16 v[10:13], v[218:221], v[178:181], v[10:13]
	v_mfma_f32_16x16x32_bf16 v[26:29], v[218:221], v[182:185], v[26:29]
	v_mfma_f32_16x16x32_bf16 v[30:33], v[222:225], v[182:185], v[30:33]
	v_mfma_f32_16x16x32_bf16 v[14:17], v[222:225], v[178:181], v[14:17]
	v_mfma_f32_16x16x32_bf16 v[46:49], v[222:225], v[186:189], v[46:49]
	v_mfma_f32_16x16x32_bf16 v[62:65], v[222:225], v[190:193], v[62:65]
	v_mfma_f32_16x16x32_bf16 v[58:61], v[218:221], v[190:193], v[58:61]
	v_mfma_f32_16x16x32_bf16 v[42:45], v[218:221], v[186:189], v[42:45]
	v_mfma_f32_16x16x32_bf16 v[38:41], v[214:217], v[186:189], v[38:41]
	v_mfma_f32_16x16x32_bf16 v[54:57], v[214:217], v[190:193], v[54:57]
	v_mfma_f32_16x16x32_bf16 v[50:53], v[210:213], v[190:193], v[50:53]
	v_mfma_f32_16x16x32_bf16 v[34:37], v[210:213], v[186:189], v[34:37]
	v_mfma_f32_16x16x32_bf16 v[66:69], v[210:213], v[194:197], v[66:69]
	v_mfma_f32_16x16x32_bf16 v[82:85], v[210:213], v[198:201], v[82:85]
	v_mfma_f32_16x16x32_bf16 v[86:89], v[214:217], v[198:201], v[86:89]
	v_mfma_f32_16x16x32_bf16 v[70:73], v[214:217], v[194:197], v[70:73]
	v_mfma_f32_16x16x32_bf16 v[74:77], v[218:221], v[194:197], v[74:77]
	v_mfma_f32_16x16x32_bf16 v[90:93], v[218:221], v[198:201], v[90:93]
	v_mfma_f32_16x16x32_bf16 v[94:97], v[222:225], v[198:201], v[94:97]
	v_mfma_f32_16x16x32_bf16 v[78:81], v[222:225], v[194:197], v[78:81]
	v_mfma_f32_16x16x32_bf16 v[110:113], v[222:225], v[202:205], v[110:113]
	v_mfma_f32_16x16x32_bf16 v[126:129], v[222:225], v[206:209], v[126:129]
	v_mfma_f32_16x16x32_bf16 v[122:125], v[218:221], v[206:209], v[122:125]
	v_mfma_f32_16x16x32_bf16 v[106:109], v[218:221], v[202:205], v[106:109]
	v_mfma_f32_16x16x32_bf16 v[102:105], v[214:217], v[202:205], v[102:105]
	v_mfma_f32_16x16x32_bf16 v[118:121], v[214:217], v[206:209], v[118:121]
	v_mfma_f32_16x16x32_bf16 v[114:117], v[210:213], v[206:209], v[114:117]
	v_mfma_f32_16x16x32_bf16 v[98:101], v[210:213], v[202:205], v[98:101]
	s_setprio 0
	s_and_b32 s39, s35, 0xfff
	s_lshr_b32 s21, s36, 7
	s_waitcnt vmcnt(0)
	v_mbcnt_lo_u32_b32 v217, -1, 0
	v_mbcnt_hi_u32_b32 v217, -1, v217
	v_lshlrev_b32_e32 v217, 5, v217
	s_lshl_b32 s26, s43, 11
	v_add_u32_e32 v248, s26, v217
	s_add_i32 s26, s26, 0x12010
	v_add_u32_e32 v217, s26, v217
	s_cmp_eq_u32 s42, 0
	s_cbranch_scc0 .Lup_el_nowr
	ds_write_b128 v217, v[114:117]
	ds_write_b128 v217, v[118:121] offset:16
	s_branch .Lup_el_wrd

.Lpj_nn_a:
	s_waitcnt lgkmcnt(0)
	v_add_u32_e32 v240, s61, v238
	v_add_u32_e32 v241, s61, v239
	s_setprio 1
	v_mfma_f32_16x16x32_bf16 v[2:5], v[162:165], v[130:133], 0
	v_mfma_f32_16x16x32_bf16 v[18:21], v[162:165], v[134:137], 0
	v_mfma_f32_16x16x32_bf16 v[22:25], v[166:169], v[134:137], 0
	v_mfma_f32_16x16x32_bf16 v[6:9], v[166:169], v[130:133], 0
	s_waitcnt vmcnt(6)
	s_barrier
	v_mfma_f32_16x16x32_bf16 v[10:13], v[170:173], v[130:133], 0
	s_add_i32 m0, s60, s62
	v_mfma_f32_16x16x32_bf16 v[26:29], v[170:173], v[134:137], 0
	global_load_lds_dwordx4 v226, s[54:55]
	v_mfma_f32_16x16x32_bf16 v[30:33], v[174:177], v[134:137], 0
	v_mfma_f32_16x16x32_bf16 v[14:17], v[174:177], v[130:133], 0
	v_mfma_f32_16x16x32_bf16 v[46:49], v[174:177], v[138:141], 0
	ds_read_b128 v[210:213], v241 offset:0
	v_mfma_f32_16x16x32_bf16 v[62:65], v[174:177], v[142:145], 0
	ds_read_b128 v[214:217], v241 offset:256
	v_mfma_f32_16x16x32_bf16 v[58:61], v[170:173], v[142:145], 0
	ds_read_b128 v[218:221], v241 offset:2048
	global_load_lds_dwordx4 v226, s[54:55] offset:1024
	v_mfma_f32_16x16x32_bf16 v[42:45], v[170:173], v[138:141], 0
	ds_read_b128 v[222:225], v241 offset:2304
	v_mfma_f32_16x16x32_bf16 v[38:41], v[166:169], v[138:141], 0
	ds_read_b128 v[178:181], v240 offset:0
	v_mfma_f32_16x16x32_bf16 v[54:57], v[166:169], v[142:145], 0
	ds_read_b128 v[182:185], v240 offset:1024
	v_mfma_f32_16x16x32_bf16 v[50:53], v[162:165], v[142:145], 0
	ds_read_b128 v[186:189], v240 offset:2048
	v_mfma_f32_16x16x32_bf16 v[34:37], v[162:165], v[138:141], 0
	ds_read_b128 v[190:193], v240 offset:3072
	global_load_lds_dwordx4 v226, s[54:55] offset:2048
	v_mfma_f32_16x16x32_bf16 v[66:69], v[162:165], v[146:149], 0
	ds_read_b128 v[194:197], v240 offset:4096
	v_mfma_f32_16x16x32_bf16 v[82:85], v[162:165], v[150:153], 0
	ds_read_b128 v[198:201], v240 offset:5120
	v_mfma_f32_16x16x32_bf16 v[86:89], v[166:169], v[150:153], 0
	ds_read_b128 v[202:205], v240 offset:6144
	v_mfma_f32_16x16x32_bf16 v[70:73], v[166:169], v[146:149], 0
	ds_read_b128 v[206:209], v240 offset:7168
	v_mfma_f32_16x16x32_bf16 v[74:77], v[170:173], v[146:149], 0
	global_load_lds_dwordx4 v226, s[54:55] offset:3072
	v_mfma_f32_16x16x32_bf16 v[90:93], v[170:173], v[150:153], 0
	v_mfma_f32_16x16x32_bf16 v[94:97], v[174:177], v[150:153], 0
	v_mfma_f32_16x16x32_bf16 v[78:81], v[174:177], v[146:149], 0
	v_mfma_f32_16x16x32_bf16 v[110:113], v[174:177], v[154:157], 0
	s_add_i32 m0, s60, s63
	v_mfma_f32_16x16x32_bf16 v[126:129], v[174:177], v[158:161], 0
	global_load_lds_dwordx4 v230, s[56:57]
	v_mfma_f32_16x16x32_bf16 v[122:125], v[170:173], v[158:161], 0
	v_mfma_f32_16x16x32_bf16 v[106:109], v[170:173], v[154:157], 0
	v_mfma_f32_16x16x32_bf16 v[102:105], v[166:169], v[154:157], 0
	v_mfma_f32_16x16x32_bf16 v[118:121], v[166:169], v[158:161], 0
	v_mfma_f32_16x16x32_bf16 v[114:117], v[162:165], v[158:161], 0
	global_load_lds_dwordx4 v231, s[56:57] offset:1024
	v_mfma_f32_16x16x32_bf16 v[98:101], v[162:165], v[154:157], 0
	s_setprio 0
	s_add_i32 s60, s60, 0x6000
	s_cmp_eq_u32 s60, 0x12000
	s_cselect_b32 s60, 0, s60
	s_add_u32 s54, s54, s72
	s_addc_u32 s55, s55, 0
	s_add_u32 s56, s56, s73
	s_addc_u32 s57, s57, 0
	s_add_i32 s61, s61, 0x6000
	s_cmp_eq_u32 s61, 0x12000
	s_cselect_b32 s61, 0, s61
	s_waitcnt lgkmcnt(0)
	v_add_u32_e32 v240, s61, v238
	v_add_u32_e32 v241, s61, v239
	s_setprio 1
	v_mfma_f32_16x16x32_bf16 v[2:5], v[210:213], v[178:181], v[2:5]
	v_mfma_f32_16x16x32_bf16 v[18:21], v[210:213], v[182:185], v[18:21]
	v_mfma_f32_16x16x32_bf16 v[22:25], v[214:217], v[182:185], v[22:25]
	v_mfma_f32_16x16x32_bf16 v[6:9], v[214:217], v[178:181], v[6:9]
	s_waitcnt vmcnt(6)
	s_barrier
	v_mfma_f32_16x16x32_bf16 v[10:13], v[218:221], v[178:181], v[10:13]
	s_add_i32 m0, s60, s62
	v_mfma_f32_16x16x32_bf16 v[26:29], v[218:221], v[182:185], v[26:29]
	global_load_lds_dwordx4 v226, s[54:55]
	v_mfma_f32_16x16x32_bf16 v[30:33], v[222:225], v[182:185], v[30:33]
	v_mfma_f32_16x16x32_bf16 v[14:17], v[222:225], v[178:181], v[14:17]
	v_mfma_f32_16x16x32_bf16 v[46:49], v[222:225], v[186:189], v[46:49]
	ds_read_b128 v[162:165], v241 offset:0
	v_mfma_f32_16x16x32_bf16 v[62:65], v[222:225], v[190:193], v[62:65]
	ds_read_b128 v[166:169], v241 offset:256
	v_mfma_f32_16x16x32_bf16 v[58:61], v[218:221], v[190:193], v[58:61]
	ds_read_b128 v[170:173], v241 offset:2048
	global_load_lds_dwordx4 v226, s[54:55] offset:1024
	v_mfma_f32_16x16x32_bf16 v[42:45], v[218:221], v[186:189], v[42:45]
	ds_read_b128 v[174:177], v241 offset:2304
	v_mfma_f32_16x16x32_bf16 v[38:41], v[214:217], v[186:189], v[38:41]
	ds_read_b128 v[130:133], v240 offset:0
	v_mfma_f32_16x16x32_bf16 v[54:57], v[214:217], v[190:193], v[54:57]
	ds_read_b128 v[134:137], v240 offset:1024
	v_mfma_f32_16x16x32_bf16 v[50:53], v[210:213], v[190:193], v[50:53]
	ds_read_b128 v[138:141], v240 offset:2048
	v_mfma_f32_16x16x32_bf16 v[34:37], v[210:213], v[186:189], v[34:37]
	ds_read_b128 v[142:145], v240 offset:3072
	global_load_lds_dwordx4 v226, s[54:55] offset:2048
	v_mfma_f32_16x16x32_bf16 v[66:69], v[210:213], v[194:197], v[66:69]
	ds_read_b128 v[146:149], v240 offset:4096
	v_mfma_f32_16x16x32_bf16 v[82:85], v[210:213], v[198:201], v[82:85]
	ds_read_b128 v[150:153], v240 offset:5120
	v_mfma_f32_16x16x32_bf16 v[86:89], v[214:217], v[198:201], v[86:89]
	ds_read_b128 v[154:157], v240 offset:6144
	v_mfma_f32_16x16x32_bf16 v[70:73], v[214:217], v[194:197], v[70:73]
	ds_read_b128 v[158:161], v240 offset:7168
	v_mfma_f32_16x16x32_bf16 v[74:77], v[218:221], v[194:197], v[74:77]
	global_load_lds_dwordx4 v226, s[54:55] offset:3072
	v_mfma_f32_16x16x32_bf16 v[90:93], v[218:221], v[198:201], v[90:93]
	v_mfma_f32_16x16x32_bf16 v[94:97], v[222:225], v[198:201], v[94:97]
	v_mfma_f32_16x16x32_bf16 v[78:81], v[222:225], v[194:197], v[78:81]
	v_mfma_f32_16x16x32_bf16 v[110:113], v[222:225], v[202:205], v[110:113]
	s_add_i32 m0, s60, s63
	v_mfma_f32_16x16x32_bf16 v[126:129], v[222:225], v[206:209], v[126:129]
	global_load_lds_dwordx4 v230, s[56:57]
	v_mfma_f32_16x16x32_bf16 v[122:125], v[218:221], v[206:209], v[122:125]
	v_mfma_f32_16x16x32_bf16 v[106:109], v[218:221], v[202:205], v[106:109]
	v_mfma_f32_16x16x32_bf16 v[102:105], v[214:217], v[202:205], v[102:105]
	v_mfma_f32_16x16x32_bf16 v[118:121], v[214:217], v[206:209], v[118:121]
	v_mfma_f32_16x16x32_bf16 v[114:117], v[210:213], v[206:209], v[114:117]
	global_load_lds_dwordx4 v231, s[56:57] offset:1024
	v_mfma_f32_16x16x32_bf16 v[98:101], v[210:213], v[202:205], v[98:101]
	s_setprio 0
	s_add_i32 s60, s60, 0x6000
	s_cmp_eq_u32 s60, 0x12000
	s_cselect_b32 s60, 0, s60
	s_add_u32 s54, s54, s72
	s_addc_u32 s55, s55, 0
	s_add_u32 s56, s56, s73
	s_addc_u32 s57, s57, 0
	s_add_i32 s61, s61, 0x6000
	s_cmp_eq_u32 s61, 0x12000
	s_cselect_b32 s61, 0, s61
	s_branch .Lpj_main

.Lpj_nn_b:
	s_waitcnt lgkmcnt(0)
	v_add_u32_e32 v240, s61, v238
	v_add_u32_e32 v241, s61, v239
	s_setprio 1
	v_mfma_f32_16x16x32_bf16 v[2:5], v[162:165], v[130:133], 0
	v_mfma_f32_16x16x32_bf16 v[18:21], v[162:165], v[134:137], 0
	v_mfma_f32_16x16x32_bf16 v[22:25], v[166:169], v[134:137], 0
	v_mfma_f32_16x16x32_bf16 v[6:9], v[166:169], v[130:133], 0
	s_waitcnt vmcnt(63)
	s_barrier
	v_mfma_f32_16x16x32_bf16 v[10:13], v[170:173], v[130:133], 0
	s_add_i32 m0, s60, s62
	v_mfma_f32_16x16x32_bf16 v[26:29], v[170:173], v[134:137], 0
	global_load_lds_dwordx4 v226, s[54:55]
	v_mfma_f32_16x16x32_bf16 v[30:33], v[174:177], v[134:137], 0
	v_mfma_f32_16x16x32_bf16 v[14:17], v[174:177], v[130:133], 0
	v_mfma_f32_16x16x32_bf16 v[46:49], v[174:177], v[138:141], 0
	ds_read_b128 v[210:213], v241 offset:0
	v_mfma_f32_16x16x32_bf16 v[62:65], v[174:177], v[142:145], 0
	ds_read_b128 v[214:217], v241 offset:256
	v_mfma_f32_16x16x32_bf16 v[58:61], v[170:173], v[142:145], 0
	ds_read_b128 v[218:221], v241 offset:2048
	global_load_lds_dwordx4 v226, s[54:55] offset:1024
	v_mfma_f32_16x16x32_bf16 v[42:45], v[170:173], v[138:141], 0
	ds_read_b128 v[222:225], v241 offset:2304
	v_mfma_f32_16x16x32_bf16 v[38:41], v[166:169], v[138:141], 0
	ds_read_b128 v[178:181], v240 offset:0
	v_mfma_f32_16x16x32_bf16 v[54:57], v[166:169], v[142:145], 0
	ds_read_b128 v[182:185], v240 offset:1024
	v_mfma_f32_16x16x32_bf16 v[50:53], v[162:165], v[142:145], 0
	ds_read_b128 v[186:189], v240 offset:2048
	v_mfma_f32_16x16x32_bf16 v[34:37], v[162:165], v[138:141], 0
	ds_read_b128 v[190:193], v240 offset:3072
	global_load_lds_dwordx4 v226, s[54:55] offset:2048
	v_mfma_f32_16x16x32_bf16 v[66:69], v[162:165], v[146:149], 0
	ds_read_b128 v[194:197], v240 offset:4096
	v_mfma_f32_16x16x32_bf16 v[82:85], v[162:165], v[150:153], 0
	ds_read_b128 v[198:201], v240 offset:5120
	v_mfma_f32_16x16x32_bf16 v[86:89], v[166:169], v[150:153], 0
	ds_read_b128 v[202:205], v240 offset:6144
	v_mfma_f32_16x16x32_bf16 v[70:73], v[166:169], v[146:149], 0
	ds_read_b128 v[206:209], v240 offset:7168
	v_mfma_f32_16x16x32_bf16 v[74:77], v[170:173], v[146:149], 0
	global_load_lds_dwordx4 v226, s[54:55] offset:3072
	v_mfma_f32_16x16x32_bf16 v[90:93], v[170:173], v[150:153], 0
	v_mfma_f32_16x16x32_bf16 v[94:97], v[174:177], v[150:153], 0
	v_mfma_f32_16x16x32_bf16 v[78:81], v[174:177], v[146:149], 0
	v_mfma_f32_16x16x32_bf16 v[110:113], v[174:177], v[154:157], 0
	s_add_i32 m0, s60, s63
	v_mfma_f32_16x16x32_bf16 v[126:129], v[174:177], v[158:161], 0
	global_load_lds_dwordx4 v230, s[56:57]
	v_mfma_f32_16x16x32_bf16 v[122:125], v[170:173], v[158:161], 0
	v_mfma_f32_16x16x32_bf16 v[106:109], v[170:173], v[154:157], 0
	v_mfma_f32_16x16x32_bf16 v[102:105], v[166:169], v[154:157], 0
	v_mfma_f32_16x16x32_bf16 v[118:121], v[166:169], v[158:161], 0
	v_mfma_f32_16x16x32_bf16 v[114:117], v[162:165], v[158:161], 0
	global_load_lds_dwordx4 v231, s[56:57] offset:1024
	v_mfma_f32_16x16x32_bf16 v[98:101], v[162:165], v[154:157], 0
	s_setprio 0
	s_add_i32 s60, s60, 0x6000
	s_cmp_eq_u32 s60, 0x12000
	s_cselect_b32 s60, 0, s60
	s_add_u32 s54, s54, s72
	s_addc_u32 s55, s55, 0
	s_add_u32 s56, s56, s73
	s_addc_u32 s57, s57, 0
	s_add_i32 s61, s61, 0x6000
	s_cmp_eq_u32 s61, 0x12000
	s_cselect_b32 s61, 0, s61
	s_waitcnt lgkmcnt(0)
	v_add_u32_e32 v240, s61, v238
	v_add_u32_e32 v241, s61, v239
	s_setprio 1
	v_mfma_f32_16x16x32_bf16 v[2:5], v[210:213], v[178:181], v[2:5]
	v_mfma_f32_16x16x32_bf16 v[18:21], v[210:213], v[182:185], v[18:21]
	v_mfma_f32_16x16x32_bf16 v[22:25], v[214:217], v[182:185], v[22:25]
	v_mfma_f32_16x16x32_bf16 v[6:9], v[214:217], v[178:181], v[6:9]
	s_waitcnt vmcnt(63)
	s_barrier
	v_mfma_f32_16x16x32_bf16 v[10:13], v[218:221], v[178:181], v[10:13]
	s_add_i32 m0, s60, s62
	v_mfma_f32_16x16x32_bf16 v[26:29], v[218:221], v[182:185], v[26:29]
	global_load_lds_dwordx4 v226, s[54:55]
	v_mfma_f32_16x16x32_bf16 v[30:33], v[222:225], v[182:185], v[30:33]
	v_mfma_f32_16x16x32_bf16 v[14:17], v[222:225], v[178:181], v[14:17]
	v_mfma_f32_16x16x32_bf16 v[46:49], v[222:225], v[186:189], v[46:49]
	ds_read_b128 v[162:165], v241 offset:0
	v_mfma_f32_16x16x32_bf16 v[62:65], v[222:225], v[190:193], v[62:65]
	ds_read_b128 v[166:169], v241 offset:256
	v_mfma_f32_16x16x32_bf16 v[58:61], v[218:221], v[190:193], v[58:61]
	ds_read_b128 v[170:173], v241 offset:2048
	global_load_lds_dwordx4 v226, s[54:55] offset:1024
	v_mfma_f32_16x16x32_bf16 v[42:45], v[218:221], v[186:189], v[42:45]
	ds_read_b128 v[174:177], v241 offset:2304
	v_mfma_f32_16x16x32_bf16 v[38:41], v[214:217], v[186:189], v[38:41]
	ds_read_b128 v[130:133], v240 offset:0
	v_mfma_f32_16x16x32_bf16 v[54:57], v[214:217], v[190:193], v[54:57]
	ds_read_b128 v[134:137], v240 offset:1024
	v_mfma_f32_16x16x32_bf16 v[50:53], v[210:213], v[190:193], v[50:53]
	ds_read_b128 v[138:141], v240 offset:2048
	v_mfma_f32_16x16x32_bf16 v[34:37], v[210:213], v[186:189], v[34:37]
	ds_read_b128 v[142:145], v240 offset:3072
	global_load_lds_dwordx4 v226, s[54:55] offset:2048
	v_mfma_f32_16x16x32_bf16 v[66:69], v[210:213], v[194:197], v[66:69]
	ds_read_b128 v[146:149], v240 offset:4096
	v_mfma_f32_16x16x32_bf16 v[82:85], v[210:213], v[198:201], v[82:85]
	ds_read_b128 v[150:153], v240 offset:5120
	v_mfma_f32_16x16x32_bf16 v[86:89], v[214:217], v[198:201], v[86:89]
	ds_read_b128 v[154:157], v240 offset:6144
	v_mfma_f32_16x16x32_bf16 v[70:73], v[214:217], v[194:197], v[70:73]
	ds_read_b128 v[158:161], v240 offset:7168
	v_mfma_f32_16x16x32_bf16 v[74:77], v[218:221], v[194:197], v[74:77]
	global_load_lds_dwordx4 v226, s[54:55] offset:3072
	v_mfma_f32_16x16x32_bf16 v[90:93], v[218:221], v[198:201], v[90:93]
	v_mfma_f32_16x16x32_bf16 v[94:97], v[222:225], v[198:201], v[94:97]
	v_mfma_f32_16x16x32_bf16 v[78:81], v[222:225], v[194:197], v[78:81]
	v_mfma_f32_16x16x32_bf16 v[110:113], v[222:225], v[202:205], v[110:113]
	s_add_i32 m0, s60, s63
	v_mfma_f32_16x16x32_bf16 v[126:129], v[222:225], v[206:209], v[126:129]
	global_load_lds_dwordx4 v230, s[56:57]
	v_mfma_f32_16x16x32_bf16 v[122:125], v[218:221], v[206:209], v[122:125]
	v_mfma_f32_16x16x32_bf16 v[106:109], v[218:221], v[202:205], v[106:109]
	v_mfma_f32_16x16x32_bf16 v[102:105], v[214:217], v[202:205], v[102:105]
	v_mfma_f32_16x16x32_bf16 v[118:121], v[214:217], v[206:209], v[118:121]
	v_mfma_f32_16x16x32_bf16 v[114:117], v[210:213], v[206:209], v[114:117]
	global_load_lds_dwordx4 v231, s[56:57] offset:1024
	v_mfma_f32_16x16x32_bf16 v[98:101], v[210:213], v[202:205], v[98:101]
	s_setprio 0
	s_add_i32 s60, s60, 0x6000
	s_cmp_eq_u32 s60, 0x12000
	s_cselect_b32 s60, 0, s60
	s_add_u32 s54, s54, s72
	s_addc_u32 s55, s55, 0
	s_add_u32 s56, s56, s73
	s_addc_u32 s57, s57, 0
	s_add_i32 s61, s61, 0x6000
	s_cmp_eq_u32 s61, 0x12000
	s_cselect_b32 s61, 0, s61

.Lpj_kdone:
	s_cmp_eq_u32 s37, 0
	s_cbranch_scc1 .Lpj_tail_last
	s_waitcnt lgkmcnt(0)
	v_add_u32_e32 v240, s61, v238
	v_add_u32_e32 v241, s61, v239
	s_setprio 1
	v_mfma_f32_16x16x32_bf16 v[2:5], v[162:165], v[130:133], v[2:5]
	v_mfma_f32_16x16x32_bf16 v[18:21], v[162:165], v[134:137], v[18:21]
	v_mfma_f32_16x16x32_bf16 v[22:25], v[166:169], v[134:137], v[22:25]
	v_mfma_f32_16x16x32_bf16 v[6:9], v[166:169], v[130:133], v[6:9]
	s_waitcnt vmcnt(6)
	s_barrier
	v_mfma_f32_16x16x32_bf16 v[10:13], v[170:173], v[130:133], v[10:13]
	s_add_i32 m0, s60, s62
	v_mfma_f32_16x16x32_bf16 v[26:29], v[170:173], v[134:137], v[26:29]
	global_load_lds_dwordx4 v226, s[54:55]
	v_mfma_f32_16x16x32_bf16 v[30:33], v[174:177], v[134:137], v[30:33]
	v_mfma_f32_16x16x32_bf16 v[14:17], v[174:177], v[130:133], v[14:17]
	v_mfma_f32_16x16x32_bf16 v[46:49], v[174:177], v[138:141], v[46:49]
	ds_read_b128 v[210:213], v241 offset:0
	v_mfma_f32_16x16x32_bf16 v[62:65], v[174:177], v[142:145], v[62:65]
	ds_read_b128 v[214:217], v241 offset:256
	v_mfma_f32_16x16x32_bf16 v[58:61], v[170:173], v[142:145], v[58:61]
	ds_read_b128 v[218:221], v241 offset:2048
	global_load_lds_dwordx4 v226, s[54:55] offset:1024
	v_mfma_f32_16x16x32_bf16 v[42:45], v[170:173], v[138:141], v[42:45]
	ds_read_b128 v[222:225], v241 offset:2304
	v_mfma_f32_16x16x32_bf16 v[38:41], v[166:169], v[138:141], v[38:41]
	ds_read_b128 v[178:181], v240 offset:0
	v_mfma_f32_16x16x32_bf16 v[54:57], v[166:169], v[142:145], v[54:57]
	ds_read_b128 v[182:185], v240 offset:1024
	v_mfma_f32_16x16x32_bf16 v[50:53], v[162:165], v[142:145], v[50:53]
	ds_read_b128 v[186:189], v240 offset:2048
	v_mfma_f32_16x16x32_bf16 v[34:37], v[162:165], v[138:141], v[34:37]
	ds_read_b128 v[190:193], v240 offset:3072
	global_load_lds_dwordx4 v226, s[54:55] offset:2048
	v_mfma_f32_16x16x32_bf16 v[66:69], v[162:165], v[146:149], v[66:69]
	ds_read_b128 v[194:197], v240 offset:4096
	v_mfma_f32_16x16x32_bf16 v[82:85], v[162:165], v[150:153], v[82:85]
	ds_read_b128 v[198:201], v240 offset:5120
	v_mfma_f32_16x16x32_bf16 v[86:89], v[166:169], v[150:153], v[86:89]
	ds_read_b128 v[202:205], v240 offset:6144
	v_mfma_f32_16x16x32_bf16 v[70:73], v[166:169], v[146:149], v[70:73]
	ds_read_b128 v[206:209], v240 offset:7168
	v_mfma_f32_16x16x32_bf16 v[74:77], v[170:173], v[146:149], v[74:77]
	global_load_lds_dwordx4 v226, s[54:55] offset:3072
	v_mfma_f32_16x16x32_bf16 v[90:93], v[170:173], v[150:153], v[90:93]
	v_mfma_f32_16x16x32_bf16 v[94:97], v[174:177], v[150:153], v[94:97]
	v_mfma_f32_16x16x32_bf16 v[78:81], v[174:177], v[146:149], v[78:81]
	v_mfma_f32_16x16x32_bf16 v[110:113], v[174:177], v[154:157], v[110:113]
	s_add_i32 m0, s60, s63
	v_mfma_f32_16x16x32_bf16 v[126:129], v[174:177], v[158:161], v[126:129]
	global_load_lds_dwordx4 v230, s[56:57]
	v_mfma_f32_16x16x32_bf16 v[122:125], v[170:173], v[158:161], v[122:125]
	v_mfma_f32_16x16x32_bf16 v[106:109], v[170:173], v[154:157], v[106:109]
	v_mfma_f32_16x16x32_bf16 v[102:105], v[166:169], v[154:157], v[102:105]
	v_mfma_f32_16x16x32_bf16 v[118:121], v[166:169], v[158:161], v[118:121]
	v_mfma_f32_16x16x32_bf16 v[114:117], v[162:165], v[158:161], v[114:117]
	global_load_lds_dwordx4 v231, s[56:57] offset:1024
	v_mfma_f32_16x16x32_bf16 v[98:101], v[162:165], v[154:157], v[98:101]
	s_setprio 0
	s_add_i32 s60, s60, 0x6000
	s_cmp_eq_u32 s60, 0x12000
	s_cselect_b32 s60, 0, s60
	s_add_u32 s54, s54, s72
	s_addc_u32 s55, s55, 0
	s_add_u32 s56, s56, s73
	s_addc_u32 s57, s57, 0
	s_add_i32 s61, s61, 0x6000
	s_cmp_eq_u32 s61, 0x12000
	s_cselect_b32 s61, 0, s61
	v_mov_b32_e32 v226, v232
	v_mov_b32_e32 v230, v236
	v_mov_b32_e32 v231, v237
	s_mov_b64 s[54:55], s[48:49]
	s_mov_b64 s[56:57], s[50:51]
	s_waitcnt lgkmcnt(0)
	v_add_u32_e32 v240, s61, v238
	v_add_u32_e32 v241, s61, v239
	s_setprio 1
	v_mfma_f32_16x16x32_bf16 v[2:5], v[210:213], v[178:181], v[2:5]
	v_mfma_f32_16x16x32_bf16 v[18:21], v[210:213], v[182:185], v[18:21]
	v_mfma_f32_16x16x32_bf16 v[22:25], v[214:217], v[182:185], v[22:25]
	v_mfma_f32_16x16x32_bf16 v[6:9], v[214:217], v[178:181], v[6:9]
	s_waitcnt vmcnt(6)
	s_barrier
	v_mfma_f32_16x16x32_bf16 v[10:13], v[218:221], v[178:181], v[10:13]
	s_add_i32 m0, s60, s62
	v_mfma_f32_16x16x32_bf16 v[26:29], v[218:221], v[182:185], v[26:29]
	global_load_lds_dwordx4 v226, s[54:55]
	v_mfma_f32_16x16x32_bf16 v[30:33], v[222:225], v[182:185], v[30:33]
	v_mfma_f32_16x16x32_bf16 v[14:17], v[222:225], v[178:181], v[14:17]
	v_mfma_f32_16x16x32_bf16 v[46:49], v[222:225], v[186:189], v[46:49]
	ds_read_b128 v[162:165], v241 offset:0
	v_mfma_f32_16x16x32_bf16 v[62:65], v[222:225], v[190:193], v[62:65]
	ds_read_b128 v[166:169], v241 offset:256
	v_mfma_f32_16x16x32_bf16 v[58:61], v[218:221], v[190:193], v[58:61]
	ds_read_b128 v[170:173], v241 offset:2048
	global_load_lds_dwordx4 v226, s[54:55] offset:1024
	v_mfma_f32_16x16x32_bf16 v[42:45], v[218:221], v[186:189], v[42:45]
	ds_read_b128 v[174:177], v241 offset:2304
	v_mfma_f32_16x16x32_bf16 v[38:41], v[214:217], v[186:189], v[38:41]
	ds_read_b128 v[130:133], v240 offset:0
	v_mfma_f32_16x16x32_bf16 v[54:57], v[214:217], v[190:193], v[54:57]
	ds_read_b128 v[134:137], v240 offset:1024
	v_mfma_f32_16x16x32_bf16 v[50:53], v[210:213], v[190:193], v[50:53]
	ds_read_b128 v[138:141], v240 offset:2048
	v_mfma_f32_16x16x32_bf16 v[34:37], v[210:213], v[186:189], v[34:37]
	ds_read_b128 v[142:145], v240 offset:3072
	global_load_lds_dwordx4 v226, s[54:55] offset:2048
	v_mfma_f32_16x16x32_bf16 v[66:69], v[210:213], v[194:197], v[66:69]
	ds_read_b128 v[146:149], v240 offset:4096
	v_mfma_f32_16x16x32_bf16 v[82:85], v[210:213], v[198:201], v[82:85]
	ds_read_b128 v[150:153], v240 offset:5120
	v_mfma_f32_16x16x32_bf16 v[86:89], v[214:217], v[198:201], v[86:89]
	ds_read_b128 v[154:157], v240 offset:6144
	v_mfma_f32_16x16x32_bf16 v[70:73], v[214:217], v[194:197], v[70:73]
	ds_read_b128 v[158:161], v240 offset:7168
	v_mfma_f32_16x16x32_bf16 v[74:77], v[218:221], v[194:197], v[74:77]
	global_load_lds_dwordx4 v226, s[54:55] offset:3072
	v_mfma_f32_16x16x32_bf16 v[90:93], v[218:221], v[198:201], v[90:93]
	v_mfma_f32_16x16x32_bf16 v[94:97], v[222:225], v[198:201], v[94:97]
	v_mfma_f32_16x16x32_bf16 v[78:81], v[222:225], v[194:197], v[78:81]
	v_mfma_f32_16x16x32_bf16 v[110:113], v[222:225], v[202:205], v[110:113]
	s_add_i32 m0, s60, s63
	v_mfma_f32_16x16x32_bf16 v[126:129], v[222:225], v[206:209], v[126:129]
	global_load_lds_dwordx4 v230, s[56:57]
	v_mfma_f32_16x16x32_bf16 v[122:125], v[218:221], v[206:209], v[122:125]
	v_mfma_f32_16x16x32_bf16 v[106:109], v[218:221], v[202:205], v[106:109]
	v_mfma_f32_16x16x32_bf16 v[102:105], v[214:217], v[202:205], v[102:105]
	v_mfma_f32_16x16x32_bf16 v[118:121], v[214:217], v[206:209], v[118:121]
	v_mfma_f32_16x16x32_bf16 v[114:117], v[210:213], v[206:209], v[114:117]
	global_load_lds_dwordx4 v231, s[56:57] offset:1024
	v_mfma_f32_16x16x32_bf16 v[98:101], v[210:213], v[202:205], v[98:101]
	s_setprio 0
	s_add_i32 s60, s60, 0x6000
	s_cmp_eq_u32 s60, 0x12000
	s_cselect_b32 s60, 0, s60
	s_add_u32 s54, s54, s72
	s_addc_u32 s55, s55, 0
	s_add_u32 s56, s56, s73
	s_addc_u32 s57, s57, 0
	s_add_i32 s61, s61, 0x6000
	s_cmp_eq_u32 s61, 0x12000
	s_cselect_b32 s61, 0, s61
	s_waitcnt lgkmcnt(0)
	v_add_u32_e32 v240, s61, v238
	v_add_u32_e32 v241, s61, v239
	s_setprio 1
	v_mfma_f32_16x16x32_bf16 v[2:5], v[162:165], v[130:133], v[2:5]
	v_mfma_f32_16x16x32_bf16 v[18:21], v[162:165], v[134:137], v[18:21]
	v_mfma_f32_16x16x32_bf16 v[22:25], v[166:169], v[134:137], v[22:25]
	v_mfma_f32_16x16x32_bf16 v[6:9], v[166:169], v[130:133], v[6:9]
	s_waitcnt vmcnt(6)
	s_barrier
	v_mfma_f32_16x16x32_bf16 v[10:13], v[170:173], v[130:133], v[10:13]
	s_add_i32 m0, s60, s62
	v_mfma_f32_16x16x32_bf16 v[26:29], v[170:173], v[134:137], v[26:29]
	global_load_lds_dwordx4 v226, s[54:55]
	v_mfma_f32_16x16x32_bf16 v[30:33], v[174:177], v[134:137], v[30:33]
	v_mfma_f32_16x16x32_bf16 v[14:17], v[174:177], v[130:133], v[14:17]
	v_mfma_f32_16x16x32_bf16 v[46:49], v[174:177], v[138:141], v[46:49]
	ds_read_b128 v[210:213], v241 offset:0
	v_mfma_f32_16x16x32_bf16 v[62:65], v[174:177], v[142:145], v[62:65]
	ds_read_b128 v[214:217], v241 offset:256
	v_mfma_f32_16x16x32_bf16 v[58:61], v[170:173], v[142:145], v[58:61]
	ds_read_b128 v[218:221], v241 offset:2048
	global_load_lds_dwordx4 v226, s[54:55] offset:1024
	v_mfma_f32_16x16x32_bf16 v[42:45], v[170:173], v[138:141], v[42:45]
	ds_read_b128 v[222:225], v241 offset:2304
	v_mfma_f32_16x16x32_bf16 v[38:41], v[166:169], v[138:141], v[38:41]
	ds_read_b128 v[178:181], v240 offset:0
	v_mfma_f32_16x16x32_bf16 v[54:57], v[166:169], v[142:145], v[54:57]
	ds_read_b128 v[182:185], v240 offset:1024
	v_mfma_f32_16x16x32_bf16 v[50:53], v[162:165], v[142:145], v[50:53]
	ds_read_b128 v[186:189], v240 offset:2048
	v_mfma_f32_16x16x32_bf16 v[34:37], v[162:165], v[138:141], v[34:37]
	ds_read_b128 v[190:193], v240 offset:3072
	global_load_lds_dwordx4 v226, s[54:55] offset:2048
	v_mfma_f32_16x16x32_bf16 v[66:69], v[162:165], v[146:149], v[66:69]
	ds_read_b128 v[194:197], v240 offset:4096
	v_mfma_f32_16x16x32_bf16 v[82:85], v[162:165], v[150:153], v[82:85]
	ds_read_b128 v[198:201], v240 offset:5120
	v_mfma_f32_16x16x32_bf16 v[86:89], v[166:169], v[150:153], v[86:89]
	ds_read_b128 v[202:205], v240 offset:6144
	v_mfma_f32_16x16x32_bf16 v[70:73], v[166:169], v[146:149], v[70:73]
	ds_read_b128 v[206:209], v240 offset:7168
	v_mfma_f32_16x16x32_bf16 v[74:77], v[170:173], v[146:149], v[74:77]
	global_load_lds_dwordx4 v226, s[54:55] offset:3072
	v_mfma_f32_16x16x32_bf16 v[90:93], v[170:173], v[150:153], v[90:93]
	v_mfma_f32_16x16x32_bf16 v[94:97], v[174:177], v[150:153], v[94:97]
	v_mfma_f32_16x16x32_bf16 v[78:81], v[174:177], v[146:149], v[78:81]
	v_mfma_f32_16x16x32_bf16 v[110:113], v[174:177], v[154:157], v[110:113]
	s_add_i32 m0, s60, s63
	v_mfma_f32_16x16x32_bf16 v[126:129], v[174:177], v[158:161], v[126:129]
	global_load_lds_dwordx4 v230, s[56:57]
	v_mfma_f32_16x16x32_bf16 v[122:125], v[170:173], v[158:161], v[122:125]
	v_mfma_f32_16x16x32_bf16 v[106:109], v[170:173], v[154:157], v[106:109]
	v_mfma_f32_16x16x32_bf16 v[102:105], v[166:169], v[154:157], v[102:105]
	v_mfma_f32_16x16x32_bf16 v[118:121], v[166:169], v[158:161], v[118:121]
	v_mfma_f32_16x16x32_bf16 v[114:117], v[162:165], v[158:161], v[114:117]
	global_load_lds_dwordx4 v231, s[56:57] offset:1024
	v_mfma_f32_16x16x32_bf16 v[98:101], v[162:165], v[154:157], v[98:101]
	s_setprio 0
	s_add_i32 s60, s60, 0x6000
	s_cmp_eq_u32 s60, 0x12000
	s_cselect_b32 s60, 0, s60
	s_add_u32 s54, s54, s72
	s_addc_u32 s55, s55, 0
	s_add_u32 s56, s56, s73
	s_addc_u32 s57, s57, 0
	s_add_i32 s61, s61, 0x6000
	s_cmp_eq_u32 s61, 0x12000
	s_cselect_b32 s61, 0, s61
	s_waitcnt lgkmcnt(0)
	v_add_u32_e32 v240, s61, v238
	v_add_u32_e32 v241, s61, v239
	s_setprio 1
	v_mfma_f32_16x16x32_bf16 v[2:5], v[210:213], v[178:181], v[2:5]
	v_mfma_f32_16x16x32_bf16 v[18:21], v[210:213], v[182:185], v[18:21]
	v_mfma_f32_16x16x32_bf16 v[22:25], v[214:217], v[182:185], v[22:25]
	v_mfma_f32_16x16x32_bf16 v[6:9], v[214:217], v[178:181], v[6:9]
	s_waitcnt vmcnt(6)
	s_barrier
	v_mfma_f32_16x16x32_bf16 v[10:13], v[218:221], v[178:181], v[10:13]
	s_add_i32 m0, s60, s62
	v_mfma_f32_16x16x32_bf16 v[26:29], v[218:221], v[182:185], v[26:29]
	global_load_lds_dwordx4 v226, s[54:55]
	v_mfma_f32_16x16x32_bf16 v[30:33], v[222:225], v[182:185], v[30:33]
	v_mfma_f32_16x16x32_bf16 v[14:17], v[222:225], v[178:181], v[14:17]
	v_mfma_f32_16x16x32_bf16 v[46:49], v[222:225], v[186:189], v[46:49]
	ds_read_b128 v[162:165], v241 offset:0
	v_mfma_f32_16x16x32_bf16 v[62:65], v[222:225], v[190:193], v[62:65]
	ds_read_b128 v[166:169], v241 offset:256
	v_mfma_f32_16x16x32_bf16 v[58:61], v[218:221], v[190:193], v[58:61]
	ds_read_b128 v[170:173], v241 offset:2048
	global_load_lds_dwordx4 v226, s[54:55] offset:1024
	v_mfma_f32_16x16x32_bf16 v[42:45], v[218:221], v[186:189], v[42:45]
	ds_read_b128 v[174:177], v241 offset:2304
	v_mfma_f32_16x16x32_bf16 v[38:41], v[214:217], v[186:189], v[38:41]
	ds_read_b128 v[130:133], v240 offset:0
	v_mfma_f32_16x16x32_bf16 v[54:57], v[214:217], v[190:193], v[54:57]
	ds_read_b128 v[134:137], v240 offset:1024
	v_mfma_f32_16x16x32_bf16 v[50:53], v[210:213], v[190:193], v[50:53]
	ds_read_b128 v[138:141], v240 offset:2048
	v_mfma_f32_16x16x32_bf16 v[34:37], v[210:213], v[186:189], v[34:37]
	ds_read_b128 v[142:145], v240 offset:3072
	global_load_lds_dwordx4 v226, s[54:55] offset:2048
	v_mfma_f32_16x16x32_bf16 v[66:69], v[210:213], v[194:197], v[66:69]
	ds_read_b128 v[146:149], v240 offset:4096
	v_mfma_f32_16x16x32_bf16 v[82:85], v[210:213], v[198:201], v[82:85]
	ds_read_b128 v[150:153], v240 offset:5120
	v_mfma_f32_16x16x32_bf16 v[86:89], v[214:217], v[198:201], v[86:89]
	ds_read_b128 v[154:157], v240 offset:6144
	v_mfma_f32_16x16x32_bf16 v[70:73], v[214:217], v[194:197], v[70:73]
	ds_read_b128 v[158:161], v240 offset:7168
	v_mfma_f32_16x16x32_bf16 v[74:77], v[218:221], v[194:197], v[74:77]
	global_load_lds_dwordx4 v226, s[54:55] offset:3072
	v_mfma_f32_16x16x32_bf16 v[90:93], v[218:221], v[198:201], v[90:93]
	v_mfma_f32_16x16x32_bf16 v[94:97], v[222:225], v[198:201], v[94:97]
	v_mfma_f32_16x16x32_bf16 v[78:81], v[222:225], v[194:197], v[78:81]
	v_mfma_f32_16x16x32_bf16 v[110:113], v[222:225], v[202:205], v[110:113]
	s_add_i32 m0, s60, s63
	v_mfma_f32_16x16x32_bf16 v[126:129], v[222:225], v[206:209], v[126:129]
	global_load_lds_dwordx4 v230, s[56:57]
	v_mfma_f32_16x16x32_bf16 v[122:125], v[218:221], v[206:209], v[122:125]
	v_mfma_f32_16x16x32_bf16 v[106:109], v[218:221], v[202:205], v[106:109]
	v_mfma_f32_16x16x32_bf16 v[102:105], v[214:217], v[202:205], v[102:105]
	v_mfma_f32_16x16x32_bf16 v[118:121], v[214:217], v[206:209], v[118:121]
	v_mfma_f32_16x16x32_bf16 v[114:117], v[210:213], v[206:209], v[114:117]
	global_load_lds_dwordx4 v231, s[56:57] offset:1024
	v_mfma_f32_16x16x32_bf16 v[98:101], v[210:213], v[202:205], v[98:101]
	s_setprio 0
	s_add_i32 s60, s60, 0x6000
	s_cmp_eq_u32 s60, 0x12000
	s_cselect_b32 s60, 0, s60
	s_add_u32 s54, s54, s72
	s_addc_u32 s55, s55, 0
	s_add_u32 s56, s56, s73
	s_addc_u32 s57, s57, 0
	s_add_i32 s61, s61, 0x6000
	s_cmp_eq_u32 s61, 0x12000
	s_cselect_b32 s61, 0, s61
	s_branch .Lpj_epi

.Lpj_tail_last:
	s_waitcnt lgkmcnt(0)
	v_add_u32_e32 v240, s61, v238
	v_add_u32_e32 v241, s61, v239
	s_setprio 1
	v_mfma_f32_16x16x32_bf16 v[2:5], v[162:165], v[130:133], v[2:5]
	v_mfma_f32_16x16x32_bf16 v[18:21], v[162:165], v[134:137], v[18:21]
	v_mfma_f32_16x16x32_bf16 v[22:25], v[166:169], v[134:137], v[22:25]
	v_mfma_f32_16x16x32_bf16 v[6:9], v[166:169], v[130:133], v[6:9]
	s_waitcnt vmcnt(6)
	s_barrier
	v_mfma_f32_16x16x32_bf16 v[10:13], v[170:173], v[130:133], v[10:13]
	s_add_i32 m0, s60, s62
	v_mfma_f32_16x16x32_bf16 v[26:29], v[170:173], v[134:137], v[26:29]
	global_load_lds_dwordx4 v226, s[54:55]
	v_mfma_f32_16x16x32_bf16 v[30:33], v[174:177], v[134:137], v[30:33]
	v_mfma_f32_16x16x32_bf16 v[14:17], v[174:177], v[130:133], v[14:17]
	v_mfma_f32_16x16x32_bf16 v[46:49], v[174:177], v[138:141], v[46:49]
	ds_read_b128 v[210:213], v241 offset:0
	v_mfma_f32_16x16x32_bf16 v[62:65], v[174:177], v[142:145], v[62:65]
	ds_read_b128 v[214:217], v241 offset:256
	v_mfma_f32_16x16x32_bf16 v[58:61], v[170:173], v[142:145], v[58:61]
	ds_read_b128 v[218:221], v241 offset:2048
	global_load_lds_dwordx4 v226, s[54:55] offset:1024
	v_mfma_f32_16x16x32_bf16 v[42:45], v[170:173], v[138:141], v[42:45]
	ds_read_b128 v[222:225], v241 offset:2304
	v_mfma_f32_16x16x32_bf16 v[38:41], v[166:169], v[138:141], v[38:41]
	ds_read_b128 v[178:181], v240 offset:0
	v_mfma_f32_16x16x32_bf16 v[54:57], v[166:169], v[142:145], v[54:57]
	ds_read_b128 v[182:185], v240 offset:1024
	v_mfma_f32_16x16x32_bf16 v[50:53], v[162:165], v[142:145], v[50:53]
	ds_read_b128 v[186:189], v240 offset:2048
	v_mfma_f32_16x16x32_bf16 v[34:37], v[162:165], v[138:141], v[34:37]
	ds_read_b128 v[190:193], v240 offset:3072
	global_load_lds_dwordx4 v226, s[54:55] offset:2048
	v_mfma_f32_16x16x32_bf16 v[66:69], v[162:165], v[146:149], v[66:69]
	ds_read_b128 v[194:197], v240 offset:4096
	v_mfma_f32_16x16x32_bf16 v[82:85], v[162:165], v[150:153], v[82:85]
	ds_read_b128 v[198:201], v240 offset:5120
	v_mfma_f32_16x16x32_bf16 v[86:89], v[166:169], v[150:153], v[86:89]
	ds_read_b128 v[202:205], v240 offset:6144
	v_mfma_f32_16x16x32_bf16 v[70:73], v[166:169], v[146:149], v[70:73]
	ds_read_b128 v[206:209], v240 offset:7168
	v_mfma_f32_16x16x32_bf16 v[74:77], v[170:173], v[146:149], v[74:77]
	global_load_lds_dwordx4 v226, s[54:55] offset:3072
	v_mfma_f32_16x16x32_bf16 v[90:93], v[170:173], v[150:153], v[90:93]
	v_mfma_f32_16x16x32_bf16 v[94:97], v[174:177], v[150:153], v[94:97]
	v_mfma_f32_16x16x32_bf16 v[78:81], v[174:177], v[146:149], v[78:81]
	v_mfma_f32_16x16x32_bf16 v[110:113], v[174:177], v[154:157], v[110:113]
	s_add_i32 m0, s60, s63
	v_mfma_f32_16x16x32_bf16 v[126:129], v[174:177], v[158:161], v[126:129]
	global_load_lds_dwordx4 v230, s[56:57]
	v_mfma_f32_16x16x32_bf16 v[122:125], v[170:173], v[158:161], v[122:125]
	v_mfma_f32_16x16x32_bf16 v[106:109], v[170:173], v[154:157], v[106:109]
	v_mfma_f32_16x16x32_bf16 v[102:105], v[166:169], v[154:157], v[102:105]
	v_mfma_f32_16x16x32_bf16 v[118:121], v[166:169], v[158:161], v[118:121]
	v_mfma_f32_16x16x32_bf16 v[114:117], v[162:165], v[158:161], v[114:117]
	global_load_lds_dwordx4 v231, s[56:57] offset:1024
	v_mfma_f32_16x16x32_bf16 v[98:101], v[162:165], v[154:157], v[98:101]
	s_setprio 0
	s_add_i32 s60, s60, 0x6000
	s_cmp_eq_u32 s60, 0x12000
	s_cselect_b32 s60, 0, s60
	s_add_u32 s54, s54, s72
	s_addc_u32 s55, s55, 0
	s_add_u32 s56, s56, s73
	s_addc_u32 s57, s57, 0
	s_add_i32 s61, s61, 0x6000
	s_cmp_eq_u32 s61, 0x12000
	s_cselect_b32 s61, 0, s61
	s_waitcnt lgkmcnt(0)
	v_add_u32_e32 v240, s61, v238
	v_add_u32_e32 v241, s61, v239
	s_setprio 1
	v_mfma_f32_16x16x32_bf16 v[2:5], v[210:213], v[178:181], v[2:5]
	v_mfma_f32_16x16x32_bf16 v[18:21], v[210:213], v[182:185], v[18:21]
	v_mfma_f32_16x16x32_bf16 v[22:25], v[214:217], v[182:185], v[22:25]
	v_mfma_f32_16x16x32_bf16 v[6:9], v[214:217], v[178:181], v[6:9]
	s_waitcnt vmcnt(6)
	s_barrier
	v_mfma_f32_16x16x32_bf16 v[10:13], v[218:221], v[178:181], v[10:13]
	v_mfma_f32_16x16x32_bf16 v[26:29], v[218:221], v[182:185], v[26:29]
	v_mfma_f32_16x16x32_bf16 v[30:33], v[222:225], v[182:185], v[30:33]
	v_mfma_f32_16x16x32_bf16 v[14:17], v[222:225], v[178:181], v[14:17]
	v_mfma_f32_16x16x32_bf16 v[46:49], v[222:225], v[186:189], v[46:49]
	ds_read_b128 v[162:165], v241 offset:0
	v_mfma_f32_16x16x32_bf16 v[62:65], v[222:225], v[190:193], v[62:65]
	ds_read_b128 v[166:169], v241 offset:256
	v_mfma_f32_16x16x32_bf16 v[58:61], v[218:221], v[190:193], v[58:61]
	ds_read_b128 v[170:173], v241 offset:2048
	v_mfma_f32_16x16x32_bf16 v[42:45], v[218:221], v[186:189], v[42:45]
	ds_read_b128 v[174:177], v241 offset:2304
	v_mfma_f32_16x16x32_bf16 v[38:41], v[214:217], v[186:189], v[38:41]
	ds_read_b128 v[130:133], v240 offset:0
	v_mfma_f32_16x16x32_bf16 v[54:57], v[214:217], v[190:193], v[54:57]
	ds_read_b128 v[134:137], v240 offset:1024
	v_mfma_f32_16x16x32_bf16 v[50:53], v[210:213], v[190:193], v[50:53]
	ds_read_b128 v[138:141], v240 offset:2048
	v_mfma_f32_16x16x32_bf16 v[34:37], v[210:213], v[186:189], v[34:37]
	ds_read_b128 v[142:145], v240 offset:3072
	v_mfma_f32_16x16x32_bf16 v[66:69], v[210:213], v[194:197], v[66:69]
	ds_read_b128 v[146:149], v240 offset:4096
	v_mfma_f32_16x16x32_bf16 v[82:85], v[210:213], v[198:201], v[82:85]
	ds_read_b128 v[150:153], v240 offset:5120
	v_mfma_f32_16x16x32_bf16 v[86:89], v[214:217], v[198:201], v[86:89]
	ds_read_b128 v[154:157], v240 offset:6144
	v_mfma_f32_16x16x32_bf16 v[70:73], v[214:217], v[194:197], v[70:73]
	ds_read_b128 v[158:161], v240 offset:7168
	v_mfma_f32_16x16x32_bf16 v[74:77], v[218:221], v[194:197], v[74:77]
	v_mfma_f32_16x16x32_bf16 v[90:93], v[218:221], v[198:201], v[90:93]
	v_mfma_f32_16x16x32_bf16 v[94:97], v[222:225], v[198:201], v[94:97]
	v_mfma_f32_16x16x32_bf16 v[78:81], v[222:225], v[194:197], v[78:81]
	v_mfma_f32_16x16x32_bf16 v[110:113], v[222:225], v[202:205], v[110:113]
	v_mfma_f32_16x16x32_bf16 v[126:129], v[222:225], v[206:209], v[126:129]
	v_mfma_f32_16x16x32_bf16 v[122:125], v[218:221], v[206:209], v[122:125]
	v_mfma_f32_16x16x32_bf16 v[106:109], v[218:221], v[202:205], v[106:109]
	v_mfma_f32_16x16x32_bf16 v[102:105], v[214:217], v[202:205], v[102:105]
	v_mfma_f32_16x16x32_bf16 v[118:121], v[214:217], v[206:209], v[118:121]
	v_mfma_f32_16x16x32_bf16 v[114:117], v[210:213], v[206:209], v[114:117]
	v_mfma_f32_16x16x32_bf16 v[98:101], v[210:213], v[202:205], v[98:101]
	s_setprio 0
	s_add_i32 s61, s61, 0x6000
	s_cmp_eq_u32 s61, 0x12000
	s_cselect_b32 s61, 0, s61
	s_waitcnt lgkmcnt(0)
	v_add_u32_e32 v240, s61, v238
	v_add_u32_e32 v241, s61, v239
	s_setprio 1
	v_mfma_f32_16x16x32_bf16 v[2:5], v[162:165], v[130:133], v[2:5]
	v_mfma_f32_16x16x32_bf16 v[18:21], v[162:165], v[134:137], v[18:21]
	v_mfma_f32_16x16x32_bf16 v[22:25], v[166:169], v[134:137], v[22:25]
	v_mfma_f32_16x16x32_bf16 v[6:9], v[166:169], v[130:133], v[6:9]
	s_waitcnt vmcnt(0)
	s_barrier
	v_mfma_f32_16x16x32_bf16 v[10:13], v[170:173], v[130:133], v[10:13]
	v_mfma_f32_16x16x32_bf16 v[26:29], v[170:173], v[134:137], v[26:29]
	v_mfma_f32_16x16x32_bf16 v[30:33], v[174:177], v[134:137], v[30:33]
	v_mfma_f32_16x16x32_bf16 v[14:17], v[174:177], v[130:133], v[14:17]
	v_mfma_f32_16x16x32_bf16 v[46:49], v[174:177], v[138:141], v[46:49]
	ds_read_b128 v[210:213], v241 offset:0
	v_mfma_f32_16x16x32_bf16 v[62:65], v[174:177], v[142:145], v[62:65]
	ds_read_b128 v[214:217], v241 offset:256
	v_mfma_f32_16x16x32_bf16 v[58:61], v[170:173], v[142:145], v[58:61]
	ds_read_b128 v[218:221], v241 offset:2048
	v_mfma_f32_16x16x32_bf16 v[42:45], v[170:173], v[138:141], v[42:45]
	ds_read_b128 v[222:225], v241 offset:2304
	v_mfma_f32_16x16x32_bf16 v[38:41], v[166:169], v[138:141], v[38:41]
	ds_read_b128 v[178:181], v240 offset:0
	v_mfma_f32_16x16x32_bf16 v[54:57], v[166:169], v[142:145], v[54:57]
	ds_read_b128 v[182:185], v240 offset:1024
	v_mfma_f32_16x16x32_bf16 v[50:53], v[162:165], v[142:145], v[50:53]
	ds_read_b128 v[186:189], v240 offset:2048
	v_mfma_f32_16x16x32_bf16 v[34:37], v[162:165], v[138:141], v[34:37]
	ds_read_b128 v[190:193], v240 offset:3072
	v_mfma_f32_16x16x32_bf16 v[66:69], v[162:165], v[146:149], v[66:69]
	ds_read_b128 v[194:197], v240 offset:4096
	v_mfma_f32_16x16x32_bf16 v[82:85], v[162:165], v[150:153], v[82:85]
	ds_read_b128 v[198:201], v240 offset:5120
	v_mfma_f32_16x16x32_bf16 v[86:89], v[166:169], v[150:153], v[86:89]
	ds_read_b128 v[202:205], v240 offset:6144
	v_mfma_f32_16x16x32_bf16 v[70:73], v[166:169], v[146:149], v[70:73]
	ds_read_b128 v[206:209], v240 offset:7168
	v_mfma_f32_16x16x32_bf16 v[74:77], v[170:173], v[146:149], v[74:77]
	v_mfma_f32_16x16x32_bf16 v[90:93], v[170:173], v[150:153], v[90:93]
	v_mfma_f32_16x16x32_bf16 v[94:97], v[174:177], v[150:153], v[94:97]
	v_mfma_f32_16x16x32_bf16 v[78:81], v[174:177], v[146:149], v[78:81]
	v_mfma_f32_16x16x32_bf16 v[110:113], v[174:177], v[154:157], v[110:113]
	v_mfma_f32_16x16x32_bf16 v[126:129], v[174:177], v[158:161], v[126:129]
	v_mfma_f32_16x16x32_bf16 v[122:125], v[170:173], v[158:161], v[122:125]
	v_mfma_f32_16x16x32_bf16 v[106:109], v[170:173], v[154:157], v[106:109]
	v_mfma_f32_16x16x32_bf16 v[102:105], v[166:169], v[154:157], v[102:105]
	v_mfma_f32_16x16x32_bf16 v[118:121], v[166:169], v[158:161], v[118:121]
	v_mfma_f32_16x16x32_bf16 v[114:117], v[162:165], v[158:161], v[114:117]
	v_mfma_f32_16x16x32_bf16 v[98:101], v[162:165], v[154:157], v[98:101]
	s_setprio 0
	s_add_i32 s61, s61, 0x6000
	s_cmp_eq_u32 s61, 0x12000
	s_cselect_b32 s61, 0, s61
	s_waitcnt lgkmcnt(0)
	s_setprio 1
	v_mfma_f32_16x16x32_bf16 v[2:5], v[210:213], v[178:181], v[2:5]
	v_mfma_f32_16x16x32_bf16 v[18:21], v[210:213], v[182:185], v[18:21]
	v_mfma_f32_16x16x32_bf16 v[22:25], v[214:217], v[182:185], v[22:25]
	v_mfma_f32_16x16x32_bf16 v[6:9], v[214:217], v[178:181], v[6:9]
	s_barrier
	v_mfma_f32_16x16x32_bf16 v[10:13], v[218:221], v[178:181], v[10:13]
	v_mfma_f32_16x16x32_bf16 v[26:29], v[218:221], v[182:185], v[26:29]
	v_mfma_f32_16x16x32_bf16 v[30:33], v[222:225], v[182:185], v[30:33]
	v_mfma_f32_16x16x32_bf16 v[14:17], v[222:225], v[178:181], v[14:17]
	v_mfma_f32_16x16x32_bf16 v[46:49], v[222:225], v[186:189], v[46:49]
	v_mfma_f32_16x16x32_bf16 v[62:65], v[222:225], v[190:193], v[62:65]
	v_mfma_f32_16x16x32_bf16 v[58:61], v[218:221], v[190:193], v[58:61]
	v_mfma_f32_16x16x32_bf16 v[42:45], v[218:221], v[186:189], v[42:45]
	v_mfma_f32_16x16x32_bf16 v[38:41], v[214:217], v[186:189], v[38:41]
	v_mfma_f32_16x16x32_bf16 v[54:57], v[214:217], v[190:193], v[54:57]
	v_mfma_f32_16x16x32_bf16 v[50:53], v[210:213], v[190:193], v[50:53]
	v_mfma_f32_16x16x32_bf16 v[34:37], v[210:213], v[186:189], v[34:37]
	v_mfma_f32_16x16x32_bf16 v[66:69], v[210:213], v[194:197], v[66:69]
	v_mfma_f32_16x16x32_bf16 v[82:85], v[210:213], v[198:201], v[82:85]
	v_mfma_f32_16x16x32_bf16 v[86:89], v[214:217], v[198:201], v[86:89]
	v_mfma_f32_16x16x32_bf16 v[70:73], v[214:217], v[194:197], v[70:73]
	v_mfma_f32_16x16x32_bf16 v[74:77], v[218:221], v[194:197], v[74:77]
	v_mfma_f32_16x16x32_bf16 v[90:93], v[218:221], v[198:201], v[90:93]
	v_mfma_f32_16x16x32_bf16 v[94:97], v[222:225], v[198:201], v[94:97]
	v_mfma_f32_16x16x32_bf16 v[78:81], v[222:225], v[194:197], v[78:81]
	v_mfma_f32_16x16x32_bf16 v[110:113], v[222:225], v[202:205], v[110:113]
	v_mfma_f32_16x16x32_bf16 v[126:129], v[222:225], v[206:209], v[126:129]
	v_mfma_f32_16x16x32_bf16 v[122:125], v[218:221], v[206:209], v[122:125]
	v_mfma_f32_16x16x32_bf16 v[106:109], v[218:221], v[202:205], v[106:109]
	v_mfma_f32_16x16x32_bf16 v[102:105], v[214:217], v[202:205], v[102:105]
	v_mfma_f32_16x16x32_bf16 v[118:121], v[214:217], v[206:209], v[118:121]
	v_mfma_f32_16x16x32_bf16 v[114:117], v[210:213], v[206:209], v[114:117]
	v_mfma_f32_16x16x32_bf16 v[98:101], v[210:213], v[202:205], v[98:101]
	s_setprio 0
